# GEMM inner loops (all 10): back-edge counter/exit-test SALU block hoisted above the loop-back s_barrier (section 7.11 loop-edge edit), on top of EpiDil/P0/P3 changes
# baseline (speedup 1.0000x reference)
; #define PG8_STAGE(bufoff, gbase, voff) do { _Pragma("unroll") for (int _i = 0; _i < 2; ++_i) \
;         __builtin_amdgcn_global_load_lds((const unsigned*)((const char*)(gbase) + (voff)[_i]), (LAS unsigned*)(lds + (bufoff) + ldsw + _i * 8192), 16, 0, 1); } while (0)
; #define PG8_LDA(dst, b, h) do { _Pragma("unroll") for (int m = 0; m < 4; ++m) _Pragma("unroll") for (int k = 0; k < 2; ++k) dst[m][k] = *(const LAS bf16x8*)(lds + PG8_SA(b, h) + aoff + m * 2048 + k * 1024); } while (0)
; #define PG8_LDB(dst, b, h) do { _Pragma("unroll") for (int n = 0; n < 2; ++n) _Pragma("unroll") for (int k = 0; k < 2; ++k) dst[n][k] = *(const LAS bf16x8*)(lds + PG8_SB(b, h) + boff + n * 2048 + k * 1024); } while (0)
; #define PG8_MMA(ai, bj, At, Bt) do { __builtin_amdgcn_s_setprio(1); _Pragma("unroll") for (int m = 0; m < 4; ++m) _Pragma("unroll") for (int n = 0; n < 2; ++n) _Pragma("unroll") for (int k = 0; k < 2; ++k) \
;         acc[ai][bj][m][n] = __builtin_amdgcn_mfma_f32_16x16x32_bf16(Bt[n][k], At[m][k], acc[ai][bj][m][n], 0, 0, 0); __builtin_amdgcn_s_setprio(0); } while (0)
; #define PG8_WAIT_V(n) asm volatile("s_waitcnt vmcnt(" #n ")" ::: "memory")
; #define PG8_WAIT_L(n) asm volatile("s_waitcnt lgkmcnt(" #n ")" ::: "memory")
; #define PG8_BAR __builtin_amdgcn_s_barrier()
; template <class Epi, class Sched, bool ALIGN_EPI = false, bool SP2 = false>
; __device__ __forceinline__ void gemm_phase(LAS unsigned char* lds, const Gemm g, const Sched& S, const Epi& E) {
;     ...
;             const bool last = (t == nt - 2);
;             const char* a1 = cA + (size_t)(t + 1) * kstep;
;             const char* a2 = last ? nA : cA + (size_t)(t + 2) * kstep; const char* b2 = last ? nB : cB + (size_t)(t + 2) * kstep;
;             const char* a3 = a2 + kstep; const char* b3 = b2 + kstep;
;             if (last && has_next) S.a_ready(nxt);
;             if constexpr (SP2) {
;             PG8_LDB(B0, 0, 0); PG8_LDB(B1, 0, 1); PG8_SCHED; PG8_LDA(At, 0, 0); PG8_STAGE(PG8_SA(1, 1), a1 + hstep, voffA);
;             PG8_WAIT_V(8); PG8_WAIT_L(0); PG8_BAR; PG8_MMA(0, 0, At, B0); PG8_MMA(0, 1, At, B1); PG8_BAR; PG8_SCHED;
;             PG8_LDA(At, 0, 1); PG8_STAGE(PG8_SB(0, 0), b2, voffB); PG8_STAGE(PG8_SB(0, 1), b2 + hstep, voffB); PG8_STAGE(PG8_SA(0, 0), a2, voffA);
;             PG8_WAIT_V(8); PG8_WAIT_L(0); PG8_BAR; PG8_MMA(1, 0, At, B0); PG8_MMA(1, 1, At, B1); PG8_BAR; PG8_SCHED;
.LBB0_103:
	ds_read_b128 v[164:167], v147
	ds_read_b128 v[168:171], v147 offset:1024
	ds_read_b128 v[172:175], v147 offset:2048
	ds_read_b128 v[176:179], v147 offset:3072
	ds_read_b128 v[180:183], v148
	ds_read_b128 v[184:187], v148 offset:1024
	ds_read_b128 v[188:191], v148 offset:2048
	ds_read_b128 v[192:195], v148 offset:3072
	s_add_u32 s38, s36, 0xfff80080
	s_addc_u32 s39, s37, -1
	s_cmp_eq_u32 s43, 28
	s_cselect_b32 s45, s23, s39
	s_cselect_b32 s44, s62, s38
	s_cselect_b32 s39, s21, s42
	s_cselect_b32 s38, s63, s64
	v_lshl_add_u64 v[150:151], s[36:37], 0, v[136:137]
	s_add_i32 m0, s29, 0xc000
	ds_read_b128 v[196:199], v149
	ds_read_b128 v[200:203], v149 offset:1024
	ds_read_b128 v[204:207], v149 offset:2048
	ds_read_b128 v[208:211], v149 offset:3072
	ds_read_b128 v[212:215], v149 offset:4096
	ds_read_b128 v[216:219], v149 offset:5120
	ds_read_b128 v[220:223], v149 offset:6144
	ds_read_b128 v[224:227], v149 offset:7168
	global_load_lds_dwordx4 v[150:151], off sc0
	v_lshl_add_u64 v[150:151], s[36:37], 0, v[138:139]
	s_add_i32 m0, s29, 0xe000
	s_nop 0
	global_load_lds_dwordx4 v[150:151], off sc0
	s_waitcnt vmcnt(8)
	s_waitcnt lgkmcnt(0)
	s_barrier
	s_setprio 1
	s_waitcnt lgkmcnt(0)
	v_mfma_f32_16x16x32_bf16 v[124:127], v[164:167], v[196:199], v[124:127]
	v_mfma_f32_16x16x32_bf16 v[116:119], v[172:175], v[196:199], v[116:119]
	v_mfma_f32_16x16x32_bf16 v[108:111], v[164:167], v[204:207], v[108:111]
	v_mfma_f32_16x16x32_bf16 v[100:103], v[172:175], v[204:207], v[100:103]
	v_mfma_f32_16x16x32_bf16 v[92:95], v[164:167], v[212:215], v[92:95]
	v_mfma_f32_16x16x32_bf16 v[84:87], v[172:175], v[212:215], v[84:87]
	v_mfma_f32_16x16x32_bf16 v[76:79], v[164:167], v[220:223], v[76:79]
	v_mfma_f32_16x16x32_bf16 v[68:71], v[172:175], v[220:223], v[68:71]
	v_mfma_f32_16x16x32_bf16 v[124:127], v[168:171], v[200:203], v[124:127]
	v_mfma_f32_16x16x32_bf16 v[116:119], v[176:179], v[200:203], v[116:119]
	v_mfma_f32_16x16x32_bf16 v[108:111], v[168:171], v[208:211], v[108:111]
	v_mfma_f32_16x16x32_bf16 v[100:103], v[176:179], v[208:211], v[100:103]
	v_mfma_f32_16x16x32_bf16 v[92:95], v[168:171], v[216:219], v[92:95]
	v_mfma_f32_16x16x32_bf16 v[84:87], v[176:179], v[216:219], v[84:87]
	v_mfma_f32_16x16x32_bf16 v[76:79], v[168:171], v[224:227], v[76:79]
	v_mfma_f32_16x16x32_bf16 v[68:71], v[176:179], v[224:227], v[68:71]
	s_setprio 0
	s_setprio 1
	v_mfma_f32_16x16x32_bf16 v[120:123], v[180:183], v[196:199], v[120:123]
	v_mfma_f32_16x16x32_bf16 v[112:115], v[188:191], v[196:199], v[112:115]
	v_mfma_f32_16x16x32_bf16 v[104:107], v[180:183], v[204:207], v[104:107]
	v_mfma_f32_16x16x32_bf16 v[96:99], v[188:191], v[204:207], v[96:99]
	v_mfma_f32_16x16x32_bf16 v[88:91], v[180:183], v[212:215], v[88:91]
	v_mfma_f32_16x16x32_bf16 v[80:83], v[188:191], v[212:215], v[80:83]
	v_mfma_f32_16x16x32_bf16 v[72:75], v[180:183], v[220:223], v[72:75]
	v_mfma_f32_16x16x32_bf16 v[64:67], v[188:191], v[220:223], v[64:67]
	v_mfma_f32_16x16x32_bf16 v[120:123], v[184:187], v[200:203], v[120:123]
	v_mfma_f32_16x16x32_bf16 v[112:115], v[192:195], v[200:203], v[112:115]
	v_mfma_f32_16x16x32_bf16 v[104:107], v[184:187], v[208:211], v[104:107]
	v_mfma_f32_16x16x32_bf16 v[96:99], v[192:195], v[208:211], v[96:99]
	v_mfma_f32_16x16x32_bf16 v[88:91], v[184:187], v[216:219], v[88:91]
	v_mfma_f32_16x16x32_bf16 v[80:83], v[192:195], v[216:219], v[80:83]
	v_mfma_f32_16x16x32_bf16 v[72:75], v[184:187], v[224:227], v[72:75]
	v_mfma_f32_16x16x32_bf16 v[64:67], v[192:195], v[224:227], v[64:67]
	s_setprio 0
	s_barrier
	s_add_i32 s65, s58, s48
	v_lshl_add_u64 v[150:151], s[38:39], 0, v[132:133]
	s_mov_b32 m0, s65
	ds_read_b128 v[196:199], v149 offset:16384
	ds_read_b128 v[200:203], v149 offset:17408
	ds_read_b128 v[204:207], v149 offset:18432
	ds_read_b128 v[208:211], v149 offset:19456
	ds_read_b128 v[212:215], v149 offset:20480
	ds_read_b128 v[216:219], v149 offset:21504
	ds_read_b128 v[220:223], v149 offset:22528
	ds_read_b128 v[224:227], v149 offset:23552
	global_load_lds_dwordx4 v[150:151], off sc0
	s_add_i32 m0, s65, 0x2000
	s_add_u32 s66, s38, 0x80000
	v_lshl_add_u64 v[228:229], s[38:39], 0, v[128:129]
	s_addc_u32 s67, s39, 0
	s_add_i32 s65, s59, s48
	global_load_lds_dwordx4 v[228:229], off sc0
	v_lshl_add_u64 v[230:231], s[66:67], 0, v[132:133]
	s_mov_b32 m0, s65
	v_lshl_add_u64 v[232:233], s[44:45], 0, v[130:131]
	global_load_lds_dwordx4 v[230:231], off sc0
	v_lshl_add_u64 v[230:231], s[66:67], 0, v[128:129]
	s_add_i32 m0, s65, 0x2000
	s_nop 0
	global_load_lds_dwordx4 v[230:231], off sc0
	v_lshl_add_u64 v[230:231], s[44:45], 0, v[134:135]
	s_mov_b32 m0, s29
	s_nop 0
	global_load_lds_dwordx4 v[230:231], off sc0
	s_mov_b32 m0, s51
	s_nop 0
	global_load_lds_dwordx4 v[232:233], off sc0
	s_waitcnt vmcnt(8)
	s_waitcnt lgkmcnt(0)
	s_barrier
; #define PG8_STAGE(bufoff, gbase, voff) do { _Pragma("unroll") for (int _i = 0; _i < 2; ++_i) \
;         __builtin_amdgcn_global_load_lds((const unsigned*)((const char*)(gbase) + (voff)[_i]), (LAS unsigned*)(lds + (bufoff) + ldsw + _i * 8192), 16, 0, 1); } while (0)
; #define PG8_LDA(dst, b, h) do { _Pragma("unroll") for (int m = 0; m < 4; ++m) _Pragma("unroll") for (int k = 0; k < 2; ++k) dst[m][k] = *(const LAS bf16x8*)(lds + PG8_SA(b, h) + aoff + m * 2048 + k * 1024); } while (0)
; #define PG8_LDB(dst, b, h) do { _Pragma("unroll") for (int n = 0; n < 2; ++n) _Pragma("unroll") for (int k = 0; k < 2; ++k) dst[n][k] = *(const LAS bf16x8*)(lds + PG8_SB(b, h) + boff + n * 2048 + k * 1024); } while (0)
; #define PG8_MMA(ai, bj, At, Bt) do { __builtin_amdgcn_s_setprio(1); _Pragma("unroll") for (int m = 0; m < 4; ++m) _Pragma("unroll") for (int n = 0; n < 2; ++n) _Pragma("unroll") for (int k = 0; k < 2; ++k) \
;         acc[ai][bj][m][n] = __builtin_amdgcn_mfma_f32_16x16x32_bf16(Bt[n][k], At[m][k], acc[ai][bj][m][n], 0, 0, 0); __builtin_amdgcn_s_setprio(0); } while (0)
; #define PG8_WAIT_V(n) asm volatile("s_waitcnt vmcnt(" #n ")" ::: "memory")
; #define PG8_WAIT_L(n) asm volatile("s_waitcnt lgkmcnt(" #n ")" ::: "memory")
; #define PG8_BAR __builtin_amdgcn_s_barrier()
; #define PG8_SCHED __builtin_amdgcn_sched_barrier(0)
; template <class Epi, class Sched, bool ALIGN_EPI = false, bool SP2 = false>
; __device__ __forceinline__ void gemm_phase(LAS unsigned char* lds, const Gemm g, const Sched& S, const Epi& E) {
;     ...
;             PG8_WAIT_V(8); PG8_WAIT_L(0); PG8_BAR; PG8_MMA(1, 0, At, B0); PG8_MMA(1, 1, At, B1); PG8_BAR; PG8_SCHED;
;             PG8_LDB(B0, 1, 0); PG8_LDB(B1, 1, 1); PG8_SCHED; PG8_LDA(At, 1, 0); PG8_STAGE(PG8_SA(0, 1), a2 + hstep, voffA);
;             PG8_WAIT_V(8); PG8_WAIT_L(0); PG8_BAR; PG8_MMA(0, 0, At, B0); PG8_MMA(0, 1, At, B1); PG8_BAR; PG8_SCHED;
	s_setprio 1
	s_waitcnt lgkmcnt(0)
	v_mfma_f32_16x16x32_bf16 v[60:63], v[164:167], v[196:199], v[60:63]
	v_mfma_f32_16x16x32_bf16 v[52:55], v[172:175], v[196:199], v[52:55]
	v_mfma_f32_16x16x32_bf16 v[44:47], v[164:167], v[204:207], v[44:47]
	v_mfma_f32_16x16x32_bf16 v[36:39], v[172:175], v[204:207], v[36:39]
	v_mfma_f32_16x16x32_bf16 v[28:31], v[164:167], v[212:215], v[28:31]
	v_mfma_f32_16x16x32_bf16 v[20:23], v[172:175], v[212:215], v[20:23]
	v_mfma_f32_16x16x32_bf16 v[12:15], v[164:167], v[220:223], v[12:15]
	v_mfma_f32_16x16x32_bf16 v[4:7], v[172:175], v[220:223], v[4:7]
	v_mfma_f32_16x16x32_bf16 v[60:63], v[168:171], v[200:203], v[60:63]
	v_mfma_f32_16x16x32_bf16 v[52:55], v[176:179], v[200:203], v[52:55]
	v_mfma_f32_16x16x32_bf16 v[44:47], v[168:171], v[208:211], v[44:47]
	v_mfma_f32_16x16x32_bf16 v[36:39], v[176:179], v[208:211], v[36:39]
	v_mfma_f32_16x16x32_bf16 v[28:31], v[168:171], v[216:219], v[28:31]
	v_mfma_f32_16x16x32_bf16 v[20:23], v[176:179], v[216:219], v[20:23]
	v_mfma_f32_16x16x32_bf16 v[12:15], v[168:171], v[224:227], v[12:15]
	v_mfma_f32_16x16x32_bf16 v[4:7], v[176:179], v[224:227], v[4:7]
	s_setprio 0
	s_setprio 1
	v_mfma_f32_16x16x32_bf16 v[56:59], v[180:183], v[196:199], v[56:59]
	v_mfma_f32_16x16x32_bf16 v[48:51], v[188:191], v[196:199], v[48:51]
	v_mfma_f32_16x16x32_bf16 v[40:43], v[180:183], v[204:207], v[40:43]
	v_mfma_f32_16x16x32_bf16 v[32:35], v[188:191], v[204:207], v[32:35]
	v_mfma_f32_16x16x32_bf16 v[24:27], v[180:183], v[212:215], v[24:27]
	v_mfma_f32_16x16x32_bf16 v[16:19], v[188:191], v[212:215], v[16:19]
	v_mfma_f32_16x16x32_bf16 v[8:11], v[180:183], v[220:223], v[8:11]
	v_mfma_f32_16x16x32_bf16 v[0:3], v[188:191], v[220:223], v[0:3]
	v_mfma_f32_16x16x32_bf16 v[56:59], v[184:187], v[200:203], v[56:59]
	v_mfma_f32_16x16x32_bf16 v[48:51], v[192:195], v[200:203], v[48:51]
	v_mfma_f32_16x16x32_bf16 v[40:43], v[184:187], v[208:211], v[40:43]
	v_mfma_f32_16x16x32_bf16 v[32:35], v[192:195], v[208:211], v[32:35]
	v_mfma_f32_16x16x32_bf16 v[24:27], v[184:187], v[216:219], v[24:27]
	v_mfma_f32_16x16x32_bf16 v[16:19], v[192:195], v[216:219], v[16:19]
	v_mfma_f32_16x16x32_bf16 v[8:11], v[184:187], v[224:227], v[8:11]
	v_mfma_f32_16x16x32_bf16 v[0:3], v[192:195], v[224:227], v[0:3]
	s_setprio 0
	s_barrier
	s_add_i32 s65, 0, 0x18000
	v_add_u32_e32 v153, s65, v145
	s_add_i32 s66, 0, 0x1c000
	ds_read_b128 v[164:167], v153
	ds_read_b128 v[168:171], v153 offset:1024
	ds_read_b128 v[172:175], v153 offset:2048
	ds_read_b128 v[176:179], v153 offset:3072
	v_add_u32_e32 v153, s66, v145
	ds_read_b128 v[180:183], v153
	ds_read_b128 v[184:187], v153 offset:1024
	ds_read_b128 v[188:191], v153 offset:2048
	ds_read_b128 v[192:195], v153 offset:3072
	s_add_u32 s44, s44, 0x80000
	s_addc_u32 s45, s45, 0
	s_mov_b32 m0, s52
	v_lshl_add_u64 v[234:235], s[44:45], 0, v[134:135]
	ds_read_b128 v[196:199], v149 offset:32768
	ds_read_b128 v[200:203], v149 offset:33792
	ds_read_b128 v[204:207], v149 offset:34816
	ds_read_b128 v[208:211], v149 offset:35840
	ds_read_b128 v[212:215], v149 offset:36864
	ds_read_b128 v[216:219], v149 offset:37888
	ds_read_b128 v[220:223], v149 offset:38912
	ds_read_b128 v[224:227], v149 offset:39936
	global_load_lds_dwordx4 v[234:235], off sc0
	v_lshl_add_u64 v[234:235], s[44:45], 0, v[130:131]
	s_mov_b32 m0, s53
	s_nop 0
	global_load_lds_dwordx4 v[234:235], off sc0
	s_waitcnt vmcnt(8)
	s_waitcnt lgkmcnt(0)
	s_barrier
	s_setprio 1
	s_waitcnt lgkmcnt(0)
	v_mfma_f32_16x16x32_bf16 v[124:127], v[164:167], v[196:199], v[124:127]
	v_mfma_f32_16x16x32_bf16 v[116:119], v[172:175], v[196:199], v[116:119]
	v_mfma_f32_16x16x32_bf16 v[108:111], v[164:167], v[204:207], v[108:111]
	v_mfma_f32_16x16x32_bf16 v[100:103], v[172:175], v[204:207], v[100:103]
	v_mfma_f32_16x16x32_bf16 v[92:95], v[164:167], v[212:215], v[92:95]
	v_mfma_f32_16x16x32_bf16 v[84:87], v[172:175], v[212:215], v[84:87]
	v_mfma_f32_16x16x32_bf16 v[76:79], v[164:167], v[220:223], v[76:79]
	v_mfma_f32_16x16x32_bf16 v[68:71], v[172:175], v[220:223], v[68:71]
	v_mfma_f32_16x16x32_bf16 v[124:127], v[168:171], v[200:203], v[124:127]
	v_mfma_f32_16x16x32_bf16 v[116:119], v[176:179], v[200:203], v[116:119]
	v_mfma_f32_16x16x32_bf16 v[108:111], v[168:171], v[208:211], v[108:111]
	v_mfma_f32_16x16x32_bf16 v[100:103], v[176:179], v[208:211], v[100:103]
	v_mfma_f32_16x16x32_bf16 v[92:95], v[168:171], v[216:219], v[92:95]
	v_mfma_f32_16x16x32_bf16 v[84:87], v[176:179], v[216:219], v[84:87]
	v_mfma_f32_16x16x32_bf16 v[76:79], v[168:171], v[224:227], v[76:79]
	v_mfma_f32_16x16x32_bf16 v[68:71], v[176:179], v[224:227], v[68:71]
	s_setprio 0
	s_setprio 1
	v_mfma_f32_16x16x32_bf16 v[120:123], v[180:183], v[196:199], v[120:123]
	v_mfma_f32_16x16x32_bf16 v[112:115], v[188:191], v[196:199], v[112:115]
	v_mfma_f32_16x16x32_bf16 v[104:107], v[180:183], v[204:207], v[104:107]
	v_mfma_f32_16x16x32_bf16 v[96:99], v[188:191], v[204:207], v[96:99]
	v_mfma_f32_16x16x32_bf16 v[88:91], v[180:183], v[212:215], v[88:91]
	v_mfma_f32_16x16x32_bf16 v[80:83], v[188:191], v[212:215], v[80:83]
	v_mfma_f32_16x16x32_bf16 v[72:75], v[180:183], v[220:223], v[72:75]
	v_mfma_f32_16x16x32_bf16 v[64:67], v[188:191], v[220:223], v[64:67]
	v_mfma_f32_16x16x32_bf16 v[120:123], v[184:187], v[200:203], v[120:123]
	v_mfma_f32_16x16x32_bf16 v[112:115], v[192:195], v[200:203], v[112:115]
	v_mfma_f32_16x16x32_bf16 v[104:107], v[184:187], v[208:211], v[104:107]
	v_mfma_f32_16x16x32_bf16 v[96:99], v[192:195], v[208:211], v[96:99]
	v_mfma_f32_16x16x32_bf16 v[88:91], v[184:187], v[216:219], v[88:91]
	v_mfma_f32_16x16x32_bf16 v[80:83], v[192:195], v[216:219], v[80:83]
	v_mfma_f32_16x16x32_bf16 v[72:75], v[184:187], v[224:227], v[72:75]
	v_mfma_f32_16x16x32_bf16 v[64:67], v[192:195], v[224:227], v[64:67]
	s_setprio 0
	s_barrier
; #define PG8_STAGE(bufoff, gbase, voff) do { _Pragma("unroll") for (int _i = 0; _i < 2; ++_i) \
;         __builtin_amdgcn_global_load_lds((const unsigned*)((const char*)(gbase) + (voff)[_i]), (LAS unsigned*)(lds + (bufoff) + ldsw + _i * 8192), 16, 0, 1); } while (0)
; #define PG8_LDA(dst, b, h) do { _Pragma("unroll") for (int m = 0; m < 4; ++m) _Pragma("unroll") for (int k = 0; k < 2; ++k) dst[m][k] = *(const LAS bf16x8*)(lds + PG8_SA(b, h) + aoff + m * 2048 + k * 1024); } while (0)
; #define PG8_MMA(ai, bj, At, Bt) do { __builtin_amdgcn_s_setprio(1); _Pragma("unroll") for (int m = 0; m < 4; ++m) _Pragma("unroll") for (int n = 0; n < 2; ++n) _Pragma("unroll") for (int k = 0; k < 2; ++k) \
;         acc[ai][bj][m][n] = __builtin_amdgcn_mfma_f32_16x16x32_bf16(Bt[n][k], At[m][k], acc[ai][bj][m][n], 0, 0, 0); __builtin_amdgcn_s_setprio(0); } while (0)
; #define PG8_WAIT_V(n) asm volatile("s_waitcnt vmcnt(" #n ")" ::: "memory")
; #define PG8_WAIT_L(n) asm volatile("s_waitcnt lgkmcnt(" #n ")" ::: "memory")
; #define PG8_BAR __builtin_amdgcn_s_barrier()
; #define PG8_SCHED __builtin_amdgcn_sched_barrier(0)
; template <class Epi, class Sched, bool ALIGN_EPI = false, bool SP2 = false>
; __device__ __forceinline__ void gemm_phase(LAS unsigned char* lds, const Gemm g, const Sched& S, const Epi& E) {
;     ...
;         for (int t = 0; t < nt; t += 2) {
;             const bool last = (t == nt - 2);
;             const char* a1 = cA + (size_t)(t + 1) * kstep;
;             const char* a2 = last ? nA : cA + (size_t)(t + 2) * kstep; const char* b2 = last ? nB : cB + (size_t)(t + 2) * kstep;
;     ...
;             PG8_LDA(At, 1, 1); PG8_STAGE(PG8_SB(1, 0), b3, voffB); PG8_STAGE(PG8_SB(1, 1), b3 + hstep, voffB); PG8_STAGE(PG8_SA(1, 0), a3, voffA);
;             PG8_WAIT_V(8); PG8_WAIT_L(0); PG8_BAR; PG8_MMA(1, 0, At, B0); PG8_MMA(1, 1, At, B1); PG8_BAR; PG8_SCHED;
	s_add_i32 s44, s65, s48
	v_lshl_add_u64 v[150:151], v[150:151], 0, s[14:15]
	s_mov_b32 m0, s44
	ds_read_b128 v[196:199], v149 offset:49152
	ds_read_b128 v[200:203], v149 offset:50176
	ds_read_b128 v[204:207], v149 offset:51200
	ds_read_b128 v[208:211], v149 offset:52224
	ds_read_b128 v[212:215], v149 offset:53248
	ds_read_b128 v[216:219], v149 offset:54272
	ds_read_b128 v[220:223], v149 offset:55296
	ds_read_b128 v[224:227], v149 offset:56320
	global_load_lds_dwordx4 v[150:151], off sc0
	s_add_i32 m0, s44, 0x2000
	s_add_u32 s38, s38, 0x80080
	v_lshl_add_u64 v[150:151], v[228:229], 0, s[14:15]
	s_addc_u32 s39, s39, 0
	s_add_i32 s44, s66, s48
	global_load_lds_dwordx4 v[150:151], off sc0
	v_lshl_add_u64 v[150:151], s[38:39], 0, v[132:133]
	s_mov_b32 m0, s44
	s_nop 0
	global_load_lds_dwordx4 v[150:151], off sc0
	v_lshl_add_u64 v[150:151], s[38:39], 0, v[128:129]
	s_add_i32 m0, s44, 0x2000
	s_nop 0
	global_load_lds_dwordx4 v[150:151], off sc0
	v_lshl_add_u64 v[150:151], v[230:231], 0, s[14:15]
	s_mov_b32 m0, s55
	s_nop 0
	global_load_lds_dwordx4 v[150:151], off sc0
	v_lshl_add_u64 v[150:151], v[232:233], 0, s[14:15]
	s_mov_b32 m0, s56
	s_nop 0
	global_load_lds_dwordx4 v[150:151], off sc0
	s_waitcnt vmcnt(8)
	s_waitcnt lgkmcnt(0)
	s_barrier
	s_setprio 1
	s_waitcnt lgkmcnt(0)
	v_mfma_f32_16x16x32_bf16 v[60:63], v[164:167], v[196:199], v[60:63]
	v_mfma_f32_16x16x32_bf16 v[52:55], v[172:175], v[196:199], v[52:55]
	v_mfma_f32_16x16x32_bf16 v[44:47], v[164:167], v[204:207], v[44:47]
	v_mfma_f32_16x16x32_bf16 v[36:39], v[172:175], v[204:207], v[36:39]
	v_mfma_f32_16x16x32_bf16 v[28:31], v[164:167], v[212:215], v[28:31]
	v_mfma_f32_16x16x32_bf16 v[20:23], v[172:175], v[212:215], v[20:23]
	v_mfma_f32_16x16x32_bf16 v[12:15], v[164:167], v[220:223], v[12:15]
	v_mfma_f32_16x16x32_bf16 v[4:7], v[172:175], v[220:223], v[4:7]
	v_mfma_f32_16x16x32_bf16 v[60:63], v[168:171], v[200:203], v[60:63]
	v_mfma_f32_16x16x32_bf16 v[52:55], v[176:179], v[200:203], v[52:55]
	v_mfma_f32_16x16x32_bf16 v[44:47], v[168:171], v[208:211], v[44:47]
	v_mfma_f32_16x16x32_bf16 v[36:39], v[176:179], v[208:211], v[36:39]
	v_mfma_f32_16x16x32_bf16 v[28:31], v[168:171], v[216:219], v[28:31]
	v_mfma_f32_16x16x32_bf16 v[20:23], v[176:179], v[216:219], v[20:23]
	v_mfma_f32_16x16x32_bf16 v[12:15], v[168:171], v[224:227], v[12:15]
	v_mfma_f32_16x16x32_bf16 v[4:7], v[176:179], v[224:227], v[4:7]
	s_setprio 0
	s_setprio 1
	v_mfma_f32_16x16x32_bf16 v[56:59], v[180:183], v[196:199], v[56:59]
	v_mfma_f32_16x16x32_bf16 v[48:51], v[188:191], v[196:199], v[48:51]
	v_mfma_f32_16x16x32_bf16 v[40:43], v[180:183], v[204:207], v[40:43]
	v_mfma_f32_16x16x32_bf16 v[32:35], v[188:191], v[204:207], v[32:35]
	v_mfma_f32_16x16x32_bf16 v[24:27], v[180:183], v[212:215], v[24:27]
	v_mfma_f32_16x16x32_bf16 v[16:19], v[188:191], v[212:215], v[16:19]
	v_mfma_f32_16x16x32_bf16 v[8:11], v[180:183], v[220:223], v[8:11]
	v_mfma_f32_16x16x32_bf16 v[0:3], v[188:191], v[220:223], v[0:3]
	v_mfma_f32_16x16x32_bf16 v[56:59], v[184:187], v[200:203], v[56:59]
	v_mfma_f32_16x16x32_bf16 v[48:51], v[192:195], v[200:203], v[48:51]
	v_mfma_f32_16x16x32_bf16 v[40:43], v[184:187], v[208:211], v[40:43]
	v_mfma_f32_16x16x32_bf16 v[32:35], v[192:195], v[208:211], v[32:35]
	v_mfma_f32_16x16x32_bf16 v[24:27], v[184:187], v[216:219], v[24:27]
	v_mfma_f32_16x16x32_bf16 v[16:19], v[192:195], v[216:219], v[16:19]
	v_mfma_f32_16x16x32_bf16 v[8:11], v[184:187], v[224:227], v[8:11]
	v_mfma_f32_16x16x32_bf16 v[0:3], v[192:195], v[224:227], v[0:3]
	s_setprio 0
	s_add_i32 s43, s43, 2
	s_add_u32 s36, s36, 0x100
	s_addc_u32 s37, s37, 0
	s_add_u32 s64, s64, 0x100
	s_addc_u32 s42, s42, 0
	s_cmp_gt_u32 s43, 29
	s_barrier
	s_cbranch_scc0 .LBB0_103
	s_and_b64 vcc, exec, s[18:19]
	s_cbranch_vccz .LBB0_106
	s_barrier

; #define PG8_STAGE(bufoff, gbase, voff) do { _Pragma("unroll") for (int _i = 0; _i < 2; ++_i) \
;         __builtin_amdgcn_global_load_lds((const unsigned*)((const char*)(gbase) + (voff)[_i]), (LAS unsigned*)(lds + (bufoff) + ldsw + _i * 8192), 16, 0, 1); } while (0)
; #define PG8_LDA(dst, b, h) do { _Pragma("unroll") for (int m = 0; m < 4; ++m) _Pragma("unroll") for (int k = 0; k < 2; ++k) dst[m][k] = *(const LAS bf16x8*)(lds + PG8_SA(b, h) + aoff + m * 2048 + k * 1024); } while (0)
; #define PG8_LDB(dst, b, h) do { _Pragma("unroll") for (int n = 0; n < 2; ++n) _Pragma("unroll") for (int k = 0; k < 2; ++k) dst[n][k] = *(const LAS bf16x8*)(lds + PG8_SB(b, h) + boff + n * 2048 + k * 1024); } while (0)
; #define PG8_MMA(ai, bj, At, Bt) do { __builtin_amdgcn_s_setprio(1); _Pragma("unroll") for (int m = 0; m < 4; ++m) _Pragma("unroll") for (int n = 0; n < 2; ++n) _Pragma("unroll") for (int k = 0; k < 2; ++k) \
;         acc[ai][bj][m][n] = __builtin_amdgcn_mfma_f32_16x16x32_bf16(Bt[n][k], At[m][k], acc[ai][bj][m][n], 0, 0, 0); __builtin_amdgcn_s_setprio(0); } while (0)
; #define PG8_WAIT_V(n) asm volatile("s_waitcnt vmcnt(" #n ")" ::: "memory")
; #define PG8_WAIT_L(n) asm volatile("s_waitcnt lgkmcnt(" #n ")" ::: "memory")
; #define PG8_BAR __builtin_amdgcn_s_barrier()
; template <class Epi, class Sched, bool ALIGN_EPI = false, bool SP2 = false>
; __device__ __forceinline__ void gemm_phase(LAS unsigned char* lds, const Gemm g, const Sched& S, const Epi& E) {
;     ...
;             const bool last = (t == nt - 2);
;             const char* a1 = cA + (size_t)(t + 1) * kstep;
;             const char* a2 = last ? nA : cA + (size_t)(t + 2) * kstep; const char* b2 = last ? nB : cB + (size_t)(t + 2) * kstep;
;             const char* a3 = a2 + kstep; const char* b3 = b2 + kstep;
;             if (last && has_next) S.a_ready(nxt);
;             if constexpr (SP2) {
;             PG8_LDB(B0, 0, 0); PG8_LDB(B1, 0, 1); PG8_SCHED; PG8_LDA(At, 0, 0); PG8_STAGE(PG8_SA(1, 1), a1 + hstep, voffA);
;             PG8_WAIT_V(8); PG8_WAIT_L(0); PG8_BAR; PG8_MMA(0, 0, At, B0); PG8_MMA(0, 1, At, B1); PG8_BAR; PG8_SCHED;
;             PG8_LDA(At, 0, 1); PG8_STAGE(PG8_SB(0, 0), b2, voffB); PG8_STAGE(PG8_SB(0, 1), b2 + hstep, voffB); PG8_STAGE(PG8_SA(0, 0), a2, voffA);
;             PG8_WAIT_V(8); PG8_WAIT_L(0); PG8_BAR; PG8_MMA(1, 0, At, B0); PG8_MMA(1, 1, At, B1); PG8_BAR; PG8_SCHED;
.LBB0_154:
	ds_read_b128 v[140:143], v151
	ds_read_b128 v[144:147], v151 offset:1024
	ds_read_b128 v[164:167], v151 offset:2048
	ds_read_b128 v[168:171], v151 offset:3072
	ds_read_b128 v[172:175], v153
	ds_read_b128 v[176:179], v153 offset:1024
	ds_read_b128 v[180:183], v153 offset:2048
	ds_read_b128 v[184:187], v153 offset:3072
	s_add_u32 s50, s48, 0x100
	s_addc_u32 s51, s49, 0
	s_cmpk_eq_i32 s75, 0x54
	s_cselect_b32 s55, s11, s51
	s_cselect_b32 s54, s10, s50
	s_cselect_b32 s53, s47, s43
	s_cselect_b32 s52, s46, s42
	v_lshl_add_u64 v[220:221], s[48:49], 0, v[132:133]
	s_add_i32 m0, s59, 0xc000
	ds_read_b128 v[188:191], v155
	ds_read_b128 v[192:195], v155 offset:1024
	ds_read_b128 v[196:199], v155 offset:2048
	ds_read_b128 v[200:203], v155 offset:3072
	ds_read_b128 v[204:207], v155 offset:4096
	ds_read_b128 v[208:211], v155 offset:5120
	ds_read_b128 v[212:215], v155 offset:6144
	ds_read_b128 v[216:219], v155 offset:7168
	global_load_lds_dwordx4 v[220:221], off sc0
	v_lshl_add_u64 v[220:221], s[48:49], 0, v[134:135]
	s_add_i32 m0, s59, 0xe000
	s_nop 0
	global_load_lds_dwordx4 v[220:221], off sc0
	s_waitcnt vmcnt(8)
	s_waitcnt lgkmcnt(0)
	s_barrier
	s_setprio 1
	s_waitcnt lgkmcnt(0)
	v_mfma_f32_16x16x32_bf16 v[124:127], v[140:143], v[188:191], v[124:127]
	v_mfma_f32_16x16x32_bf16 v[120:123], v[164:167], v[188:191], v[120:123]
	v_mfma_f32_16x16x32_bf16 v[112:115], v[140:143], v[196:199], v[112:115]
	v_mfma_f32_16x16x32_bf16 v[104:107], v[164:167], v[196:199], v[104:107]
	v_mfma_f32_16x16x32_bf16 v[96:99], v[140:143], v[204:207], v[96:99]
	v_mfma_f32_16x16x32_bf16 v[88:91], v[164:167], v[204:207], v[88:91]
	v_mfma_f32_16x16x32_bf16 v[80:83], v[140:143], v[212:215], v[80:83]
	v_mfma_f32_16x16x32_bf16 v[72:75], v[164:167], v[212:215], v[72:75]
	v_mfma_f32_16x16x32_bf16 v[124:127], v[144:147], v[192:195], v[124:127]
	v_mfma_f32_16x16x32_bf16 v[120:123], v[168:171], v[192:195], v[120:123]
	v_mfma_f32_16x16x32_bf16 v[112:115], v[144:147], v[200:203], v[112:115]
	v_mfma_f32_16x16x32_bf16 v[104:107], v[168:171], v[200:203], v[104:107]
	v_mfma_f32_16x16x32_bf16 v[96:99], v[144:147], v[208:211], v[96:99]
	v_mfma_f32_16x16x32_bf16 v[88:91], v[168:171], v[208:211], v[88:91]
	v_mfma_f32_16x16x32_bf16 v[80:83], v[144:147], v[216:219], v[80:83]
	v_mfma_f32_16x16x32_bf16 v[72:75], v[168:171], v[216:219], v[72:75]
	s_setprio 0
	s_setprio 1
	v_mfma_f32_16x16x32_bf16 v[116:119], v[172:175], v[188:191], v[116:119]
	v_mfma_f32_16x16x32_bf16 v[108:111], v[180:183], v[188:191], v[108:111]
	v_mfma_f32_16x16x32_bf16 v[100:103], v[172:175], v[196:199], v[100:103]
	v_mfma_f32_16x16x32_bf16 v[92:95], v[180:183], v[196:199], v[92:95]
	v_mfma_f32_16x16x32_bf16 v[84:87], v[172:175], v[204:207], v[84:87]
	v_mfma_f32_16x16x32_bf16 v[76:79], v[180:183], v[204:207], v[76:79]
	v_mfma_f32_16x16x32_bf16 v[68:71], v[172:175], v[212:215], v[68:71]
	v_mfma_f32_16x16x32_bf16 v[64:67], v[180:183], v[212:215], v[64:67]
	v_mfma_f32_16x16x32_bf16 v[116:119], v[176:179], v[192:195], v[116:119]
	v_mfma_f32_16x16x32_bf16 v[108:111], v[184:187], v[192:195], v[108:111]
	v_mfma_f32_16x16x32_bf16 v[100:103], v[176:179], v[200:203], v[100:103]
	v_mfma_f32_16x16x32_bf16 v[92:95], v[184:187], v[200:203], v[92:95]
	v_mfma_f32_16x16x32_bf16 v[84:87], v[176:179], v[208:211], v[84:87]
	v_mfma_f32_16x16x32_bf16 v[76:79], v[184:187], v[208:211], v[76:79]
	v_mfma_f32_16x16x32_bf16 v[68:71], v[176:179], v[216:219], v[68:71]
	v_mfma_f32_16x16x32_bf16 v[64:67], v[184:187], v[216:219], v[64:67]
	s_setprio 0
	s_barrier
	s_add_i32 s48, s69, s58
	v_lshl_add_u64 v[220:221], s[52:53], 0, v[128:129]
	s_mov_b32 m0, s48
	ds_read_b128 v[188:191], v155 offset:16384
	ds_read_b128 v[192:195], v155 offset:17408
	ds_read_b128 v[196:199], v155 offset:18432
	ds_read_b128 v[200:203], v155 offset:19456
	ds_read_b128 v[204:207], v155 offset:20480
	ds_read_b128 v[208:211], v155 offset:21504
	ds_read_b128 v[212:215], v155 offset:22528
	ds_read_b128 v[216:219], v155 offset:23552
	global_load_lds_dwordx4 v[220:221], off sc0
	s_add_i32 m0, s48, 0x2000
	s_add_u32 s48, s52, 0x160000
	v_lshl_add_u64 v[222:223], s[52:53], 0, v[130:131]
	s_addc_u32 s49, s53, 0
	s_add_i32 s76, s70, s58
	global_load_lds_dwordx4 v[222:223], off sc0
	v_lshl_add_u64 v[224:225], s[48:49], 0, v[128:129]
	s_mov_b32 m0, s76
	v_lshl_add_u64 v[226:227], s[54:55], 0, v[130:131]
	global_load_lds_dwordx4 v[224:225], off sc0
	v_lshl_add_u64 v[224:225], s[48:49], 0, v[130:131]
	s_add_i32 m0, s76, 0x2000
	s_nop 0
	global_load_lds_dwordx4 v[224:225], off sc0
	v_lshl_add_u64 v[224:225], s[54:55], 0, v[128:129]
	s_mov_b32 m0, s59
	s_nop 0
	global_load_lds_dwordx4 v[224:225], off sc0
	s_mov_b32 m0, s60
	s_nop 0
	global_load_lds_dwordx4 v[226:227], off sc0
	s_waitcnt vmcnt(8)
	s_waitcnt lgkmcnt(0)
	s_barrier
; #define PG8_STAGE(bufoff, gbase, voff) do { _Pragma("unroll") for (int _i = 0; _i < 2; ++_i) \
;         __builtin_amdgcn_global_load_lds((const unsigned*)((const char*)(gbase) + (voff)[_i]), (LAS unsigned*)(lds + (bufoff) + ldsw + _i * 8192), 16, 0, 1); } while (0)
; #define PG8_LDA(dst, b, h) do { _Pragma("unroll") for (int m = 0; m < 4; ++m) _Pragma("unroll") for (int k = 0; k < 2; ++k) dst[m][k] = *(const LAS bf16x8*)(lds + PG8_SA(b, h) + aoff + m * 2048 + k * 1024); } while (0)
; #define PG8_LDB(dst, b, h) do { _Pragma("unroll") for (int n = 0; n < 2; ++n) _Pragma("unroll") for (int k = 0; k < 2; ++k) dst[n][k] = *(const LAS bf16x8*)(lds + PG8_SB(b, h) + boff + n * 2048 + k * 1024); } while (0)
; #define PG8_MMA(ai, bj, At, Bt) do { __builtin_amdgcn_s_setprio(1); _Pragma("unroll") for (int m = 0; m < 4; ++m) _Pragma("unroll") for (int n = 0; n < 2; ++n) _Pragma("unroll") for (int k = 0; k < 2; ++k) \
;         acc[ai][bj][m][n] = __builtin_amdgcn_mfma_f32_16x16x32_bf16(Bt[n][k], At[m][k], acc[ai][bj][m][n], 0, 0, 0); __builtin_amdgcn_s_setprio(0); } while (0)
; #define PG8_WAIT_V(n) asm volatile("s_waitcnt vmcnt(" #n ")" ::: "memory")
; #define PG8_WAIT_L(n) asm volatile("s_waitcnt lgkmcnt(" #n ")" ::: "memory")
; #define PG8_BAR __builtin_amdgcn_s_barrier()
; #define PG8_SCHED __builtin_amdgcn_sched_barrier(0)
; template <class Epi, class Sched, bool ALIGN_EPI = false, bool SP2 = false>
; __device__ __forceinline__ void gemm_phase(LAS unsigned char* lds, const Gemm g, const Sched& S, const Epi& E) {
;     ...
;             PG8_WAIT_V(8); PG8_WAIT_L(0); PG8_BAR; PG8_MMA(1, 0, At, B0); PG8_MMA(1, 1, At, B1); PG8_BAR; PG8_SCHED;
;             PG8_LDB(B0, 1, 0); PG8_LDB(B1, 1, 1); PG8_SCHED; PG8_LDA(At, 1, 0); PG8_STAGE(PG8_SA(0, 1), a2 + hstep, voffA);
;             PG8_WAIT_V(8); PG8_WAIT_L(0); PG8_BAR; PG8_MMA(0, 0, At, B0); PG8_MMA(0, 1, At, B1); PG8_BAR; PG8_SCHED;
	s_setprio 1
	s_waitcnt lgkmcnt(0)
	v_mfma_f32_16x16x32_bf16 v[60:63], v[140:143], v[188:191], v[60:63]
	v_mfma_f32_16x16x32_bf16 v[56:59], v[164:167], v[188:191], v[56:59]
	v_mfma_f32_16x16x32_bf16 v[48:51], v[140:143], v[196:199], v[48:51]
	v_mfma_f32_16x16x32_bf16 v[40:43], v[164:167], v[196:199], v[40:43]
	v_mfma_f32_16x16x32_bf16 v[32:35], v[140:143], v[204:207], v[32:35]
	v_mfma_f32_16x16x32_bf16 v[24:27], v[164:167], v[204:207], v[24:27]
	v_mfma_f32_16x16x32_bf16 v[16:19], v[140:143], v[212:215], v[16:19]
	v_mfma_f32_16x16x32_bf16 v[8:11], v[164:167], v[212:215], v[8:11]
	v_mfma_f32_16x16x32_bf16 v[60:63], v[144:147], v[192:195], v[60:63]
	v_mfma_f32_16x16x32_bf16 v[56:59], v[168:171], v[192:195], v[56:59]
	v_mfma_f32_16x16x32_bf16 v[48:51], v[144:147], v[200:203], v[48:51]
	v_mfma_f32_16x16x32_bf16 v[40:43], v[168:171], v[200:203], v[40:43]
	v_mfma_f32_16x16x32_bf16 v[32:35], v[144:147], v[208:211], v[32:35]
	v_mfma_f32_16x16x32_bf16 v[24:27], v[168:171], v[208:211], v[24:27]
	v_mfma_f32_16x16x32_bf16 v[16:19], v[144:147], v[216:219], v[16:19]
	v_mfma_f32_16x16x32_bf16 v[8:11], v[168:171], v[216:219], v[8:11]
	s_setprio 0
	s_setprio 1
	v_mfma_f32_16x16x32_bf16 v[52:55], v[172:175], v[188:191], v[52:55]
	v_mfma_f32_16x16x32_bf16 v[44:47], v[180:183], v[188:191], v[44:47]
	v_mfma_f32_16x16x32_bf16 v[36:39], v[172:175], v[196:199], v[36:39]
	v_mfma_f32_16x16x32_bf16 v[28:31], v[180:183], v[196:199], v[28:31]
	v_mfma_f32_16x16x32_bf16 v[20:23], v[172:175], v[204:207], v[20:23]
	v_mfma_f32_16x16x32_bf16 v[12:15], v[180:183], v[204:207], v[12:15]
	v_mfma_f32_16x16x32_bf16 v[4:7], v[172:175], v[212:215], v[4:7]
	v_mfma_f32_16x16x32_bf16 v[0:3], v[180:183], v[212:215], v[0:3]
	v_mfma_f32_16x16x32_bf16 v[52:55], v[176:179], v[192:195], v[52:55]
	v_mfma_f32_16x16x32_bf16 v[44:47], v[184:187], v[192:195], v[44:47]
	v_mfma_f32_16x16x32_bf16 v[36:39], v[176:179], v[200:203], v[36:39]
	v_mfma_f32_16x16x32_bf16 v[28:31], v[184:187], v[200:203], v[28:31]
	v_mfma_f32_16x16x32_bf16 v[20:23], v[176:179], v[208:211], v[20:23]
	v_mfma_f32_16x16x32_bf16 v[12:15], v[184:187], v[208:211], v[12:15]
	v_mfma_f32_16x16x32_bf16 v[4:7], v[176:179], v[216:219], v[4:7]
	v_mfma_f32_16x16x32_bf16 v[0:3], v[184:187], v[216:219], v[0:3]
	s_setprio 0
	s_barrier
	s_add_i32 s76, 0, 0x18000
	v_add_u32_e32 v159, s76, v149
	s_add_i32 s77, 0, 0x1c000
	ds_read_b128 v[140:143], v159
	ds_read_b128 v[144:147], v159 offset:1024
	ds_read_b128 v[164:167], v159 offset:2048
	ds_read_b128 v[168:171], v159 offset:3072
	v_add_u32_e32 v159, s77, v149
	ds_read_b128 v[172:175], v159
	ds_read_b128 v[176:179], v159 offset:1024
	ds_read_b128 v[180:183], v159 offset:2048
	ds_read_b128 v[184:187], v159 offset:3072
	s_add_u32 s48, s54, 0x160000
	s_addc_u32 s49, s55, 0
	s_mov_b32 m0, s61
	v_lshl_add_u64 v[228:229], s[48:49], 0, v[128:129]
	ds_read_b128 v[188:191], v155 offset:32768
	ds_read_b128 v[192:195], v155 offset:33792
	ds_read_b128 v[196:199], v155 offset:34816
	ds_read_b128 v[200:203], v155 offset:35840
	ds_read_b128 v[204:207], v155 offset:36864
	ds_read_b128 v[208:211], v155 offset:37888
	ds_read_b128 v[212:215], v155 offset:38912
	ds_read_b128 v[216:219], v155 offset:39936
	global_load_lds_dwordx4 v[228:229], off sc0
	v_lshl_add_u64 v[228:229], s[48:49], 0, v[130:131]
	s_mov_b32 m0, s62
	s_nop 0
	global_load_lds_dwordx4 v[228:229], off sc0
	s_waitcnt vmcnt(8)
	s_waitcnt lgkmcnt(0)
	s_barrier
	s_setprio 1
	s_waitcnt lgkmcnt(0)
	v_mfma_f32_16x16x32_bf16 v[124:127], v[140:143], v[188:191], v[124:127]
	v_mfma_f32_16x16x32_bf16 v[120:123], v[164:167], v[188:191], v[120:123]
	v_mfma_f32_16x16x32_bf16 v[112:115], v[140:143], v[196:199], v[112:115]
	v_mfma_f32_16x16x32_bf16 v[104:107], v[164:167], v[196:199], v[104:107]
	v_mfma_f32_16x16x32_bf16 v[96:99], v[140:143], v[204:207], v[96:99]
	v_mfma_f32_16x16x32_bf16 v[88:91], v[164:167], v[204:207], v[88:91]
	v_mfma_f32_16x16x32_bf16 v[80:83], v[140:143], v[212:215], v[80:83]
	v_mfma_f32_16x16x32_bf16 v[72:75], v[164:167], v[212:215], v[72:75]
	v_mfma_f32_16x16x32_bf16 v[124:127], v[144:147], v[192:195], v[124:127]
	v_mfma_f32_16x16x32_bf16 v[120:123], v[168:171], v[192:195], v[120:123]
	v_mfma_f32_16x16x32_bf16 v[112:115], v[144:147], v[200:203], v[112:115]
	v_mfma_f32_16x16x32_bf16 v[104:107], v[168:171], v[200:203], v[104:107]
	v_mfma_f32_16x16x32_bf16 v[96:99], v[144:147], v[208:211], v[96:99]
	v_mfma_f32_16x16x32_bf16 v[88:91], v[168:171], v[208:211], v[88:91]
	v_mfma_f32_16x16x32_bf16 v[80:83], v[144:147], v[216:219], v[80:83]
	v_mfma_f32_16x16x32_bf16 v[72:75], v[168:171], v[216:219], v[72:75]
	s_setprio 0
	s_setprio 1
	v_mfma_f32_16x16x32_bf16 v[116:119], v[172:175], v[188:191], v[116:119]
	v_mfma_f32_16x16x32_bf16 v[108:111], v[180:183], v[188:191], v[108:111]
	v_mfma_f32_16x16x32_bf16 v[100:103], v[172:175], v[196:199], v[100:103]
	v_mfma_f32_16x16x32_bf16 v[92:95], v[180:183], v[196:199], v[92:95]
	v_mfma_f32_16x16x32_bf16 v[84:87], v[172:175], v[204:207], v[84:87]
	v_mfma_f32_16x16x32_bf16 v[76:79], v[180:183], v[204:207], v[76:79]
	v_mfma_f32_16x16x32_bf16 v[68:71], v[172:175], v[212:215], v[68:71]
	v_mfma_f32_16x16x32_bf16 v[64:67], v[180:183], v[212:215], v[64:67]
	v_mfma_f32_16x16x32_bf16 v[116:119], v[176:179], v[192:195], v[116:119]
	v_mfma_f32_16x16x32_bf16 v[108:111], v[184:187], v[192:195], v[108:111]
	v_mfma_f32_16x16x32_bf16 v[100:103], v[176:179], v[200:203], v[100:103]
	v_mfma_f32_16x16x32_bf16 v[92:95], v[184:187], v[200:203], v[92:95]
	v_mfma_f32_16x16x32_bf16 v[84:87], v[176:179], v[208:211], v[84:87]
	v_mfma_f32_16x16x32_bf16 v[76:79], v[184:187], v[208:211], v[76:79]
	v_mfma_f32_16x16x32_bf16 v[68:71], v[176:179], v[216:219], v[68:71]
	v_mfma_f32_16x16x32_bf16 v[64:67], v[184:187], v[216:219], v[64:67]
	s_setprio 0
	s_barrier
; #define PG8_STAGE(bufoff, gbase, voff) do { _Pragma("unroll") for (int _i = 0; _i < 2; ++_i) \
;         __builtin_amdgcn_global_load_lds((const unsigned*)((const char*)(gbase) + (voff)[_i]), (LAS unsigned*)(lds + (bufoff) + ldsw + _i * 8192), 16, 0, 1); } while (0)
; #define PG8_LDA(dst, b, h) do { _Pragma("unroll") for (int m = 0; m < 4; ++m) _Pragma("unroll") for (int k = 0; k < 2; ++k) dst[m][k] = *(const LAS bf16x8*)(lds + PG8_SA(b, h) + aoff + m * 2048 + k * 1024); } while (0)
; #define PG8_MMA(ai, bj, At, Bt) do { __builtin_amdgcn_s_setprio(1); _Pragma("unroll") for (int m = 0; m < 4; ++m) _Pragma("unroll") for (int n = 0; n < 2; ++n) _Pragma("unroll") for (int k = 0; k < 2; ++k) \
;         acc[ai][bj][m][n] = __builtin_amdgcn_mfma_f32_16x16x32_bf16(Bt[n][k], At[m][k], acc[ai][bj][m][n], 0, 0, 0); __builtin_amdgcn_s_setprio(0); } while (0)
; #define PG8_WAIT_V(n) asm volatile("s_waitcnt vmcnt(" #n ")" ::: "memory")
; #define PG8_WAIT_L(n) asm volatile("s_waitcnt lgkmcnt(" #n ")" ::: "memory")
; #define PG8_BAR __builtin_amdgcn_s_barrier()
; #define PG8_SCHED __builtin_amdgcn_sched_barrier(0)
; template <class Epi, class Sched, bool ALIGN_EPI = false, bool SP2 = false>
; __device__ __forceinline__ void gemm_phase(LAS unsigned char* lds, const Gemm g, const Sched& S, const Epi& E) {
;     ...
;         for (int t = 0; t < nt; t += 2) {
;             const bool last = (t == nt - 2);
;             const char* a1 = cA + (size_t)(t + 1) * kstep;
;             const char* a2 = last ? nA : cA + (size_t)(t + 2) * kstep; const char* b2 = last ? nB : cB + (size_t)(t + 2) * kstep;
;     ...
;             PG8_LDA(At, 1, 1); PG8_STAGE(PG8_SB(1, 0), b3, voffB); PG8_STAGE(PG8_SB(1, 1), b3 + hstep, voffB); PG8_STAGE(PG8_SA(1, 0), a3, voffA);
;             PG8_WAIT_V(8); PG8_WAIT_L(0); PG8_BAR; PG8_MMA(1, 0, At, B0); PG8_MMA(1, 1, At, B1); PG8_BAR; PG8_SCHED;
	s_add_i32 s48, s76, s58
	v_lshl_add_u64 v[220:221], v[220:221], 0, s[14:15]
	s_mov_b32 m0, s48
	ds_read_b128 v[188:191], v155 offset:49152
	ds_read_b128 v[192:195], v155 offset:50176
	ds_read_b128 v[196:199], v155 offset:51200
	ds_read_b128 v[200:203], v155 offset:52224
	ds_read_b128 v[204:207], v155 offset:53248
	ds_read_b128 v[208:211], v155 offset:54272
	ds_read_b128 v[212:215], v155 offset:55296
	ds_read_b128 v[216:219], v155 offset:56320
	global_load_lds_dwordx4 v[220:221], off sc0
	s_add_i32 m0, s48, 0x2000
	s_add_u32 s48, s52, 0x160080
	v_lshl_add_u64 v[220:221], v[222:223], 0, s[14:15]
	s_addc_u32 s49, s53, 0
	s_add_i32 s52, s77, s58
	global_load_lds_dwordx4 v[220:221], off sc0
	v_lshl_add_u64 v[220:221], s[48:49], 0, v[128:129]
	s_mov_b32 m0, s52
	s_nop 0
	global_load_lds_dwordx4 v[220:221], off sc0
	v_lshl_add_u64 v[220:221], s[48:49], 0, v[130:131]
	s_add_i32 m0, s52, 0x2000
	s_nop 0
	global_load_lds_dwordx4 v[220:221], off sc0
	v_lshl_add_u64 v[220:221], v[224:225], 0, s[14:15]
	s_mov_b32 m0, s66
	s_nop 0
	global_load_lds_dwordx4 v[220:221], off sc0
	v_lshl_add_u64 v[220:221], v[226:227], 0, s[14:15]
	s_mov_b32 m0, s67
	s_nop 0
	global_load_lds_dwordx4 v[220:221], off sc0
	s_waitcnt vmcnt(8)
	s_waitcnt lgkmcnt(0)
	s_barrier
	s_setprio 1
	s_waitcnt lgkmcnt(0)
	v_mfma_f32_16x16x32_bf16 v[60:63], v[140:143], v[188:191], v[60:63]
	v_mfma_f32_16x16x32_bf16 v[56:59], v[164:167], v[188:191], v[56:59]
	v_mfma_f32_16x16x32_bf16 v[48:51], v[140:143], v[196:199], v[48:51]
	v_mfma_f32_16x16x32_bf16 v[40:43], v[164:167], v[196:199], v[40:43]
	v_mfma_f32_16x16x32_bf16 v[32:35], v[140:143], v[204:207], v[32:35]
	v_mfma_f32_16x16x32_bf16 v[24:27], v[164:167], v[204:207], v[24:27]
	v_mfma_f32_16x16x32_bf16 v[16:19], v[140:143], v[212:215], v[16:19]
	v_mfma_f32_16x16x32_bf16 v[8:11], v[164:167], v[212:215], v[8:11]
	v_mfma_f32_16x16x32_bf16 v[60:63], v[144:147], v[192:195], v[60:63]
	v_mfma_f32_16x16x32_bf16 v[56:59], v[168:171], v[192:195], v[56:59]
	v_mfma_f32_16x16x32_bf16 v[48:51], v[144:147], v[200:203], v[48:51]
	v_mfma_f32_16x16x32_bf16 v[40:43], v[168:171], v[200:203], v[40:43]
	v_mfma_f32_16x16x32_bf16 v[32:35], v[144:147], v[208:211], v[32:35]
	v_mfma_f32_16x16x32_bf16 v[24:27], v[168:171], v[208:211], v[24:27]
	v_mfma_f32_16x16x32_bf16 v[16:19], v[144:147], v[216:219], v[16:19]
	v_mfma_f32_16x16x32_bf16 v[8:11], v[168:171], v[216:219], v[8:11]
	s_setprio 0
	s_setprio 1
	v_mfma_f32_16x16x32_bf16 v[52:55], v[172:175], v[188:191], v[52:55]
	v_mfma_f32_16x16x32_bf16 v[44:47], v[180:183], v[188:191], v[44:47]
	v_mfma_f32_16x16x32_bf16 v[36:39], v[172:175], v[196:199], v[36:39]
	v_mfma_f32_16x16x32_bf16 v[28:31], v[180:183], v[196:199], v[28:31]
	v_mfma_f32_16x16x32_bf16 v[20:23], v[172:175], v[204:207], v[20:23]
	v_mfma_f32_16x16x32_bf16 v[12:15], v[180:183], v[204:207], v[12:15]
	v_mfma_f32_16x16x32_bf16 v[4:7], v[172:175], v[212:215], v[4:7]
	v_mfma_f32_16x16x32_bf16 v[0:3], v[180:183], v[212:215], v[0:3]
	v_mfma_f32_16x16x32_bf16 v[52:55], v[176:179], v[192:195], v[52:55]
	v_mfma_f32_16x16x32_bf16 v[44:47], v[184:187], v[192:195], v[44:47]
	v_mfma_f32_16x16x32_bf16 v[36:39], v[176:179], v[200:203], v[36:39]
	v_mfma_f32_16x16x32_bf16 v[28:31], v[184:187], v[200:203], v[28:31]
	v_mfma_f32_16x16x32_bf16 v[20:23], v[176:179], v[208:211], v[20:23]
	v_mfma_f32_16x16x32_bf16 v[12:15], v[184:187], v[208:211], v[12:15]
	v_mfma_f32_16x16x32_bf16 v[4:7], v[176:179], v[216:219], v[4:7]
	v_mfma_f32_16x16x32_bf16 v[0:3], v[184:187], v[216:219], v[0:3]
	s_setprio 0
	s_add_i32 s75, s75, 2
	s_add_u32 s42, s42, 0x100
	s_addc_u32 s43, s43, 0
	s_cmpk_gt_u32 s75, 0x55
	s_mov_b64 s[48:49], s[50:51]
	s_barrier
	s_cbranch_scc0 .LBB0_154
	s_and_b64 vcc, exec, s[24:25]
	s_cbranch_vccz .LBB0_157
	s_barrier

; #define PG8_STAGE(bufoff, gbase, voff) do { _Pragma("unroll") for (int _i = 0; _i < 2; ++_i) \
;         __builtin_amdgcn_global_load_lds((const unsigned*)((const char*)(gbase) + (voff)[_i]), (LAS unsigned*)(lds + (bufoff) + ldsw + _i * 8192), 16, 0, 1); } while (0)
; #define PG8_LDA(dst, b, h) do { _Pragma("unroll") for (int m = 0; m < 4; ++m) _Pragma("unroll") for (int k = 0; k < 2; ++k) dst[m][k] = *(const LAS bf16x8*)(lds + PG8_SA(b, h) + aoff + m * 2048 + k * 1024); } while (0)
; #define PG8_LDB(dst, b, h) do { _Pragma("unroll") for (int n = 0; n < 2; ++n) _Pragma("unroll") for (int k = 0; k < 2; ++k) dst[n][k] = *(const LAS bf16x8*)(lds + PG8_SB(b, h) + boff + n * 2048 + k * 1024); } while (0)
; #define PG8_MMA(ai, bj, At, Bt) do { __builtin_amdgcn_s_setprio(1); _Pragma("unroll") for (int m = 0; m < 4; ++m) _Pragma("unroll") for (int n = 0; n < 2; ++n) _Pragma("unroll") for (int k = 0; k < 2; ++k) \
;         acc[ai][bj][m][n] = __builtin_amdgcn_mfma_f32_16x16x32_bf16(Bt[n][k], At[m][k], acc[ai][bj][m][n], 0, 0, 0); __builtin_amdgcn_s_setprio(0); } while (0)
; #define PG8_WAIT_V(n) asm volatile("s_waitcnt vmcnt(" #n ")" ::: "memory")
; #define PG8_WAIT_L(n) asm volatile("s_waitcnt lgkmcnt(" #n ")" ::: "memory")
; #define PG8_BAR __builtin_amdgcn_s_barrier()
; template <class Epi, class Sched, bool ALIGN_EPI = false, bool SP2 = false>
; __device__ __forceinline__ void gemm_phase(LAS unsigned char* lds, const Gemm g, const Sched& S, const Epi& E) {
;     ...
;             const bool last = (t == nt - 2);
;             const char* a1 = cA + (size_t)(t + 1) * kstep;
;             const char* a2 = last ? nA : cA + (size_t)(t + 2) * kstep; const char* b2 = last ? nB : cB + (size_t)(t + 2) * kstep;
;             const char* a3 = a2 + kstep; const char* b3 = b2 + kstep;
;             if (last && has_next) S.a_ready(nxt);
;             if constexpr (SP2) {
;             PG8_LDB(B0, 0, 0); PG8_LDB(B1, 0, 1); PG8_SCHED; PG8_LDA(At, 0, 0); PG8_STAGE(PG8_SA(1, 1), a1 + hstep, voffA);
;             PG8_WAIT_V(8); PG8_WAIT_L(0); PG8_BAR; PG8_MMA(0, 0, At, B0); PG8_MMA(0, 1, At, B1); PG8_BAR; PG8_SCHED;
;             PG8_LDA(At, 0, 1); PG8_STAGE(PG8_SB(0, 0), b2, voffB); PG8_STAGE(PG8_SB(0, 1), b2 + hstep, voffB); PG8_STAGE(PG8_SA(0, 0), a2, voffA);
;             PG8_WAIT_V(8); PG8_WAIT_L(0); PG8_BAR; PG8_MMA(1, 0, At, B0); PG8_MMA(1, 1, At, B1); PG8_BAR; PG8_SCHED;
.LBB0_219:
	ds_read_b128 v[164:167], v151
	ds_read_b128 v[168:171], v151 offset:1024
	ds_read_b128 v[172:175], v151 offset:2048
	ds_read_b128 v[176:179], v151 offset:3072
	ds_read_b128 v[180:183], v153
	ds_read_b128 v[184:187], v153 offset:1024
	ds_read_b128 v[188:191], v153 offset:2048
	ds_read_b128 v[192:195], v153 offset:3072
	s_add_u32 s6, s58, 0xfff80080
	s_addc_u32 s7, s59, -1
	s_cmp_eq_u32 s43, 28
	s_cselect_b32 s63, s51, s7
	s_cselect_b32 s62, s57, s6
	s_cselect_b32 s61, s49, s42
	s_cselect_b32 s60, s80, s81
	v_lshl_add_u64 v[146:147], s[58:59], 0, v[138:139]
	s_add_i32 m0, s69, 0xc000
	ds_read_b128 v[196:199], v155
	ds_read_b128 v[200:203], v155 offset:1024
	ds_read_b128 v[204:207], v155 offset:2048
	ds_read_b128 v[208:211], v155 offset:3072
	ds_read_b128 v[212:215], v155 offset:4096
	ds_read_b128 v[216:219], v155 offset:5120
	ds_read_b128 v[220:223], v155 offset:6144
	ds_read_b128 v[224:227], v155 offset:7168
	global_load_lds_dwordx4 v[146:147], off sc0
	v_lshl_add_u64 v[146:147], s[58:59], 0, v[140:141]
	s_add_i32 m0, s69, 0xe000
	s_nop 0
	global_load_lds_dwordx4 v[146:147], off sc0
	s_waitcnt vmcnt(8)
	s_waitcnt lgkmcnt(0)
	s_barrier
	s_setprio 1
	s_waitcnt lgkmcnt(0)
	v_mfma_f32_16x16x32_bf16 v[124:127], v[164:167], v[196:199], v[124:127]
	v_mfma_f32_16x16x32_bf16 v[120:123], v[172:175], v[196:199], v[120:123]
	v_mfma_f32_16x16x32_bf16 v[116:119], v[164:167], v[204:207], v[116:119]
	v_mfma_f32_16x16x32_bf16 v[112:115], v[172:175], v[204:207], v[112:115]
	v_mfma_f32_16x16x32_bf16 v[100:103], v[164:167], v[212:215], v[100:103]
	v_mfma_f32_16x16x32_bf16 v[96:99], v[172:175], v[212:215], v[96:99]
	v_mfma_f32_16x16x32_bf16 v[84:87], v[164:167], v[220:223], v[84:87]
	v_mfma_f32_16x16x32_bf16 v[80:83], v[172:175], v[220:223], v[80:83]
	v_mfma_f32_16x16x32_bf16 v[124:127], v[168:171], v[200:203], v[124:127]
	v_mfma_f32_16x16x32_bf16 v[120:123], v[176:179], v[200:203], v[120:123]
	v_mfma_f32_16x16x32_bf16 v[116:119], v[168:171], v[208:211], v[116:119]
	v_mfma_f32_16x16x32_bf16 v[112:115], v[176:179], v[208:211], v[112:115]
	v_mfma_f32_16x16x32_bf16 v[100:103], v[168:171], v[216:219], v[100:103]
	v_mfma_f32_16x16x32_bf16 v[96:99], v[176:179], v[216:219], v[96:99]
	v_mfma_f32_16x16x32_bf16 v[84:87], v[168:171], v[224:227], v[84:87]
	v_mfma_f32_16x16x32_bf16 v[80:83], v[176:179], v[224:227], v[80:83]
	s_setprio 0
	s_setprio 1
	v_mfma_f32_16x16x32_bf16 v[108:111], v[180:183], v[196:199], v[108:111]
	v_mfma_f32_16x16x32_bf16 v[104:107], v[188:191], v[196:199], v[104:107]
	v_mfma_f32_16x16x32_bf16 v[92:95], v[180:183], v[204:207], v[92:95]
	v_mfma_f32_16x16x32_bf16 v[88:91], v[188:191], v[204:207], v[88:91]
	v_mfma_f32_16x16x32_bf16 v[76:79], v[180:183], v[212:215], v[76:79]
	v_mfma_f32_16x16x32_bf16 v[72:75], v[188:191], v[212:215], v[72:75]
	v_mfma_f32_16x16x32_bf16 v[68:71], v[180:183], v[220:223], v[68:71]
	v_mfma_f32_16x16x32_bf16 v[64:67], v[188:191], v[220:223], v[64:67]
	v_mfma_f32_16x16x32_bf16 v[108:111], v[184:187], v[200:203], v[108:111]
	v_mfma_f32_16x16x32_bf16 v[104:107], v[192:195], v[200:203], v[104:107]
	v_mfma_f32_16x16x32_bf16 v[92:95], v[184:187], v[208:211], v[92:95]
	v_mfma_f32_16x16x32_bf16 v[88:91], v[192:195], v[208:211], v[88:91]
	v_mfma_f32_16x16x32_bf16 v[76:79], v[184:187], v[216:219], v[76:79]
	v_mfma_f32_16x16x32_bf16 v[72:75], v[192:195], v[216:219], v[72:75]
	v_mfma_f32_16x16x32_bf16 v[68:71], v[184:187], v[224:227], v[68:71]
	v_mfma_f32_16x16x32_bf16 v[64:67], v[192:195], v[224:227], v[64:67]
	s_setprio 0
	s_barrier
	s_add_i32 s6, s77, s66
	v_lshl_add_u64 v[146:147], s[60:61], 0, v[132:133]
	s_mov_b32 m0, s6
	ds_read_b128 v[196:199], v155 offset:16384
	ds_read_b128 v[200:203], v155 offset:17408
	ds_read_b128 v[204:207], v155 offset:18432
	ds_read_b128 v[208:211], v155 offset:19456
	ds_read_b128 v[212:215], v155 offset:20480
	ds_read_b128 v[216:219], v155 offset:21504
	ds_read_b128 v[220:223], v155 offset:22528
	ds_read_b128 v[224:227], v155 offset:23552
	global_load_lds_dwordx4 v[146:147], off sc0
	s_add_i32 m0, s6, 0x2000
	s_add_u32 s6, s60, 0x80000
	v_lshl_add_u64 v[228:229], s[60:61], 0, v[128:129]
	s_addc_u32 s7, s61, 0
	s_add_i32 s82, s78, s66
	global_load_lds_dwordx4 v[228:229], off sc0
	v_lshl_add_u64 v[230:231], s[6:7], 0, v[132:133]
	s_mov_b32 m0, s82
	v_lshl_add_u64 v[232:233], s[62:63], 0, v[130:131]
	global_load_lds_dwordx4 v[230:231], off sc0
	v_lshl_add_u64 v[230:231], s[6:7], 0, v[128:129]
	s_add_i32 m0, s82, 0x2000
	s_nop 0
	global_load_lds_dwordx4 v[230:231], off sc0
	v_lshl_add_u64 v[230:231], s[62:63], 0, v[134:135]
	s_mov_b32 m0, s69
	s_nop 0
	global_load_lds_dwordx4 v[230:231], off sc0
	s_mov_b32 m0, s70
	s_nop 0
	global_load_lds_dwordx4 v[232:233], off sc0
	s_waitcnt vmcnt(8)
	s_waitcnt lgkmcnt(0)
	s_barrier
; #define PG8_STAGE(bufoff, gbase, voff) do { _Pragma("unroll") for (int _i = 0; _i < 2; ++_i) \
;         __builtin_amdgcn_global_load_lds((const unsigned*)((const char*)(gbase) + (voff)[_i]), (LAS unsigned*)(lds + (bufoff) + ldsw + _i * 8192), 16, 0, 1); } while (0)
; #define PG8_LDA(dst, b, h) do { _Pragma("unroll") for (int m = 0; m < 4; ++m) _Pragma("unroll") for (int k = 0; k < 2; ++k) dst[m][k] = *(const LAS bf16x8*)(lds + PG8_SA(b, h) + aoff + m * 2048 + k * 1024); } while (0)
; #define PG8_LDB(dst, b, h) do { _Pragma("unroll") for (int n = 0; n < 2; ++n) _Pragma("unroll") for (int k = 0; k < 2; ++k) dst[n][k] = *(const LAS bf16x8*)(lds + PG8_SB(b, h) + boff + n * 2048 + k * 1024); } while (0)
; #define PG8_MMA(ai, bj, At, Bt) do { __builtin_amdgcn_s_setprio(1); _Pragma("unroll") for (int m = 0; m < 4; ++m) _Pragma("unroll") for (int n = 0; n < 2; ++n) _Pragma("unroll") for (int k = 0; k < 2; ++k) \
;         acc[ai][bj][m][n] = __builtin_amdgcn_mfma_f32_16x16x32_bf16(Bt[n][k], At[m][k], acc[ai][bj][m][n], 0, 0, 0); __builtin_amdgcn_s_setprio(0); } while (0)
; #define PG8_WAIT_V(n) asm volatile("s_waitcnt vmcnt(" #n ")" ::: "memory")
; #define PG8_WAIT_L(n) asm volatile("s_waitcnt lgkmcnt(" #n ")" ::: "memory")
; #define PG8_BAR __builtin_amdgcn_s_barrier()
; #define PG8_SCHED __builtin_amdgcn_sched_barrier(0)
; template <class Epi, class Sched, bool ALIGN_EPI = false, bool SP2 = false>
; __device__ __forceinline__ void gemm_phase(LAS unsigned char* lds, const Gemm g, const Sched& S, const Epi& E) {
;     ...
;             PG8_WAIT_V(8); PG8_WAIT_L(0); PG8_BAR; PG8_MMA(1, 0, At, B0); PG8_MMA(1, 1, At, B1); PG8_BAR; PG8_SCHED;
;             PG8_LDB(B0, 1, 0); PG8_LDB(B1, 1, 1); PG8_SCHED; PG8_LDA(At, 1, 0); PG8_STAGE(PG8_SA(0, 1), a2 + hstep, voffA);
;             PG8_WAIT_V(8); PG8_WAIT_L(0); PG8_BAR; PG8_MMA(0, 0, At, B0); PG8_MMA(0, 1, At, B1); PG8_BAR; PG8_SCHED;
	s_setprio 1
	s_waitcnt lgkmcnt(0)
	v_mfma_f32_16x16x32_bf16 v[60:63], v[164:167], v[196:199], v[60:63]
	v_mfma_f32_16x16x32_bf16 v[56:59], v[172:175], v[196:199], v[56:59]
	v_mfma_f32_16x16x32_bf16 v[52:55], v[164:167], v[204:207], v[52:55]
	v_mfma_f32_16x16x32_bf16 v[48:51], v[172:175], v[204:207], v[48:51]
	v_mfma_f32_16x16x32_bf16 v[36:39], v[164:167], v[212:215], v[36:39]
	v_mfma_f32_16x16x32_bf16 v[32:35], v[172:175], v[212:215], v[32:35]
	v_mfma_f32_16x16x32_bf16 v[20:23], v[164:167], v[220:223], v[20:23]
	v_mfma_f32_16x16x32_bf16 v[16:19], v[172:175], v[220:223], v[16:19]
	v_mfma_f32_16x16x32_bf16 v[60:63], v[168:171], v[200:203], v[60:63]
	v_mfma_f32_16x16x32_bf16 v[56:59], v[176:179], v[200:203], v[56:59]
	v_mfma_f32_16x16x32_bf16 v[52:55], v[168:171], v[208:211], v[52:55]
	v_mfma_f32_16x16x32_bf16 v[48:51], v[176:179], v[208:211], v[48:51]
	v_mfma_f32_16x16x32_bf16 v[36:39], v[168:171], v[216:219], v[36:39]
	v_mfma_f32_16x16x32_bf16 v[32:35], v[176:179], v[216:219], v[32:35]
	v_mfma_f32_16x16x32_bf16 v[20:23], v[168:171], v[224:227], v[20:23]
	v_mfma_f32_16x16x32_bf16 v[16:19], v[176:179], v[224:227], v[16:19]
	s_setprio 0
	s_setprio 1
	v_mfma_f32_16x16x32_bf16 v[44:47], v[180:183], v[196:199], v[44:47]
	v_mfma_f32_16x16x32_bf16 v[40:43], v[188:191], v[196:199], v[40:43]
	v_mfma_f32_16x16x32_bf16 v[28:31], v[180:183], v[204:207], v[28:31]
	v_mfma_f32_16x16x32_bf16 v[24:27], v[188:191], v[204:207], v[24:27]
	v_mfma_f32_16x16x32_bf16 v[12:15], v[180:183], v[212:215], v[12:15]
	v_mfma_f32_16x16x32_bf16 v[8:11], v[188:191], v[212:215], v[8:11]
	v_mfma_f32_16x16x32_bf16 v[4:7], v[180:183], v[220:223], v[4:7]
	v_mfma_f32_16x16x32_bf16 v[0:3], v[188:191], v[220:223], v[0:3]
	v_mfma_f32_16x16x32_bf16 v[44:47], v[184:187], v[200:203], v[44:47]
	v_mfma_f32_16x16x32_bf16 v[40:43], v[192:195], v[200:203], v[40:43]
	v_mfma_f32_16x16x32_bf16 v[28:31], v[184:187], v[208:211], v[28:31]
	v_mfma_f32_16x16x32_bf16 v[24:27], v[192:195], v[208:211], v[24:27]
	v_mfma_f32_16x16x32_bf16 v[12:15], v[184:187], v[216:219], v[12:15]
	v_mfma_f32_16x16x32_bf16 v[8:11], v[192:195], v[216:219], v[8:11]
	v_mfma_f32_16x16x32_bf16 v[4:7], v[184:187], v[224:227], v[4:7]
	v_mfma_f32_16x16x32_bf16 v[0:3], v[192:195], v[224:227], v[0:3]
	s_setprio 0
	s_barrier
	s_add_i32 s82, 0, 0x18000
	v_add_u32_e32 v159, s82, v149
	s_add_i32 s83, 0, 0x1c000
	ds_read_b128 v[164:167], v159
	ds_read_b128 v[168:171], v159 offset:1024
	ds_read_b128 v[172:175], v159 offset:2048
	ds_read_b128 v[176:179], v159 offset:3072
	v_add_u32_e32 v159, s83, v149
	ds_read_b128 v[180:183], v159
	ds_read_b128 v[184:187], v159 offset:1024
	ds_read_b128 v[188:191], v159 offset:2048
	ds_read_b128 v[192:195], v159 offset:3072
	s_add_u32 s6, s62, 0x80000
	s_addc_u32 s7, s63, 0
	s_mov_b32 m0, s71
	v_lshl_add_u64 v[234:235], s[6:7], 0, v[134:135]
	ds_read_b128 v[196:199], v155 offset:32768
	ds_read_b128 v[200:203], v155 offset:33792
	ds_read_b128 v[204:207], v155 offset:34816
	ds_read_b128 v[208:211], v155 offset:35840
	ds_read_b128 v[212:215], v155 offset:36864
	ds_read_b128 v[216:219], v155 offset:37888
	ds_read_b128 v[220:223], v155 offset:38912
	ds_read_b128 v[224:227], v155 offset:39936
	global_load_lds_dwordx4 v[234:235], off sc0
	v_lshl_add_u64 v[234:235], s[6:7], 0, v[130:131]
	s_mov_b32 m0, s72
	s_nop 0
	global_load_lds_dwordx4 v[234:235], off sc0
	s_waitcnt vmcnt(8)
	s_waitcnt lgkmcnt(0)
	s_barrier
	s_setprio 1
	s_waitcnt lgkmcnt(0)
	v_mfma_f32_16x16x32_bf16 v[124:127], v[164:167], v[196:199], v[124:127]
	v_mfma_f32_16x16x32_bf16 v[120:123], v[172:175], v[196:199], v[120:123]
	v_mfma_f32_16x16x32_bf16 v[116:119], v[164:167], v[204:207], v[116:119]
	v_mfma_f32_16x16x32_bf16 v[112:115], v[172:175], v[204:207], v[112:115]
	v_mfma_f32_16x16x32_bf16 v[100:103], v[164:167], v[212:215], v[100:103]
	v_mfma_f32_16x16x32_bf16 v[96:99], v[172:175], v[212:215], v[96:99]
	v_mfma_f32_16x16x32_bf16 v[84:87], v[164:167], v[220:223], v[84:87]
	v_mfma_f32_16x16x32_bf16 v[80:83], v[172:175], v[220:223], v[80:83]
	v_mfma_f32_16x16x32_bf16 v[124:127], v[168:171], v[200:203], v[124:127]
	v_mfma_f32_16x16x32_bf16 v[120:123], v[176:179], v[200:203], v[120:123]
	v_mfma_f32_16x16x32_bf16 v[116:119], v[168:171], v[208:211], v[116:119]
	v_mfma_f32_16x16x32_bf16 v[112:115], v[176:179], v[208:211], v[112:115]
	v_mfma_f32_16x16x32_bf16 v[100:103], v[168:171], v[216:219], v[100:103]
	v_mfma_f32_16x16x32_bf16 v[96:99], v[176:179], v[216:219], v[96:99]
	v_mfma_f32_16x16x32_bf16 v[84:87], v[168:171], v[224:227], v[84:87]
	v_mfma_f32_16x16x32_bf16 v[80:83], v[176:179], v[224:227], v[80:83]
	s_setprio 0
	s_setprio 1
	v_mfma_f32_16x16x32_bf16 v[108:111], v[180:183], v[196:199], v[108:111]
	v_mfma_f32_16x16x32_bf16 v[104:107], v[188:191], v[196:199], v[104:107]
	v_mfma_f32_16x16x32_bf16 v[92:95], v[180:183], v[204:207], v[92:95]
	v_mfma_f32_16x16x32_bf16 v[88:91], v[188:191], v[204:207], v[88:91]
	v_mfma_f32_16x16x32_bf16 v[76:79], v[180:183], v[212:215], v[76:79]
	v_mfma_f32_16x16x32_bf16 v[72:75], v[188:191], v[212:215], v[72:75]
	v_mfma_f32_16x16x32_bf16 v[68:71], v[180:183], v[220:223], v[68:71]
	v_mfma_f32_16x16x32_bf16 v[64:67], v[188:191], v[220:223], v[64:67]
	v_mfma_f32_16x16x32_bf16 v[108:111], v[184:187], v[200:203], v[108:111]
	v_mfma_f32_16x16x32_bf16 v[104:107], v[192:195], v[200:203], v[104:107]
	v_mfma_f32_16x16x32_bf16 v[92:95], v[184:187], v[208:211], v[92:95]
	v_mfma_f32_16x16x32_bf16 v[88:91], v[192:195], v[208:211], v[88:91]
	v_mfma_f32_16x16x32_bf16 v[76:79], v[184:187], v[216:219], v[76:79]
	v_mfma_f32_16x16x32_bf16 v[72:75], v[192:195], v[216:219], v[72:75]
	v_mfma_f32_16x16x32_bf16 v[68:71], v[184:187], v[224:227], v[68:71]
	v_mfma_f32_16x16x32_bf16 v[64:67], v[192:195], v[224:227], v[64:67]
	s_setprio 0
	s_barrier
; #define PG8_STAGE(bufoff, gbase, voff) do { _Pragma("unroll") for (int _i = 0; _i < 2; ++_i) \
;         __builtin_amdgcn_global_load_lds((const unsigned*)((const char*)(gbase) + (voff)[_i]), (LAS unsigned*)(lds + (bufoff) + ldsw + _i * 8192), 16, 0, 1); } while (0)
; #define PG8_LDA(dst, b, h) do { _Pragma("unroll") for (int m = 0; m < 4; ++m) _Pragma("unroll") for (int k = 0; k < 2; ++k) dst[m][k] = *(const LAS bf16x8*)(lds + PG8_SA(b, h) + aoff + m * 2048 + k * 1024); } while (0)
; #define PG8_MMA(ai, bj, At, Bt) do { __builtin_amdgcn_s_setprio(1); _Pragma("unroll") for (int m = 0; m < 4; ++m) _Pragma("unroll") for (int n = 0; n < 2; ++n) _Pragma("unroll") for (int k = 0; k < 2; ++k) \
;         acc[ai][bj][m][n] = __builtin_amdgcn_mfma_f32_16x16x32_bf16(Bt[n][k], At[m][k], acc[ai][bj][m][n], 0, 0, 0); __builtin_amdgcn_s_setprio(0); } while (0)
; #define PG8_WAIT_V(n) asm volatile("s_waitcnt vmcnt(" #n ")" ::: "memory")
; #define PG8_WAIT_L(n) asm volatile("s_waitcnt lgkmcnt(" #n ")" ::: "memory")
; #define PG8_BAR __builtin_amdgcn_s_barrier()
; #define PG8_SCHED __builtin_amdgcn_sched_barrier(0)
; template <class Epi, class Sched, bool ALIGN_EPI = false, bool SP2 = false>
; __device__ __forceinline__ void gemm_phase(LAS unsigned char* lds, const Gemm g, const Sched& S, const Epi& E) {
;     ...
;         for (int t = 0; t < nt; t += 2) {
;             const bool last = (t == nt - 2);
;             const char* a1 = cA + (size_t)(t + 1) * kstep;
;             const char* a2 = last ? nA : cA + (size_t)(t + 2) * kstep; const char* b2 = last ? nB : cB + (size_t)(t + 2) * kstep;
;     ...
;             PG8_LDA(At, 1, 1); PG8_STAGE(PG8_SB(1, 0), b3, voffB); PG8_STAGE(PG8_SB(1, 1), b3 + hstep, voffB); PG8_STAGE(PG8_SA(1, 0), a3, voffA);
;             PG8_WAIT_V(8); PG8_WAIT_L(0); PG8_BAR; PG8_MMA(1, 0, At, B0); PG8_MMA(1, 1, At, B1); PG8_BAR; PG8_SCHED;
	s_add_i32 s6, s82, s66
	v_lshl_add_u64 v[146:147], v[146:147], 0, s[22:23]
	s_mov_b32 m0, s6
	ds_read_b128 v[196:199], v155 offset:49152
	ds_read_b128 v[200:203], v155 offset:50176
	ds_read_b128 v[204:207], v155 offset:51200
	ds_read_b128 v[208:211], v155 offset:52224
	ds_read_b128 v[212:215], v155 offset:53248
	ds_read_b128 v[216:219], v155 offset:54272
	ds_read_b128 v[220:223], v155 offset:55296
	ds_read_b128 v[224:227], v155 offset:56320
	global_load_lds_dwordx4 v[146:147], off sc0
	s_add_i32 m0, s6, 0x2000
	s_add_u32 s6, s60, 0x80080
	v_lshl_add_u64 v[146:147], v[228:229], 0, s[22:23]
	s_addc_u32 s7, s61, 0
	s_add_i32 s60, s83, s66
	global_load_lds_dwordx4 v[146:147], off sc0
	v_lshl_add_u64 v[146:147], s[6:7], 0, v[132:133]
	s_mov_b32 m0, s60
	s_nop 0
	global_load_lds_dwordx4 v[146:147], off sc0
	v_lshl_add_u64 v[146:147], s[6:7], 0, v[128:129]
	s_add_i32 m0, s60, 0x2000
	s_nop 0
	global_load_lds_dwordx4 v[146:147], off sc0
	v_lshl_add_u64 v[146:147], v[230:231], 0, s[22:23]
	s_mov_b32 m0, s74
	s_nop 0
	global_load_lds_dwordx4 v[146:147], off sc0
	v_lshl_add_u64 v[146:147], v[232:233], 0, s[22:23]
	s_mov_b32 m0, s75
	s_nop 0
	global_load_lds_dwordx4 v[146:147], off sc0
	s_waitcnt vmcnt(8)
	s_waitcnt lgkmcnt(0)
	s_barrier
	s_setprio 1
	s_waitcnt lgkmcnt(0)
	v_mfma_f32_16x16x32_bf16 v[60:63], v[164:167], v[196:199], v[60:63]
	v_mfma_f32_16x16x32_bf16 v[56:59], v[172:175], v[196:199], v[56:59]
	v_mfma_f32_16x16x32_bf16 v[52:55], v[164:167], v[204:207], v[52:55]
	v_mfma_f32_16x16x32_bf16 v[48:51], v[172:175], v[204:207], v[48:51]
	v_mfma_f32_16x16x32_bf16 v[36:39], v[164:167], v[212:215], v[36:39]
	v_mfma_f32_16x16x32_bf16 v[32:35], v[172:175], v[212:215], v[32:35]
	v_mfma_f32_16x16x32_bf16 v[20:23], v[164:167], v[220:223], v[20:23]
	v_mfma_f32_16x16x32_bf16 v[16:19], v[172:175], v[220:223], v[16:19]
	v_mfma_f32_16x16x32_bf16 v[60:63], v[168:171], v[200:203], v[60:63]
	v_mfma_f32_16x16x32_bf16 v[56:59], v[176:179], v[200:203], v[56:59]
	v_mfma_f32_16x16x32_bf16 v[52:55], v[168:171], v[208:211], v[52:55]
	v_mfma_f32_16x16x32_bf16 v[48:51], v[176:179], v[208:211], v[48:51]
	v_mfma_f32_16x16x32_bf16 v[36:39], v[168:171], v[216:219], v[36:39]
	v_mfma_f32_16x16x32_bf16 v[32:35], v[176:179], v[216:219], v[32:35]
	v_mfma_f32_16x16x32_bf16 v[20:23], v[168:171], v[224:227], v[20:23]
	v_mfma_f32_16x16x32_bf16 v[16:19], v[176:179], v[224:227], v[16:19]
	s_setprio 0
	s_setprio 1
	v_mfma_f32_16x16x32_bf16 v[44:47], v[180:183], v[196:199], v[44:47]
	v_mfma_f32_16x16x32_bf16 v[40:43], v[188:191], v[196:199], v[40:43]
	v_mfma_f32_16x16x32_bf16 v[28:31], v[180:183], v[204:207], v[28:31]
	v_mfma_f32_16x16x32_bf16 v[24:27], v[188:191], v[204:207], v[24:27]
	v_mfma_f32_16x16x32_bf16 v[12:15], v[180:183], v[212:215], v[12:15]
	v_mfma_f32_16x16x32_bf16 v[8:11], v[188:191], v[212:215], v[8:11]
	v_mfma_f32_16x16x32_bf16 v[4:7], v[180:183], v[220:223], v[4:7]
	v_mfma_f32_16x16x32_bf16 v[0:3], v[188:191], v[220:223], v[0:3]
	v_mfma_f32_16x16x32_bf16 v[44:47], v[184:187], v[200:203], v[44:47]
	v_mfma_f32_16x16x32_bf16 v[40:43], v[192:195], v[200:203], v[40:43]
	v_mfma_f32_16x16x32_bf16 v[28:31], v[184:187], v[208:211], v[28:31]
	v_mfma_f32_16x16x32_bf16 v[24:27], v[192:195], v[208:211], v[24:27]
	v_mfma_f32_16x16x32_bf16 v[12:15], v[184:187], v[216:219], v[12:15]
	v_mfma_f32_16x16x32_bf16 v[8:11], v[192:195], v[216:219], v[8:11]
	v_mfma_f32_16x16x32_bf16 v[4:7], v[184:187], v[224:227], v[4:7]
	v_mfma_f32_16x16x32_bf16 v[0:3], v[192:195], v[224:227], v[0:3]
	s_setprio 0
	s_add_i32 s43, s43, 2
	s_add_u32 s58, s58, 0x100
	s_addc_u32 s59, s59, 0
	s_add_u32 s81, s81, 0x100
	s_addc_u32 s42, s42, 0
	s_cmp_gt_u32 s43, 29
	s_barrier
	s_cbranch_scc0 .LBB0_219
	s_and_b64 vcc, exec, s[24:25]
	s_cbranch_vccnz .LBB0_224
	v_lshl_add_u32 v146, s56, 8, v148
	s_cmp_gt_i32 s79, 23
	s_mov_b64 s[56:57], -1
	s_cbranch_scc1 .LBB0_225

; #define PG8_STAGE(bufoff, gbase, voff) do { _Pragma("unroll") for (int _i = 0; _i < 2; ++_i) \
;         __builtin_amdgcn_global_load_lds((const unsigned*)((const char*)(gbase) + (voff)[_i]), (LAS unsigned*)(lds + (bufoff) + ldsw + _i * 8192), 16, 0, 1); } while (0)
; #define PG8_LDA(dst, b, h) do { _Pragma("unroll") for (int m = 0; m < 4; ++m) _Pragma("unroll") for (int k = 0; k < 2; ++k) dst[m][k] = *(const LAS bf16x8*)(lds + PG8_SA(b, h) + aoff + m * 2048 + k * 1024); } while (0)
; #define PG8_LDB(dst, b, h) do { _Pragma("unroll") for (int n = 0; n < 2; ++n) _Pragma("unroll") for (int k = 0; k < 2; ++k) dst[n][k] = *(const LAS bf16x8*)(lds + PG8_SB(b, h) + boff + n * 2048 + k * 1024); } while (0)
; #define PG8_MMA(ai, bj, At, Bt) do { __builtin_amdgcn_s_setprio(1); _Pragma("unroll") for (int m = 0; m < 4; ++m) _Pragma("unroll") for (int n = 0; n < 2; ++n) _Pragma("unroll") for (int k = 0; k < 2; ++k) \
;         acc[ai][bj][m][n] = __builtin_amdgcn_mfma_f32_16x16x32_bf16(Bt[n][k], At[m][k], acc[ai][bj][m][n], 0, 0, 0); __builtin_amdgcn_s_setprio(0); } while (0)
; #define PG8_WAIT_V(n) asm volatile("s_waitcnt vmcnt(" #n ")" ::: "memory")
; #define PG8_WAIT_L(n) asm volatile("s_waitcnt lgkmcnt(" #n ")" ::: "memory")
; #define PG8_BAR __builtin_amdgcn_s_barrier()
; template <class Epi, class Sched, bool ALIGN_EPI = false, bool SP2 = false>
; __device__ __forceinline__ void gemm_phase(LAS unsigned char* lds, const Gemm g, const Sched& S, const Epi& E) {
;     ...
;             const bool last = (t == nt - 2);
;             const char* a1 = cA + (size_t)(t + 1) * kstep;
;             const char* a2 = last ? nA : cA + (size_t)(t + 2) * kstep; const char* b2 = last ? nB : cB + (size_t)(t + 2) * kstep;
;             const char* a3 = a2 + kstep; const char* b3 = b2 + kstep;
;             if (last && has_next) S.a_ready(nxt);
;             if constexpr (SP2) {
;             PG8_LDB(B0, 0, 0); PG8_LDB(B1, 0, 1); PG8_SCHED; PG8_LDA(At, 0, 0); PG8_STAGE(PG8_SA(1, 1), a1 + hstep, voffA);
;             PG8_WAIT_V(8); PG8_WAIT_L(0); PG8_BAR; PG8_MMA(0, 0, At, B0); PG8_MMA(0, 1, At, B1); PG8_BAR; PG8_SCHED;
;             PG8_LDA(At, 0, 1); PG8_STAGE(PG8_SB(0, 0), b2, voffB); PG8_STAGE(PG8_SB(0, 1), b2 + hstep, voffB); PG8_STAGE(PG8_SA(0, 0), a2, voffA);
;             PG8_WAIT_V(8); PG8_WAIT_L(0); PG8_BAR; PG8_MMA(1, 0, At, B0); PG8_MMA(1, 1, At, B1); PG8_BAR; PG8_SCHED;
.LBB0_433:
	s_add_u32 s7, s64, 0xfff80080
	s_addc_u32 s46, s65, -1
	s_add_i32 s47, 0, 0x10000
	s_cmp_eq_u32 s6, 28
	s_cselect_b32 s69, s59, s46
	s_cselect_b32 s68, vcc_lo, s7
	s_cselect_b32 s67, s57, s43
	s_cselect_b32 s66, vcc_hi, s42
	s_add_i32 s7, 0, 0x14000
	v_add_u32_e32 v178, s47, v188
	v_add_u32_e32 v186, s7, v188
	ds_read_b128 v[166:169], v178
	ds_read_b128 v[170:173], v178 offset:1024
	ds_read_b128 v[174:177], v178 offset:2048
	ds_read_b128 v[178:181], v178 offset:3072
	ds_read_b128 v[182:185], v186
	ds_read_b128 v[192:195], v186 offset:1024
	ds_read_b128 v[196:199], v186 offset:2048
	ds_read_b128 v[200:203], v186 offset:3072
	v_lshl_add_u64 v[236:237], s[64:65], 0, v[162:163]
	s_add_i32 m0, s87, 0xc000
	ds_read_b128 v[204:207], v190
	ds_read_b128 v[208:211], v190 offset:1024
	ds_read_b128 v[212:215], v190 offset:2048
	ds_read_b128 v[216:219], v190 offset:3072
	ds_read_b128 v[220:223], v190 offset:4096
	ds_read_b128 v[224:227], v190 offset:5120
	ds_read_b128 v[228:231], v190 offset:6144
	ds_read_b128 v[232:235], v190 offset:7168
	global_load_lds_dwordx4 v[236:237], off sc0
	v_lshl_add_u64 v[236:237], s[64:65], 0, v[164:165]
	s_add_i32 m0, s87, 0xe000
	s_nop 0
	global_load_lds_dwordx4 v[236:237], off sc0
	s_waitcnt vmcnt(8)
	s_waitcnt lgkmcnt(0)
	s_barrier
	s_setprio 1
	s_waitcnt lgkmcnt(0)
	v_mfma_f32_16x16x32_bf16 v[124:127], v[166:169], v[204:207], v[124:127]
	v_mfma_f32_16x16x32_bf16 v[120:123], v[174:177], v[204:207], v[120:123]
	v_mfma_f32_16x16x32_bf16 v[116:119], v[166:169], v[212:215], v[116:119]
	v_mfma_f32_16x16x32_bf16 v[112:115], v[174:177], v[212:215], v[112:115]
	v_mfma_f32_16x16x32_bf16 v[100:103], v[166:169], v[220:223], v[100:103]
	v_mfma_f32_16x16x32_bf16 v[96:99], v[174:177], v[220:223], v[96:99]
	v_mfma_f32_16x16x32_bf16 v[84:87], v[166:169], v[228:231], v[84:87]
	v_mfma_f32_16x16x32_bf16 v[80:83], v[174:177], v[228:231], v[80:83]
	v_mfma_f32_16x16x32_bf16 v[124:127], v[170:173], v[208:211], v[124:127]
	v_mfma_f32_16x16x32_bf16 v[120:123], v[178:181], v[208:211], v[120:123]
	v_mfma_f32_16x16x32_bf16 v[116:119], v[170:173], v[216:219], v[116:119]
	v_mfma_f32_16x16x32_bf16 v[112:115], v[178:181], v[216:219], v[112:115]
	v_mfma_f32_16x16x32_bf16 v[100:103], v[170:173], v[224:227], v[100:103]
	v_mfma_f32_16x16x32_bf16 v[96:99], v[178:181], v[224:227], v[96:99]
	v_mfma_f32_16x16x32_bf16 v[84:87], v[170:173], v[232:235], v[84:87]
	v_mfma_f32_16x16x32_bf16 v[80:83], v[178:181], v[232:235], v[80:83]
	s_setprio 0
	s_setprio 1
	v_mfma_f32_16x16x32_bf16 v[108:111], v[182:185], v[204:207], v[108:111]
	v_mfma_f32_16x16x32_bf16 v[104:107], v[196:199], v[204:207], v[104:107]
	v_mfma_f32_16x16x32_bf16 v[92:95], v[182:185], v[212:215], v[92:95]
	v_mfma_f32_16x16x32_bf16 v[88:91], v[196:199], v[212:215], v[88:91]
	v_mfma_f32_16x16x32_bf16 v[76:79], v[182:185], v[220:223], v[76:79]
	v_mfma_f32_16x16x32_bf16 v[72:75], v[196:199], v[220:223], v[72:75]
	v_mfma_f32_16x16x32_bf16 v[68:71], v[182:185], v[228:231], v[68:71]
	v_mfma_f32_16x16x32_bf16 v[64:67], v[196:199], v[228:231], v[64:67]
	v_mfma_f32_16x16x32_bf16 v[108:111], v[192:195], v[208:211], v[108:111]
	v_mfma_f32_16x16x32_bf16 v[104:107], v[200:203], v[208:211], v[104:107]
	v_mfma_f32_16x16x32_bf16 v[92:95], v[192:195], v[216:219], v[92:95]
	v_mfma_f32_16x16x32_bf16 v[88:91], v[200:203], v[216:219], v[88:91]
	v_mfma_f32_16x16x32_bf16 v[76:79], v[192:195], v[224:227], v[76:79]
	v_mfma_f32_16x16x32_bf16 v[72:75], v[200:203], v[224:227], v[72:75]
	v_mfma_f32_16x16x32_bf16 v[68:71], v[192:195], v[232:235], v[68:71]
	v_mfma_f32_16x16x32_bf16 v[64:67], v[200:203], v[232:235], v[64:67]
	s_setprio 0
	s_barrier
	s_add_i32 s46, s47, s86
	v_lshl_add_u64 v[236:237], s[66:67], 0, v[136:137]
	s_mov_b32 m0, s46
	ds_read_b128 v[204:207], v190 offset:16384
	ds_read_b128 v[208:211], v190 offset:17408
	ds_read_b128 v[212:215], v190 offset:18432
	ds_read_b128 v[216:219], v190 offset:19456
	ds_read_b128 v[220:223], v190 offset:20480
	ds_read_b128 v[224:227], v190 offset:21504
	ds_read_b128 v[228:231], v190 offset:22528
	ds_read_b128 v[232:235], v190 offset:23552
	global_load_lds_dwordx4 v[236:237], off sc0
	s_add_i32 m0, s46, 0x2000
	s_add_u32 s46, s66, 0x80000
	v_lshl_add_u64 v[238:239], s[66:67], 0, v[142:143]
	s_addc_u32 s47, s67, 0
	s_add_i32 s7, s7, s86
	global_load_lds_dwordx4 v[238:239], off sc0
	v_lshl_add_u64 v[240:241], s[46:47], 0, v[136:137]
	s_mov_b32 m0, s7
	v_lshl_add_u64 v[242:243], s[68:69], 0, v[144:145]
	global_load_lds_dwordx4 v[240:241], off sc0
	v_lshl_add_u64 v[240:241], s[46:47], 0, v[142:143]
	s_add_i32 m0, s7, 0x2000
	s_nop 0
	global_load_lds_dwordx4 v[240:241], off sc0
	v_lshl_add_u64 v[240:241], s[68:69], 0, v[146:147]
	s_mov_b32 m0, s87
	s_nop 0
	global_load_lds_dwordx4 v[240:241], off sc0
	s_mov_b32 m0, s88
	s_nop 0
	global_load_lds_dwordx4 v[242:243], off sc0
	s_waitcnt vmcnt(8)
	s_waitcnt lgkmcnt(0)
	s_barrier
; #define PG8_STAGE(bufoff, gbase, voff) do { _Pragma("unroll") for (int _i = 0; _i < 2; ++_i) \
;         __builtin_amdgcn_global_load_lds((const unsigned*)((const char*)(gbase) + (voff)[_i]), (LAS unsigned*)(lds + (bufoff) + ldsw + _i * 8192), 16, 0, 1); } while (0)
; #define PG8_LDA(dst, b, h) do { _Pragma("unroll") for (int m = 0; m < 4; ++m) _Pragma("unroll") for (int k = 0; k < 2; ++k) dst[m][k] = *(const LAS bf16x8*)(lds + PG8_SA(b, h) + aoff + m * 2048 + k * 1024); } while (0)
; #define PG8_LDB(dst, b, h) do { _Pragma("unroll") for (int n = 0; n < 2; ++n) _Pragma("unroll") for (int k = 0; k < 2; ++k) dst[n][k] = *(const LAS bf16x8*)(lds + PG8_SB(b, h) + boff + n * 2048 + k * 1024); } while (0)
; #define PG8_MMA(ai, bj, At, Bt) do { __builtin_amdgcn_s_setprio(1); _Pragma("unroll") for (int m = 0; m < 4; ++m) _Pragma("unroll") for (int n = 0; n < 2; ++n) _Pragma("unroll") for (int k = 0; k < 2; ++k) \
;         acc[ai][bj][m][n] = __builtin_amdgcn_mfma_f32_16x16x32_bf16(Bt[n][k], At[m][k], acc[ai][bj][m][n], 0, 0, 0); __builtin_amdgcn_s_setprio(0); } while (0)
; #define PG8_WAIT_V(n) asm volatile("s_waitcnt vmcnt(" #n ")" ::: "memory")
; #define PG8_WAIT_L(n) asm volatile("s_waitcnt lgkmcnt(" #n ")" ::: "memory")
; #define PG8_BAR __builtin_amdgcn_s_barrier()
; #define PG8_SCHED __builtin_amdgcn_sched_barrier(0)
; template <class Epi, class Sched, bool ALIGN_EPI = false, bool SP2 = false>
; __device__ __forceinline__ void gemm_phase(LAS unsigned char* lds, const Gemm g, const Sched& S, const Epi& E) {
;     ...
;             PG8_WAIT_V(8); PG8_WAIT_L(0); PG8_BAR; PG8_MMA(1, 0, At, B0); PG8_MMA(1, 1, At, B1); PG8_BAR; PG8_SCHED;
;             PG8_LDB(B0, 1, 0); PG8_LDB(B1, 1, 1); PG8_SCHED; PG8_LDA(At, 1, 0); PG8_STAGE(PG8_SA(0, 1), a2 + hstep, voffA);
;             PG8_WAIT_V(8); PG8_WAIT_L(0); PG8_BAR; PG8_MMA(0, 0, At, B0); PG8_MMA(0, 1, At, B1); PG8_BAR; PG8_SCHED;
	s_setprio 1
	s_waitcnt lgkmcnt(0)
	v_mfma_f32_16x16x32_bf16 v[60:63], v[166:169], v[204:207], v[60:63]
	v_mfma_f32_16x16x32_bf16 v[56:59], v[174:177], v[204:207], v[56:59]
	v_mfma_f32_16x16x32_bf16 v[52:55], v[166:169], v[212:215], v[52:55]
	v_mfma_f32_16x16x32_bf16 v[48:51], v[174:177], v[212:215], v[48:51]
	v_mfma_f32_16x16x32_bf16 v[36:39], v[166:169], v[220:223], v[36:39]
	v_mfma_f32_16x16x32_bf16 v[32:35], v[174:177], v[220:223], v[32:35]
	v_mfma_f32_16x16x32_bf16 v[20:23], v[166:169], v[228:231], v[20:23]
	v_mfma_f32_16x16x32_bf16 v[16:19], v[174:177], v[228:231], v[16:19]
	v_mfma_f32_16x16x32_bf16 v[60:63], v[170:173], v[208:211], v[60:63]
	v_mfma_f32_16x16x32_bf16 v[56:59], v[178:181], v[208:211], v[56:59]
	v_mfma_f32_16x16x32_bf16 v[52:55], v[170:173], v[216:219], v[52:55]
	v_mfma_f32_16x16x32_bf16 v[48:51], v[178:181], v[216:219], v[48:51]
	v_mfma_f32_16x16x32_bf16 v[36:39], v[170:173], v[224:227], v[36:39]
	v_mfma_f32_16x16x32_bf16 v[32:35], v[178:181], v[224:227], v[32:35]
	v_mfma_f32_16x16x32_bf16 v[20:23], v[170:173], v[232:235], v[20:23]
	v_mfma_f32_16x16x32_bf16 v[16:19], v[178:181], v[232:235], v[16:19]
	s_setprio 0
	s_setprio 1
	v_mfma_f32_16x16x32_bf16 v[44:47], v[182:185], v[204:207], v[44:47]
	v_mfma_f32_16x16x32_bf16 v[40:43], v[196:199], v[204:207], v[40:43]
	v_mfma_f32_16x16x32_bf16 v[28:31], v[182:185], v[212:215], v[28:31]
	v_mfma_f32_16x16x32_bf16 v[24:27], v[196:199], v[212:215], v[24:27]
	v_mfma_f32_16x16x32_bf16 v[12:15], v[182:185], v[220:223], v[12:15]
	v_mfma_f32_16x16x32_bf16 v[8:11], v[196:199], v[220:223], v[8:11]
	v_mfma_f32_16x16x32_bf16 v[4:7], v[182:185], v[228:231], v[4:7]
	v_mfma_f32_16x16x32_bf16 v[0:3], v[196:199], v[228:231], v[0:3]
	v_mfma_f32_16x16x32_bf16 v[44:47], v[192:195], v[208:211], v[44:47]
	v_mfma_f32_16x16x32_bf16 v[40:43], v[200:203], v[208:211], v[40:43]
	v_mfma_f32_16x16x32_bf16 v[28:31], v[192:195], v[216:219], v[28:31]
	v_mfma_f32_16x16x32_bf16 v[24:27], v[200:203], v[216:219], v[24:27]
	v_mfma_f32_16x16x32_bf16 v[12:15], v[192:195], v[224:227], v[12:15]
	v_mfma_f32_16x16x32_bf16 v[8:11], v[200:203], v[224:227], v[8:11]
	v_mfma_f32_16x16x32_bf16 v[4:7], v[192:195], v[232:235], v[4:7]
	v_mfma_f32_16x16x32_bf16 v[0:3], v[200:203], v[232:235], v[0:3]
	s_setprio 0
	s_barrier
	s_add_i32 s7, 0, 0x18000
	s_add_i32 s44, 0, 0x1c000
	v_add_u32_e32 v178, s7, v188
	v_add_u32_e32 v186, s44, v188
	ds_read_b128 v[166:169], v178
	ds_read_b128 v[170:173], v178 offset:1024
	ds_read_b128 v[174:177], v178 offset:2048
	ds_read_b128 v[178:181], v178 offset:3072
	ds_read_b128 v[182:185], v186
	ds_read_b128 v[192:195], v186 offset:1024
	ds_read_b128 v[196:199], v186 offset:2048
	ds_read_b128 v[200:203], v186 offset:3072
	s_add_u32 s46, s68, 0x80000
	s_addc_u32 s47, s69, 0
	s_mov_b32 m0, s89
	v_lshl_add_u64 v[244:245], s[46:47], 0, v[146:147]
	ds_read_b128 v[204:207], v190 offset:32768
	ds_read_b128 v[208:211], v190 offset:33792
	ds_read_b128 v[212:215], v190 offset:34816
	ds_read_b128 v[216:219], v190 offset:35840
	ds_read_b128 v[220:223], v190 offset:36864
	ds_read_b128 v[224:227], v190 offset:37888
	ds_read_b128 v[228:231], v190 offset:38912
	ds_read_b128 v[232:235], v190 offset:39936
	global_load_lds_dwordx4 v[244:245], off sc0
	v_lshl_add_u64 v[244:245], s[46:47], 0, v[144:145]
	s_mov_b32 m0, s90
	s_nop 0
	global_load_lds_dwordx4 v[244:245], off sc0
	s_waitcnt vmcnt(8)
	s_waitcnt lgkmcnt(0)
	s_barrier
	s_setprio 1
	s_waitcnt lgkmcnt(0)
	v_mfma_f32_16x16x32_bf16 v[124:127], v[166:169], v[204:207], v[124:127]
	v_mfma_f32_16x16x32_bf16 v[120:123], v[174:177], v[204:207], v[120:123]
	v_mfma_f32_16x16x32_bf16 v[116:119], v[166:169], v[212:215], v[116:119]
	v_mfma_f32_16x16x32_bf16 v[112:115], v[174:177], v[212:215], v[112:115]
	v_mfma_f32_16x16x32_bf16 v[100:103], v[166:169], v[220:223], v[100:103]
	v_mfma_f32_16x16x32_bf16 v[96:99], v[174:177], v[220:223], v[96:99]
	v_mfma_f32_16x16x32_bf16 v[84:87], v[166:169], v[228:231], v[84:87]
	v_mfma_f32_16x16x32_bf16 v[80:83], v[174:177], v[228:231], v[80:83]
	v_mfma_f32_16x16x32_bf16 v[124:127], v[170:173], v[208:211], v[124:127]
	v_mfma_f32_16x16x32_bf16 v[120:123], v[178:181], v[208:211], v[120:123]
	v_mfma_f32_16x16x32_bf16 v[116:119], v[170:173], v[216:219], v[116:119]
	v_mfma_f32_16x16x32_bf16 v[112:115], v[178:181], v[216:219], v[112:115]
	v_mfma_f32_16x16x32_bf16 v[100:103], v[170:173], v[224:227], v[100:103]
	v_mfma_f32_16x16x32_bf16 v[96:99], v[178:181], v[224:227], v[96:99]
	v_mfma_f32_16x16x32_bf16 v[84:87], v[170:173], v[232:235], v[84:87]
	v_mfma_f32_16x16x32_bf16 v[80:83], v[178:181], v[232:235], v[80:83]
	s_setprio 0
	s_setprio 1
	v_mfma_f32_16x16x32_bf16 v[108:111], v[182:185], v[204:207], v[108:111]
	v_mfma_f32_16x16x32_bf16 v[104:107], v[196:199], v[204:207], v[104:107]
	v_mfma_f32_16x16x32_bf16 v[92:95], v[182:185], v[212:215], v[92:95]
	v_mfma_f32_16x16x32_bf16 v[88:91], v[196:199], v[212:215], v[88:91]
	v_mfma_f32_16x16x32_bf16 v[76:79], v[182:185], v[220:223], v[76:79]
	v_mfma_f32_16x16x32_bf16 v[72:75], v[196:199], v[220:223], v[72:75]
	v_mfma_f32_16x16x32_bf16 v[68:71], v[182:185], v[228:231], v[68:71]
	v_mfma_f32_16x16x32_bf16 v[64:67], v[196:199], v[228:231], v[64:67]
	v_mfma_f32_16x16x32_bf16 v[108:111], v[192:195], v[208:211], v[108:111]
	v_mfma_f32_16x16x32_bf16 v[104:107], v[200:203], v[208:211], v[104:107]
	v_mfma_f32_16x16x32_bf16 v[92:95], v[192:195], v[216:219], v[92:95]
	v_mfma_f32_16x16x32_bf16 v[88:91], v[200:203], v[216:219], v[88:91]
	v_mfma_f32_16x16x32_bf16 v[76:79], v[192:195], v[224:227], v[76:79]
	v_mfma_f32_16x16x32_bf16 v[72:75], v[200:203], v[224:227], v[72:75]
	v_mfma_f32_16x16x32_bf16 v[68:71], v[192:195], v[232:235], v[68:71]
	v_mfma_f32_16x16x32_bf16 v[64:67], v[200:203], v[232:235], v[64:67]
	s_setprio 0
	s_barrier
; #define PG8_STAGE(bufoff, gbase, voff) do { _Pragma("unroll") for (int _i = 0; _i < 2; ++_i) \
;         __builtin_amdgcn_global_load_lds((const unsigned*)((const char*)(gbase) + (voff)[_i]), (LAS unsigned*)(lds + (bufoff) + ldsw + _i * 8192), 16, 0, 1); } while (0)
; #define PG8_LDA(dst, b, h) do { _Pragma("unroll") for (int m = 0; m < 4; ++m) _Pragma("unroll") for (int k = 0; k < 2; ++k) dst[m][k] = *(const LAS bf16x8*)(lds + PG8_SA(b, h) + aoff + m * 2048 + k * 1024); } while (0)
; #define PG8_MMA(ai, bj, At, Bt) do { __builtin_amdgcn_s_setprio(1); _Pragma("unroll") for (int m = 0; m < 4; ++m) _Pragma("unroll") for (int n = 0; n < 2; ++n) _Pragma("unroll") for (int k = 0; k < 2; ++k) \
;         acc[ai][bj][m][n] = __builtin_amdgcn_mfma_f32_16x16x32_bf16(Bt[n][k], At[m][k], acc[ai][bj][m][n], 0, 0, 0); __builtin_amdgcn_s_setprio(0); } while (0)
; #define PG8_WAIT_V(n) asm volatile("s_waitcnt vmcnt(" #n ")" ::: "memory")
; #define PG8_WAIT_L(n) asm volatile("s_waitcnt lgkmcnt(" #n ")" ::: "memory")
; #define PG8_BAR __builtin_amdgcn_s_barrier()
; #define PG8_SCHED __builtin_amdgcn_sched_barrier(0)
; template <class Epi, class Sched, bool ALIGN_EPI = false, bool SP2 = false>
; __device__ __forceinline__ void gemm_phase(LAS unsigned char* lds, const Gemm g, const Sched& S, const Epi& E) {
;     ...
;         for (int t = 0; t < nt; t += 2) {
;             const bool last = (t == nt - 2);
;             const char* a1 = cA + (size_t)(t + 1) * kstep;
;             const char* a2 = last ? nA : cA + (size_t)(t + 2) * kstep; const char* b2 = last ? nB : cB + (size_t)(t + 2) * kstep;
;     ...
;             PG8_LDA(At, 1, 1); PG8_STAGE(PG8_SB(1, 0), b3, voffB); PG8_STAGE(PG8_SB(1, 1), b3 + hstep, voffB); PG8_STAGE(PG8_SA(1, 0), a3, voffA);
;             PG8_WAIT_V(8); PG8_WAIT_L(0); PG8_BAR; PG8_MMA(1, 0, At, B0); PG8_MMA(1, 1, At, B1); PG8_BAR; PG8_SCHED;
	s_add_i32 s7, s7, s86
	v_lshl_add_u64 v[236:237], v[236:237], 0, s[48:49]
	s_mov_b32 m0, s7
	ds_read_b128 v[204:207], v190 offset:49152
	ds_read_b128 v[208:211], v190 offset:50176
	ds_read_b128 v[212:215], v190 offset:51200
	ds_read_b128 v[216:219], v190 offset:52224
	ds_read_b128 v[220:223], v190 offset:53248
	ds_read_b128 v[224:227], v190 offset:54272
	ds_read_b128 v[228:231], v190 offset:55296
	ds_read_b128 v[232:235], v190 offset:56320
	global_load_lds_dwordx4 v[236:237], off sc0
	s_add_i32 m0, s7, 0x2000
	s_add_u32 s46, s66, 0x80080
	v_lshl_add_u64 v[236:237], v[238:239], 0, s[48:49]
	s_addc_u32 s47, s67, 0
	s_add_i32 s7, s44, s86
	global_load_lds_dwordx4 v[236:237], off sc0
	v_lshl_add_u64 v[236:237], s[46:47], 0, v[136:137]
	s_mov_b32 m0, s7
	s_nop 0
	global_load_lds_dwordx4 v[236:237], off sc0
	v_lshl_add_u64 v[236:237], s[46:47], 0, v[142:143]
	s_add_i32 m0, s7, 0x2000
	s_nop 0
	global_load_lds_dwordx4 v[236:237], off sc0
	v_lshl_add_u64 v[236:237], v[240:241], 0, s[48:49]
	s_mov_b32 m0, s93
	s_nop 0
	global_load_lds_dwordx4 v[236:237], off sc0
	v_lshl_add_u64 v[236:237], v[242:243], 0, s[48:49]
	s_mov_b32 m0, s94
	s_nop 0
	global_load_lds_dwordx4 v[236:237], off sc0
	s_waitcnt vmcnt(8)
	s_waitcnt lgkmcnt(0)
	s_barrier
	s_setprio 1
	s_waitcnt lgkmcnt(0)
	v_mfma_f32_16x16x32_bf16 v[60:63], v[166:169], v[204:207], v[60:63]
	v_mfma_f32_16x16x32_bf16 v[56:59], v[174:177], v[204:207], v[56:59]
	v_mfma_f32_16x16x32_bf16 v[52:55], v[166:169], v[212:215], v[52:55]
	v_mfma_f32_16x16x32_bf16 v[48:51], v[174:177], v[212:215], v[48:51]
	v_mfma_f32_16x16x32_bf16 v[36:39], v[166:169], v[220:223], v[36:39]
	v_mfma_f32_16x16x32_bf16 v[32:35], v[174:177], v[220:223], v[32:35]
	v_mfma_f32_16x16x32_bf16 v[20:23], v[166:169], v[228:231], v[20:23]
	v_mfma_f32_16x16x32_bf16 v[16:19], v[174:177], v[228:231], v[16:19]
	v_mfma_f32_16x16x32_bf16 v[60:63], v[170:173], v[208:211], v[60:63]
	v_mfma_f32_16x16x32_bf16 v[56:59], v[178:181], v[208:211], v[56:59]
	v_mfma_f32_16x16x32_bf16 v[52:55], v[170:173], v[216:219], v[52:55]
	v_mfma_f32_16x16x32_bf16 v[48:51], v[178:181], v[216:219], v[48:51]
	v_mfma_f32_16x16x32_bf16 v[36:39], v[170:173], v[224:227], v[36:39]
	v_mfma_f32_16x16x32_bf16 v[32:35], v[178:181], v[224:227], v[32:35]
	v_mfma_f32_16x16x32_bf16 v[20:23], v[170:173], v[232:235], v[20:23]
	v_mfma_f32_16x16x32_bf16 v[16:19], v[178:181], v[232:235], v[16:19]
	s_setprio 0
	s_setprio 1
	v_mfma_f32_16x16x32_bf16 v[44:47], v[182:185], v[204:207], v[44:47]
	v_mfma_f32_16x16x32_bf16 v[40:43], v[196:199], v[204:207], v[40:43]
	v_mfma_f32_16x16x32_bf16 v[28:31], v[182:185], v[212:215], v[28:31]
	v_mfma_f32_16x16x32_bf16 v[24:27], v[196:199], v[212:215], v[24:27]
	v_mfma_f32_16x16x32_bf16 v[12:15], v[182:185], v[220:223], v[12:15]
	v_mfma_f32_16x16x32_bf16 v[8:11], v[196:199], v[220:223], v[8:11]
	v_mfma_f32_16x16x32_bf16 v[4:7], v[182:185], v[228:231], v[4:7]
	v_mfma_f32_16x16x32_bf16 v[0:3], v[196:199], v[228:231], v[0:3]
	v_mfma_f32_16x16x32_bf16 v[44:47], v[192:195], v[208:211], v[44:47]
	v_mfma_f32_16x16x32_bf16 v[40:43], v[200:203], v[208:211], v[40:43]
	v_mfma_f32_16x16x32_bf16 v[28:31], v[192:195], v[216:219], v[28:31]
	v_mfma_f32_16x16x32_bf16 v[24:27], v[200:203], v[216:219], v[24:27]
	v_mfma_f32_16x16x32_bf16 v[12:15], v[192:195], v[224:227], v[12:15]
	v_mfma_f32_16x16x32_bf16 v[8:11], v[200:203], v[224:227], v[8:11]
	v_mfma_f32_16x16x32_bf16 v[4:7], v[192:195], v[232:235], v[4:7]
	v_mfma_f32_16x16x32_bf16 v[0:3], v[200:203], v[232:235], v[0:3]
	s_setprio 0
	s_add_i32 s6, s6, 2
	s_add_u32 s64, s64, 0x100
	s_addc_u32 s65, s65, 0
	s_add_u32 s42, s42, 0x100
	s_addc_u32 s43, s43, 0
	s_cmp_gt_u32 s6, 29
	s_barrier
	s_cbranch_scc0 .LBB0_433
	s_and_b64 vcc, exec, s[54:55]
	s_cbranch_vccz .LBB0_436
	s_barrier

; #define PG8_STAGE(bufoff, gbase, voff) do { _Pragma("unroll") for (int _i = 0; _i < 2; ++_i) \
;         __builtin_amdgcn_global_load_lds((const unsigned*)((const char*)(gbase) + (voff)[_i]), (LAS unsigned*)(lds + (bufoff) + ldsw + _i * 8192), 16, 0, 1); } while (0)
; #define PG8_LDA(dst, b, h) do { _Pragma("unroll") for (int m = 0; m < 4; ++m) _Pragma("unroll") for (int k = 0; k < 2; ++k) dst[m][k] = *(const LAS bf16x8*)(lds + PG8_SA(b, h) + aoff + m * 2048 + k * 1024); } while (0)
; #define PG8_LDB(dst, b, h) do { _Pragma("unroll") for (int n = 0; n < 2; ++n) _Pragma("unroll") for (int k = 0; k < 2; ++k) dst[n][k] = *(const LAS bf16x8*)(lds + PG8_SB(b, h) + boff + n * 2048 + k * 1024); } while (0)
; #define PG8_MMA(ai, bj, At, Bt) do { __builtin_amdgcn_s_setprio(1); _Pragma("unroll") for (int m = 0; m < 4; ++m) _Pragma("unroll") for (int n = 0; n < 2; ++n) _Pragma("unroll") for (int k = 0; k < 2; ++k) \
;         acc[ai][bj][m][n] = __builtin_amdgcn_mfma_f32_16x16x32_bf16(Bt[n][k], At[m][k], acc[ai][bj][m][n], 0, 0, 0); __builtin_amdgcn_s_setprio(0); } while (0)
; #define PG8_WAIT_V(n) asm volatile("s_waitcnt vmcnt(" #n ")" ::: "memory")
; #define PG8_WAIT_L(n) asm volatile("s_waitcnt lgkmcnt(" #n ")" ::: "memory")
; #define PG8_BAR __builtin_amdgcn_s_barrier()
; template <class Epi, class Sched, bool ALIGN_EPI = false, bool SP2 = false>
; __device__ __forceinline__ void gemm_phase(LAS unsigned char* lds, const Gemm g, const Sched& S, const Epi& E) {
;     ...
;             const bool last = (t == nt - 2);
;             const char* a1 = cA + (size_t)(t + 1) * kstep;
;             const char* a2 = last ? nA : cA + (size_t)(t + 2) * kstep; const char* b2 = last ? nB : cB + (size_t)(t + 2) * kstep;
;             const char* a3 = a2 + kstep; const char* b3 = b2 + kstep;
;             if (last && has_next) S.a_ready(nxt);
;             if constexpr (SP2) {
;             PG8_LDB(B0, 0, 0); PG8_LDB(B1, 0, 1); PG8_SCHED; PG8_LDA(At, 0, 0); PG8_STAGE(PG8_SA(1, 1), a1 + hstep, voffA);
;             PG8_WAIT_V(8); PG8_WAIT_L(0); PG8_BAR; PG8_MMA(0, 0, At, B0); PG8_MMA(0, 1, At, B1); PG8_BAR; PG8_SCHED;
;             PG8_LDA(At, 0, 1); PG8_STAGE(PG8_SB(0, 0), b2, voffB); PG8_STAGE(PG8_SB(0, 1), b2 + hstep, voffB); PG8_STAGE(PG8_SA(0, 0), a2, voffA);
;             PG8_WAIT_V(8); PG8_WAIT_L(0); PG8_BAR; PG8_MMA(1, 0, At, B0); PG8_MMA(1, 1, At, B1); PG8_BAR; PG8_SCHED;
.LBB0_516:
	ds_read_b128 v[146:149], v159
	ds_read_b128 v[164:167], v159 offset:1024
	ds_read_b128 v[168:171], v159 offset:2048
	ds_read_b128 v[172:175], v159 offset:3072
	ds_read_b128 v[176:179], v161
	ds_read_b128 v[180:183], v161 offset:1024
	ds_read_b128 v[188:191], v161 offset:2048
	ds_read_b128 v[192:195], v161 offset:3072
	s_add_u32 s6, s54, 0xfff80080
	s_addc_u32 s7, s55, -1
	s_cmp_eq_u32 s43, 28
	s_cselect_b32 s59, s47, s7
	s_cselect_b32 s58, s82, s6
	s_cselect_b32 s57, s39, s42
	s_cselect_b32 s56, s83, s84
	v_lshl_add_u64 v[150:151], s[54:55], 0, v[138:139]
	s_add_i32 m0, s53, 0xc000
	ds_read_b128 v[196:199], v162
	ds_read_b128 v[200:203], v162 offset:1024
	ds_read_b128 v[204:207], v162 offset:2048
	ds_read_b128 v[208:211], v162 offset:3072
	ds_read_b128 v[212:215], v162 offset:4096
	ds_read_b128 v[216:219], v162 offset:5120
	ds_read_b128 v[220:223], v162 offset:6144
	ds_read_b128 v[224:227], v162 offset:7168
	global_load_lds_dwordx4 v[150:151], off sc0
	v_lshl_add_u64 v[150:151], s[54:55], 0, v[140:141]
	s_add_i32 m0, s53, 0xe000
	s_nop 0
	global_load_lds_dwordx4 v[150:151], off sc0
	s_waitcnt vmcnt(8)
	s_waitcnt lgkmcnt(0)
	s_barrier
	s_setprio 1
	s_waitcnt lgkmcnt(0)
	v_mfma_f32_16x16x32_bf16 v[124:127], v[146:149], v[196:199], v[124:127]
	v_mfma_f32_16x16x32_bf16 v[120:123], v[168:171], v[196:199], v[120:123]
	v_mfma_f32_16x16x32_bf16 v[108:111], v[146:149], v[204:207], v[108:111]
	v_mfma_f32_16x16x32_bf16 v[104:107], v[168:171], v[204:207], v[104:107]
	v_mfma_f32_16x16x32_bf16 v[92:95], v[146:149], v[212:215], v[92:95]
	v_mfma_f32_16x16x32_bf16 v[88:91], v[168:171], v[212:215], v[88:91]
	v_mfma_f32_16x16x32_bf16 v[76:79], v[146:149], v[220:223], v[76:79]
	v_mfma_f32_16x16x32_bf16 v[72:75], v[168:171], v[220:223], v[72:75]
	v_mfma_f32_16x16x32_bf16 v[124:127], v[164:167], v[200:203], v[124:127]
	v_mfma_f32_16x16x32_bf16 v[120:123], v[172:175], v[200:203], v[120:123]
	v_mfma_f32_16x16x32_bf16 v[108:111], v[164:167], v[208:211], v[108:111]
	v_mfma_f32_16x16x32_bf16 v[104:107], v[172:175], v[208:211], v[104:107]
	v_mfma_f32_16x16x32_bf16 v[92:95], v[164:167], v[216:219], v[92:95]
	v_mfma_f32_16x16x32_bf16 v[88:91], v[172:175], v[216:219], v[88:91]
	v_mfma_f32_16x16x32_bf16 v[76:79], v[164:167], v[224:227], v[76:79]
	v_mfma_f32_16x16x32_bf16 v[72:75], v[172:175], v[224:227], v[72:75]
	s_setprio 0
	s_setprio 1
	v_mfma_f32_16x16x32_bf16 v[116:119], v[176:179], v[196:199], v[116:119]
	v_mfma_f32_16x16x32_bf16 v[112:115], v[188:191], v[196:199], v[112:115]
	v_mfma_f32_16x16x32_bf16 v[100:103], v[176:179], v[204:207], v[100:103]
	v_mfma_f32_16x16x32_bf16 v[96:99], v[188:191], v[204:207], v[96:99]
	v_mfma_f32_16x16x32_bf16 v[84:87], v[176:179], v[212:215], v[84:87]
	v_mfma_f32_16x16x32_bf16 v[80:83], v[188:191], v[212:215], v[80:83]
	v_mfma_f32_16x16x32_bf16 v[68:71], v[176:179], v[220:223], v[68:71]
	v_mfma_f32_16x16x32_bf16 v[64:67], v[188:191], v[220:223], v[64:67]
	v_mfma_f32_16x16x32_bf16 v[116:119], v[180:183], v[200:203], v[116:119]
	v_mfma_f32_16x16x32_bf16 v[112:115], v[192:195], v[200:203], v[112:115]
	v_mfma_f32_16x16x32_bf16 v[100:103], v[180:183], v[208:211], v[100:103]
	v_mfma_f32_16x16x32_bf16 v[96:99], v[192:195], v[208:211], v[96:99]
	v_mfma_f32_16x16x32_bf16 v[84:87], v[180:183], v[216:219], v[84:87]
	v_mfma_f32_16x16x32_bf16 v[80:83], v[192:195], v[216:219], v[80:83]
	v_mfma_f32_16x16x32_bf16 v[68:71], v[180:183], v[224:227], v[68:71]
	v_mfma_f32_16x16x32_bf16 v[64:67], v[192:195], v[224:227], v[64:67]
	s_setprio 0
	s_barrier
	s_add_i32 s6, s74, s64
	v_lshl_add_u64 v[150:151], s[56:57], 0, v[130:131]
	s_mov_b32 m0, s6
	ds_read_b128 v[196:199], v162 offset:16384
	ds_read_b128 v[200:203], v162 offset:17408
	ds_read_b128 v[204:207], v162 offset:18432
	ds_read_b128 v[208:211], v162 offset:19456
	ds_read_b128 v[212:215], v162 offset:20480
	ds_read_b128 v[216:219], v162 offset:21504
	ds_read_b128 v[220:223], v162 offset:22528
	ds_read_b128 v[224:227], v162 offset:23552
	global_load_lds_dwordx4 v[150:151], off sc0
	s_add_i32 m0, s6, 0x2000
	s_add_u32 s6, s56, 0x80000
	v_lshl_add_u64 v[184:185], s[56:57], 0, v[134:135]
	s_addc_u32 s7, s57, 0
	s_add_i32 s85, s75, s64
	global_load_lds_dwordx4 v[184:185], off sc0
	v_lshl_add_u64 v[228:229], s[6:7], 0, v[130:131]
	s_mov_b32 m0, s85
	v_lshl_add_u64 v[230:231], s[58:59], 0, v[132:133]
	global_load_lds_dwordx4 v[228:229], off sc0
	v_lshl_add_u64 v[228:229], s[6:7], 0, v[134:135]
	s_add_i32 m0, s85, 0x2000
	s_nop 0
	global_load_lds_dwordx4 v[228:229], off sc0
	v_lshl_add_u64 v[228:229], s[58:59], 0, v[128:129]
	s_mov_b32 m0, s53
	s_nop 0
	global_load_lds_dwordx4 v[228:229], off sc0
	s_mov_b32 m0, s65
	s_nop 0
	global_load_lds_dwordx4 v[230:231], off sc0
	s_waitcnt vmcnt(8)
	s_waitcnt lgkmcnt(0)
	s_barrier
; #define PG8_STAGE(bufoff, gbase, voff) do { _Pragma("unroll") for (int _i = 0; _i < 2; ++_i) \
;         __builtin_amdgcn_global_load_lds((const unsigned*)((const char*)(gbase) + (voff)[_i]), (LAS unsigned*)(lds + (bufoff) + ldsw + _i * 8192), 16, 0, 1); } while (0)
; #define PG8_LDA(dst, b, h) do { _Pragma("unroll") for (int m = 0; m < 4; ++m) _Pragma("unroll") for (int k = 0; k < 2; ++k) dst[m][k] = *(const LAS bf16x8*)(lds + PG8_SA(b, h) + aoff + m * 2048 + k * 1024); } while (0)
; #define PG8_LDB(dst, b, h) do { _Pragma("unroll") for (int n = 0; n < 2; ++n) _Pragma("unroll") for (int k = 0; k < 2; ++k) dst[n][k] = *(const LAS bf16x8*)(lds + PG8_SB(b, h) + boff + n * 2048 + k * 1024); } while (0)
; #define PG8_MMA(ai, bj, At, Bt) do { __builtin_amdgcn_s_setprio(1); _Pragma("unroll") for (int m = 0; m < 4; ++m) _Pragma("unroll") for (int n = 0; n < 2; ++n) _Pragma("unroll") for (int k = 0; k < 2; ++k) \
;         acc[ai][bj][m][n] = __builtin_amdgcn_mfma_f32_16x16x32_bf16(Bt[n][k], At[m][k], acc[ai][bj][m][n], 0, 0, 0); __builtin_amdgcn_s_setprio(0); } while (0)
; #define PG8_WAIT_V(n) asm volatile("s_waitcnt vmcnt(" #n ")" ::: "memory")
; #define PG8_WAIT_L(n) asm volatile("s_waitcnt lgkmcnt(" #n ")" ::: "memory")
; #define PG8_BAR __builtin_amdgcn_s_barrier()
; #define PG8_SCHED __builtin_amdgcn_sched_barrier(0)
; template <class Epi, class Sched, bool ALIGN_EPI = false, bool SP2 = false>
; __device__ __forceinline__ void gemm_phase(LAS unsigned char* lds, const Gemm g, const Sched& S, const Epi& E) {
;     ...
;             PG8_WAIT_V(8); PG8_WAIT_L(0); PG8_BAR; PG8_MMA(1, 0, At, B0); PG8_MMA(1, 1, At, B1); PG8_BAR; PG8_SCHED;
;             PG8_LDB(B0, 1, 0); PG8_LDB(B1, 1, 1); PG8_SCHED; PG8_LDA(At, 1, 0); PG8_STAGE(PG8_SA(0, 1), a2 + hstep, voffA);
;             PG8_WAIT_V(8); PG8_WAIT_L(0); PG8_BAR; PG8_MMA(0, 0, At, B0); PG8_MMA(0, 1, At, B1); PG8_BAR; PG8_SCHED;
	s_setprio 1
	s_waitcnt lgkmcnt(0)
	v_mfma_f32_16x16x32_bf16 v[60:63], v[146:149], v[196:199], v[60:63]
	v_mfma_f32_16x16x32_bf16 v[56:59], v[168:171], v[196:199], v[56:59]
	v_mfma_f32_16x16x32_bf16 v[44:47], v[146:149], v[204:207], v[44:47]
	v_mfma_f32_16x16x32_bf16 v[40:43], v[168:171], v[204:207], v[40:43]
	v_mfma_f32_16x16x32_bf16 v[28:31], v[146:149], v[212:215], v[28:31]
	v_mfma_f32_16x16x32_bf16 v[24:27], v[168:171], v[212:215], v[24:27]
	v_mfma_f32_16x16x32_bf16 v[12:15], v[146:149], v[220:223], v[12:15]
	v_mfma_f32_16x16x32_bf16 v[8:11], v[168:171], v[220:223], v[8:11]
	v_mfma_f32_16x16x32_bf16 v[60:63], v[164:167], v[200:203], v[60:63]
	v_mfma_f32_16x16x32_bf16 v[56:59], v[172:175], v[200:203], v[56:59]
	v_mfma_f32_16x16x32_bf16 v[44:47], v[164:167], v[208:211], v[44:47]
	v_mfma_f32_16x16x32_bf16 v[40:43], v[172:175], v[208:211], v[40:43]
	v_mfma_f32_16x16x32_bf16 v[28:31], v[164:167], v[216:219], v[28:31]
	v_mfma_f32_16x16x32_bf16 v[24:27], v[172:175], v[216:219], v[24:27]
	v_mfma_f32_16x16x32_bf16 v[12:15], v[164:167], v[224:227], v[12:15]
	v_mfma_f32_16x16x32_bf16 v[8:11], v[172:175], v[224:227], v[8:11]
	s_setprio 0
	s_setprio 1
	v_mfma_f32_16x16x32_bf16 v[52:55], v[176:179], v[196:199], v[52:55]
	v_mfma_f32_16x16x32_bf16 v[48:51], v[188:191], v[196:199], v[48:51]
	v_mfma_f32_16x16x32_bf16 v[36:39], v[176:179], v[204:207], v[36:39]
	v_mfma_f32_16x16x32_bf16 v[32:35], v[188:191], v[204:207], v[32:35]
	v_mfma_f32_16x16x32_bf16 v[20:23], v[176:179], v[212:215], v[20:23]
	v_mfma_f32_16x16x32_bf16 v[16:19], v[188:191], v[212:215], v[16:19]
	v_mfma_f32_16x16x32_bf16 v[4:7], v[176:179], v[220:223], v[4:7]
	v_mfma_f32_16x16x32_bf16 v[0:3], v[188:191], v[220:223], v[0:3]
	v_mfma_f32_16x16x32_bf16 v[52:55], v[180:183], v[200:203], v[52:55]
	v_mfma_f32_16x16x32_bf16 v[48:51], v[192:195], v[200:203], v[48:51]
	v_mfma_f32_16x16x32_bf16 v[36:39], v[180:183], v[208:211], v[36:39]
	v_mfma_f32_16x16x32_bf16 v[32:35], v[192:195], v[208:211], v[32:35]
	v_mfma_f32_16x16x32_bf16 v[20:23], v[180:183], v[216:219], v[20:23]
	v_mfma_f32_16x16x32_bf16 v[16:19], v[192:195], v[216:219], v[16:19]
	v_mfma_f32_16x16x32_bf16 v[4:7], v[180:183], v[224:227], v[4:7]
	v_mfma_f32_16x16x32_bf16 v[0:3], v[192:195], v[224:227], v[0:3]
	s_setprio 0
	s_barrier
	s_add_i32 s85, 0, 0x18000
	v_add_u32_e32 v136, s85, v155
	s_add_i32 s86, 0, 0x1c000
	ds_read_b128 v[146:149], v136
	ds_read_b128 v[164:167], v136 offset:1024
	ds_read_b128 v[168:171], v136 offset:2048
	ds_read_b128 v[172:175], v136 offset:3072
	v_add_u32_e32 v136, s86, v155
	ds_read_b128 v[176:179], v136
	ds_read_b128 v[180:183], v136 offset:1024
	ds_read_b128 v[188:191], v136 offset:2048
	ds_read_b128 v[192:195], v136 offset:3072
	s_add_u32 s6, s58, 0x80000
	s_addc_u32 s7, s59, 0
	s_mov_b32 m0, s66
	v_lshl_add_u64 v[232:233], s[6:7], 0, v[128:129]
	ds_read_b128 v[196:199], v162 offset:32768
	ds_read_b128 v[200:203], v162 offset:33792
	ds_read_b128 v[204:207], v162 offset:34816
	ds_read_b128 v[208:211], v162 offset:35840
	ds_read_b128 v[212:215], v162 offset:36864
	ds_read_b128 v[216:219], v162 offset:37888
	ds_read_b128 v[220:223], v162 offset:38912
	ds_read_b128 v[224:227], v162 offset:39936
	global_load_lds_dwordx4 v[232:233], off sc0
	v_lshl_add_u64 v[232:233], s[6:7], 0, v[132:133]
	s_mov_b32 m0, s67
	s_nop 0
	global_load_lds_dwordx4 v[232:233], off sc0
	s_waitcnt vmcnt(8)
	s_waitcnt lgkmcnt(0)
	s_barrier
	s_setprio 1
	s_waitcnt lgkmcnt(0)
	v_mfma_f32_16x16x32_bf16 v[124:127], v[146:149], v[196:199], v[124:127]
	v_mfma_f32_16x16x32_bf16 v[120:123], v[168:171], v[196:199], v[120:123]
	v_mfma_f32_16x16x32_bf16 v[108:111], v[146:149], v[204:207], v[108:111]
	v_mfma_f32_16x16x32_bf16 v[104:107], v[168:171], v[204:207], v[104:107]
	v_mfma_f32_16x16x32_bf16 v[92:95], v[146:149], v[212:215], v[92:95]
	v_mfma_f32_16x16x32_bf16 v[88:91], v[168:171], v[212:215], v[88:91]
	v_mfma_f32_16x16x32_bf16 v[76:79], v[146:149], v[220:223], v[76:79]
	v_mfma_f32_16x16x32_bf16 v[72:75], v[168:171], v[220:223], v[72:75]
	v_mfma_f32_16x16x32_bf16 v[124:127], v[164:167], v[200:203], v[124:127]
	v_mfma_f32_16x16x32_bf16 v[120:123], v[172:175], v[200:203], v[120:123]
	v_mfma_f32_16x16x32_bf16 v[108:111], v[164:167], v[208:211], v[108:111]
	v_mfma_f32_16x16x32_bf16 v[104:107], v[172:175], v[208:211], v[104:107]
	v_mfma_f32_16x16x32_bf16 v[92:95], v[164:167], v[216:219], v[92:95]
	v_mfma_f32_16x16x32_bf16 v[88:91], v[172:175], v[216:219], v[88:91]
	v_mfma_f32_16x16x32_bf16 v[76:79], v[164:167], v[224:227], v[76:79]
	v_mfma_f32_16x16x32_bf16 v[72:75], v[172:175], v[224:227], v[72:75]
	s_setprio 0
	s_setprio 1
	v_mfma_f32_16x16x32_bf16 v[116:119], v[176:179], v[196:199], v[116:119]
	v_mfma_f32_16x16x32_bf16 v[112:115], v[188:191], v[196:199], v[112:115]
	v_mfma_f32_16x16x32_bf16 v[100:103], v[176:179], v[204:207], v[100:103]
	v_mfma_f32_16x16x32_bf16 v[96:99], v[188:191], v[204:207], v[96:99]
	v_mfma_f32_16x16x32_bf16 v[84:87], v[176:179], v[212:215], v[84:87]
	v_mfma_f32_16x16x32_bf16 v[80:83], v[188:191], v[212:215], v[80:83]
	v_mfma_f32_16x16x32_bf16 v[68:71], v[176:179], v[220:223], v[68:71]
	v_mfma_f32_16x16x32_bf16 v[64:67], v[188:191], v[220:223], v[64:67]
	v_mfma_f32_16x16x32_bf16 v[116:119], v[180:183], v[200:203], v[116:119]
	v_mfma_f32_16x16x32_bf16 v[112:115], v[192:195], v[200:203], v[112:115]
	v_mfma_f32_16x16x32_bf16 v[100:103], v[180:183], v[208:211], v[100:103]
	v_mfma_f32_16x16x32_bf16 v[96:99], v[192:195], v[208:211], v[96:99]
	v_mfma_f32_16x16x32_bf16 v[84:87], v[180:183], v[216:219], v[84:87]
	v_mfma_f32_16x16x32_bf16 v[80:83], v[192:195], v[216:219], v[80:83]
	v_mfma_f32_16x16x32_bf16 v[68:71], v[180:183], v[224:227], v[68:71]
	v_mfma_f32_16x16x32_bf16 v[64:67], v[192:195], v[224:227], v[64:67]
	s_setprio 0
	s_barrier
; #define PG8_STAGE(bufoff, gbase, voff) do { _Pragma("unroll") for (int _i = 0; _i < 2; ++_i) \
;         __builtin_amdgcn_global_load_lds((const unsigned*)((const char*)(gbase) + (voff)[_i]), (LAS unsigned*)(lds + (bufoff) + ldsw + _i * 8192), 16, 0, 1); } while (0)
; #define PG8_LDA(dst, b, h) do { _Pragma("unroll") for (int m = 0; m < 4; ++m) _Pragma("unroll") for (int k = 0; k < 2; ++k) dst[m][k] = *(const LAS bf16x8*)(lds + PG8_SA(b, h) + aoff + m * 2048 + k * 1024); } while (0)
; #define PG8_MMA(ai, bj, At, Bt) do { __builtin_amdgcn_s_setprio(1); _Pragma("unroll") for (int m = 0; m < 4; ++m) _Pragma("unroll") for (int n = 0; n < 2; ++n) _Pragma("unroll") for (int k = 0; k < 2; ++k) \
;         acc[ai][bj][m][n] = __builtin_amdgcn_mfma_f32_16x16x32_bf16(Bt[n][k], At[m][k], acc[ai][bj][m][n], 0, 0, 0); __builtin_amdgcn_s_setprio(0); } while (0)
; #define PG8_WAIT_V(n) asm volatile("s_waitcnt vmcnt(" #n ")" ::: "memory")
; #define PG8_WAIT_L(n) asm volatile("s_waitcnt lgkmcnt(" #n ")" ::: "memory")
; #define PG8_BAR __builtin_amdgcn_s_barrier()
; #define PG8_SCHED __builtin_amdgcn_sched_barrier(0)
; template <class Epi, class Sched, bool ALIGN_EPI = false, bool SP2 = false>
; __device__ __forceinline__ void gemm_phase(LAS unsigned char* lds, const Gemm g, const Sched& S, const Epi& E) {
;     ...
;         for (int t = 0; t < nt; t += 2) {
;             const bool last = (t == nt - 2);
;             const char* a1 = cA + (size_t)(t + 1) * kstep;
;             const char* a2 = last ? nA : cA + (size_t)(t + 2) * kstep; const char* b2 = last ? nB : cB + (size_t)(t + 2) * kstep;
;     ...
;             PG8_LDA(At, 1, 1); PG8_STAGE(PG8_SB(1, 0), b3, voffB); PG8_STAGE(PG8_SB(1, 1), b3 + hstep, voffB); PG8_STAGE(PG8_SA(1, 0), a3, voffA);
;             PG8_WAIT_V(8); PG8_WAIT_L(0); PG8_BAR; PG8_MMA(1, 0, At, B0); PG8_MMA(1, 1, At, B1); PG8_BAR; PG8_SCHED;
	s_add_i32 s6, s85, s64
	v_lshl_add_u64 v[150:151], v[150:151], 0, s[18:19]
	s_mov_b32 m0, s6
	ds_read_b128 v[196:199], v162 offset:49152
	ds_read_b128 v[200:203], v162 offset:50176
	ds_read_b128 v[204:207], v162 offset:51200
	ds_read_b128 v[208:211], v162 offset:52224
	ds_read_b128 v[212:215], v162 offset:53248
	ds_read_b128 v[216:219], v162 offset:54272
	ds_read_b128 v[220:223], v162 offset:55296
	ds_read_b128 v[224:227], v162 offset:56320
	global_load_lds_dwordx4 v[150:151], off sc0
	s_add_i32 m0, s6, 0x2000
	s_add_u32 s6, s56, 0x80080
	v_lshl_add_u64 v[150:151], v[184:185], 0, s[18:19]
	s_addc_u32 s7, s57, 0
	s_add_i32 s56, s86, s64
	global_load_lds_dwordx4 v[150:151], off sc0
	v_lshl_add_u64 v[150:151], s[6:7], 0, v[130:131]
	s_mov_b32 m0, s56
	s_nop 0
	global_load_lds_dwordx4 v[150:151], off sc0
	v_lshl_add_u64 v[150:151], s[6:7], 0, v[134:135]
	s_add_i32 m0, s56, 0x2000
	s_nop 0
	global_load_lds_dwordx4 v[150:151], off sc0
	v_lshl_add_u64 v[150:151], v[228:229], 0, s[18:19]
	s_mov_b32 m0, s69
	s_nop 0
	global_load_lds_dwordx4 v[150:151], off sc0
	v_lshl_add_u64 v[150:151], v[230:231], 0, s[18:19]
	s_mov_b32 m0, s73
	s_nop 0
	global_load_lds_dwordx4 v[150:151], off sc0
	s_waitcnt vmcnt(8)
	s_waitcnt lgkmcnt(0)
	s_barrier
	s_setprio 1
	s_waitcnt lgkmcnt(0)
	v_mfma_f32_16x16x32_bf16 v[60:63], v[146:149], v[196:199], v[60:63]
	v_mfma_f32_16x16x32_bf16 v[56:59], v[168:171], v[196:199], v[56:59]
	v_mfma_f32_16x16x32_bf16 v[44:47], v[146:149], v[204:207], v[44:47]
	v_mfma_f32_16x16x32_bf16 v[40:43], v[168:171], v[204:207], v[40:43]
	v_mfma_f32_16x16x32_bf16 v[28:31], v[146:149], v[212:215], v[28:31]
	v_mfma_f32_16x16x32_bf16 v[24:27], v[168:171], v[212:215], v[24:27]
	v_mfma_f32_16x16x32_bf16 v[12:15], v[146:149], v[220:223], v[12:15]
	v_mfma_f32_16x16x32_bf16 v[8:11], v[168:171], v[220:223], v[8:11]
	v_mfma_f32_16x16x32_bf16 v[60:63], v[164:167], v[200:203], v[60:63]
	v_mfma_f32_16x16x32_bf16 v[56:59], v[172:175], v[200:203], v[56:59]
	v_mfma_f32_16x16x32_bf16 v[44:47], v[164:167], v[208:211], v[44:47]
	v_mfma_f32_16x16x32_bf16 v[40:43], v[172:175], v[208:211], v[40:43]
	v_mfma_f32_16x16x32_bf16 v[28:31], v[164:167], v[216:219], v[28:31]
	v_mfma_f32_16x16x32_bf16 v[24:27], v[172:175], v[216:219], v[24:27]
	v_mfma_f32_16x16x32_bf16 v[12:15], v[164:167], v[224:227], v[12:15]
	v_mfma_f32_16x16x32_bf16 v[8:11], v[172:175], v[224:227], v[8:11]
	s_setprio 0
	s_setprio 1
	v_mfma_f32_16x16x32_bf16 v[52:55], v[176:179], v[196:199], v[52:55]
	v_mfma_f32_16x16x32_bf16 v[48:51], v[188:191], v[196:199], v[48:51]
	v_mfma_f32_16x16x32_bf16 v[36:39], v[176:179], v[204:207], v[36:39]
	v_mfma_f32_16x16x32_bf16 v[32:35], v[188:191], v[204:207], v[32:35]
	v_mfma_f32_16x16x32_bf16 v[20:23], v[176:179], v[212:215], v[20:23]
	v_mfma_f32_16x16x32_bf16 v[16:19], v[188:191], v[212:215], v[16:19]
	v_mfma_f32_16x16x32_bf16 v[4:7], v[176:179], v[220:223], v[4:7]
	v_mfma_f32_16x16x32_bf16 v[0:3], v[188:191], v[220:223], v[0:3]
	v_mfma_f32_16x16x32_bf16 v[52:55], v[180:183], v[200:203], v[52:55]
	v_mfma_f32_16x16x32_bf16 v[48:51], v[192:195], v[200:203], v[48:51]
	v_mfma_f32_16x16x32_bf16 v[36:39], v[180:183], v[208:211], v[36:39]
	v_mfma_f32_16x16x32_bf16 v[32:35], v[192:195], v[208:211], v[32:35]
	v_mfma_f32_16x16x32_bf16 v[20:23], v[180:183], v[216:219], v[20:23]
	v_mfma_f32_16x16x32_bf16 v[16:19], v[192:195], v[216:219], v[16:19]
	v_mfma_f32_16x16x32_bf16 v[4:7], v[180:183], v[224:227], v[4:7]
	v_mfma_f32_16x16x32_bf16 v[0:3], v[192:195], v[224:227], v[0:3]
	s_setprio 0
	s_add_i32 s43, s43, 2
	s_add_u32 s54, s54, 0x100
	s_addc_u32 s55, s55, 0
	s_add_u32 s84, s84, 0x100
	s_addc_u32 s42, s42, 0
	s_cmp_gt_u32 s43, 29
	s_barrier
	s_cbranch_scc0 .LBB0_516
	s_and_b64 vcc, exec, s[24:25]
	s_cbranch_vccz .LBB0_519
	s_barrier

; #define PG8_STAGE(bufoff, gbase, voff) do { _Pragma("unroll") for (int _i = 0; _i < 2; ++_i) \
;         __builtin_amdgcn_global_load_lds((const unsigned*)((const char*)(gbase) + (voff)[_i]), (LAS unsigned*)(lds + (bufoff) + ldsw + _i * 8192), 16, 0, 1); } while (0)
; #define PG8_LDA(dst, b, h) do { _Pragma("unroll") for (int m = 0; m < 4; ++m) _Pragma("unroll") for (int k = 0; k < 2; ++k) dst[m][k] = *(const LAS bf16x8*)(lds + PG8_SA(b, h) + aoff + m * 2048 + k * 1024); } while (0)
; #define PG8_LDB(dst, b, h) do { _Pragma("unroll") for (int n = 0; n < 2; ++n) _Pragma("unroll") for (int k = 0; k < 2; ++k) dst[n][k] = *(const LAS bf16x8*)(lds + PG8_SB(b, h) + boff + n * 2048 + k * 1024); } while (0)
; #define PG8_MMA(ai, bj, At, Bt) do { __builtin_amdgcn_s_setprio(1); _Pragma("unroll") for (int m = 0; m < 4; ++m) _Pragma("unroll") for (int n = 0; n < 2; ++n) _Pragma("unroll") for (int k = 0; k < 2; ++k) \
;         acc[ai][bj][m][n] = __builtin_amdgcn_mfma_f32_16x16x32_bf16(Bt[n][k], At[m][k], acc[ai][bj][m][n], 0, 0, 0); __builtin_amdgcn_s_setprio(0); } while (0)
; #define PG8_WAIT_V(n) asm volatile("s_waitcnt vmcnt(" #n ")" ::: "memory")
; #define PG8_WAIT_L(n) asm volatile("s_waitcnt lgkmcnt(" #n ")" ::: "memory")
; #define PG8_BAR __builtin_amdgcn_s_barrier()
; template <class Epi, class Sched, bool ALIGN_EPI = false, bool SP2 = false>
; __device__ __forceinline__ void gemm_phase(LAS unsigned char* lds, const Gemm g, const Sched& S, const Epi& E) {
;     ...
;             const bool last = (t == nt - 2);
;             const char* a1 = cA + (size_t)(t + 1) * kstep;
;             const char* a2 = last ? nA : cA + (size_t)(t + 2) * kstep; const char* b2 = last ? nB : cB + (size_t)(t + 2) * kstep;
;             const char* a3 = a2 + kstep; const char* b3 = b2 + kstep;
;             if (last && has_next) S.a_ready(nxt);
;             if constexpr (SP2) {
;             PG8_LDB(B0, 0, 0); PG8_LDB(B1, 0, 1); PG8_SCHED; PG8_LDA(At, 0, 0); PG8_STAGE(PG8_SA(1, 1), a1 + hstep, voffA);
;             PG8_WAIT_V(8); PG8_WAIT_L(0); PG8_BAR; PG8_MMA(0, 0, At, B0); PG8_MMA(0, 1, At, B1); PG8_BAR; PG8_SCHED;
;             PG8_LDA(At, 0, 1); PG8_STAGE(PG8_SB(0, 0), b2, voffB); PG8_STAGE(PG8_SB(0, 1), b2 + hstep, voffB); PG8_STAGE(PG8_SA(0, 0), a2, voffA);
;             PG8_WAIT_V(8); PG8_WAIT_L(0); PG8_BAR; PG8_MMA(1, 0, At, B0); PG8_MMA(1, 1, At, B1); PG8_BAR; PG8_SCHED;
.LBB0_563:
	ds_read_b128 v[128:131], v159
	ds_read_b128 v[132:135], v159 offset:1024
	ds_read_b128 v[136:139], v159 offset:2048
	ds_read_b128 v[166:169], v159 offset:3072
	ds_read_b128 v[174:177], v161
	ds_read_b128 v[178:181], v161 offset:1024
	ds_read_b128 v[182:185], v161 offset:2048
	ds_read_b128 v[188:191], v161 offset:3072
	s_add_u32 s6, s54, 0xfff80080
	s_addc_u32 s7, s55, -1
	s_cmp_eq_u32 s43, 28
	s_cselect_b32 s59, s47, s7
	s_cselect_b32 s58, s81, s6
	s_cselect_b32 s57, s45, s42
	s_cselect_b32 s56, s82, s83
	v_lshl_add_u64 v[170:171], s[54:55], 0, v[148:149]
	s_add_i32 m0, s53, 0xc000
	ds_read_b128 v[192:195], v172
	ds_read_b128 v[196:199], v172 offset:1024
	ds_read_b128 v[200:203], v172 offset:2048
	ds_read_b128 v[204:207], v172 offset:3072
	ds_read_b128 v[208:211], v172 offset:4096
	ds_read_b128 v[212:215], v172 offset:5120
	ds_read_b128 v[216:219], v172 offset:6144
	ds_read_b128 v[220:223], v172 offset:7168
	global_load_lds_dwordx4 v[170:171], off sc0
	v_lshl_add_u64 v[170:171], s[54:55], 0, v[150:151]
	s_add_i32 m0, s53, 0xe000
	s_nop 0
	global_load_lds_dwordx4 v[170:171], off sc0
	s_waitcnt vmcnt(8)
	s_waitcnt lgkmcnt(0)
	s_barrier
	s_setprio 1
	s_waitcnt lgkmcnt(0)
	v_mfma_f32_16x16x32_bf16 v[124:127], v[128:131], v[192:195], v[124:127]
	v_mfma_f32_16x16x32_bf16 v[120:123], v[136:139], v[192:195], v[120:123]
	v_mfma_f32_16x16x32_bf16 v[112:115], v[128:131], v[200:203], v[112:115]
	v_mfma_f32_16x16x32_bf16 v[104:107], v[136:139], v[200:203], v[104:107]
	v_mfma_f32_16x16x32_bf16 v[92:95], v[128:131], v[208:211], v[92:95]
	v_mfma_f32_16x16x32_bf16 v[88:91], v[136:139], v[208:211], v[88:91]
	v_mfma_f32_16x16x32_bf16 v[76:79], v[128:131], v[216:219], v[76:79]
	v_mfma_f32_16x16x32_bf16 v[72:75], v[136:139], v[216:219], v[72:75]
	v_mfma_f32_16x16x32_bf16 v[124:127], v[132:135], v[196:199], v[124:127]
	v_mfma_f32_16x16x32_bf16 v[120:123], v[166:169], v[196:199], v[120:123]
	v_mfma_f32_16x16x32_bf16 v[112:115], v[132:135], v[204:207], v[112:115]
	v_mfma_f32_16x16x32_bf16 v[104:107], v[166:169], v[204:207], v[104:107]
	v_mfma_f32_16x16x32_bf16 v[92:95], v[132:135], v[212:215], v[92:95]
	v_mfma_f32_16x16x32_bf16 v[88:91], v[166:169], v[212:215], v[88:91]
	v_mfma_f32_16x16x32_bf16 v[76:79], v[132:135], v[220:223], v[76:79]
	v_mfma_f32_16x16x32_bf16 v[72:75], v[166:169], v[220:223], v[72:75]
	s_setprio 0
	s_setprio 1
	v_mfma_f32_16x16x32_bf16 v[116:119], v[174:177], v[192:195], v[116:119]
	v_mfma_f32_16x16x32_bf16 v[108:111], v[182:185], v[192:195], v[108:111]
	v_mfma_f32_16x16x32_bf16 v[100:103], v[174:177], v[200:203], v[100:103]
	v_mfma_f32_16x16x32_bf16 v[96:99], v[182:185], v[200:203], v[96:99]
	v_mfma_f32_16x16x32_bf16 v[84:87], v[174:177], v[208:211], v[84:87]
	v_mfma_f32_16x16x32_bf16 v[80:83], v[182:185], v[208:211], v[80:83]
	v_mfma_f32_16x16x32_bf16 v[68:71], v[174:177], v[216:219], v[68:71]
	v_mfma_f32_16x16x32_bf16 v[64:67], v[182:185], v[216:219], v[64:67]
	v_mfma_f32_16x16x32_bf16 v[116:119], v[178:181], v[196:199], v[116:119]
	v_mfma_f32_16x16x32_bf16 v[108:111], v[188:191], v[196:199], v[108:111]
	v_mfma_f32_16x16x32_bf16 v[100:103], v[178:181], v[204:207], v[100:103]
	v_mfma_f32_16x16x32_bf16 v[96:99], v[188:191], v[204:207], v[96:99]
	v_mfma_f32_16x16x32_bf16 v[84:87], v[178:181], v[212:215], v[84:87]
	v_mfma_f32_16x16x32_bf16 v[80:83], v[188:191], v[212:215], v[80:83]
	v_mfma_f32_16x16x32_bf16 v[68:71], v[178:181], v[220:223], v[68:71]
	v_mfma_f32_16x16x32_bf16 v[64:67], v[188:191], v[220:223], v[64:67]
	s_setprio 0
	s_barrier
	s_add_i32 s6, s74, s64
	v_lshl_add_u64 v[170:171], s[56:57], 0, v[142:143]
	s_mov_b32 m0, s6
	ds_read_b128 v[192:195], v172 offset:16384
	ds_read_b128 v[196:199], v172 offset:17408
	ds_read_b128 v[200:203], v172 offset:18432
	ds_read_b128 v[204:207], v172 offset:19456
	ds_read_b128 v[208:211], v172 offset:20480
	ds_read_b128 v[212:215], v172 offset:21504
	ds_read_b128 v[216:219], v172 offset:22528
	ds_read_b128 v[220:223], v172 offset:23552
	global_load_lds_dwordx4 v[170:171], off sc0
	s_add_i32 m0, s6, 0x2000
	s_add_u32 s6, s56, 0x80000
	v_lshl_add_u64 v[224:225], s[56:57], 0, v[146:147]
	s_addc_u32 s7, s57, 0
	s_add_i32 s84, s75, s64
	global_load_lds_dwordx4 v[224:225], off sc0
	v_lshl_add_u64 v[226:227], s[6:7], 0, v[142:143]
	s_mov_b32 m0, s84
	v_lshl_add_u64 v[228:229], s[58:59], 0, v[144:145]
	global_load_lds_dwordx4 v[226:227], off sc0
	v_lshl_add_u64 v[226:227], s[6:7], 0, v[146:147]
	s_add_i32 m0, s84, 0x2000
	s_nop 0
	global_load_lds_dwordx4 v[226:227], off sc0
	v_lshl_add_u64 v[226:227], s[58:59], 0, v[140:141]
	s_mov_b32 m0, s53
	s_nop 0
	global_load_lds_dwordx4 v[226:227], off sc0
	s_mov_b32 m0, s65
	s_nop 0
	global_load_lds_dwordx4 v[228:229], off sc0
	s_waitcnt vmcnt(8)
	s_waitcnt lgkmcnt(0)
	s_barrier
; #define PG8_STAGE(bufoff, gbase, voff) do { _Pragma("unroll") for (int _i = 0; _i < 2; ++_i) \
;         __builtin_amdgcn_global_load_lds((const unsigned*)((const char*)(gbase) + (voff)[_i]), (LAS unsigned*)(lds + (bufoff) + ldsw + _i * 8192), 16, 0, 1); } while (0)
; #define PG8_LDA(dst, b, h) do { _Pragma("unroll") for (int m = 0; m < 4; ++m) _Pragma("unroll") for (int k = 0; k < 2; ++k) dst[m][k] = *(const LAS bf16x8*)(lds + PG8_SA(b, h) + aoff + m * 2048 + k * 1024); } while (0)
; #define PG8_LDB(dst, b, h) do { _Pragma("unroll") for (int n = 0; n < 2; ++n) _Pragma("unroll") for (int k = 0; k < 2; ++k) dst[n][k] = *(const LAS bf16x8*)(lds + PG8_SB(b, h) + boff + n * 2048 + k * 1024); } while (0)
; #define PG8_MMA(ai, bj, At, Bt) do { __builtin_amdgcn_s_setprio(1); _Pragma("unroll") for (int m = 0; m < 4; ++m) _Pragma("unroll") for (int n = 0; n < 2; ++n) _Pragma("unroll") for (int k = 0; k < 2; ++k) \
;         acc[ai][bj][m][n] = __builtin_amdgcn_mfma_f32_16x16x32_bf16(Bt[n][k], At[m][k], acc[ai][bj][m][n], 0, 0, 0); __builtin_amdgcn_s_setprio(0); } while (0)
; #define PG8_WAIT_V(n) asm volatile("s_waitcnt vmcnt(" #n ")" ::: "memory")
; #define PG8_WAIT_L(n) asm volatile("s_waitcnt lgkmcnt(" #n ")" ::: "memory")
; #define PG8_BAR __builtin_amdgcn_s_barrier()
; #define PG8_SCHED __builtin_amdgcn_sched_barrier(0)
; template <class Epi, class Sched, bool ALIGN_EPI = false, bool SP2 = false>
; __device__ __forceinline__ void gemm_phase(LAS unsigned char* lds, const Gemm g, const Sched& S, const Epi& E) {
;     ...
;             PG8_WAIT_V(8); PG8_WAIT_L(0); PG8_BAR; PG8_MMA(1, 0, At, B0); PG8_MMA(1, 1, At, B1); PG8_BAR; PG8_SCHED;
;             PG8_LDB(B0, 1, 0); PG8_LDB(B1, 1, 1); PG8_SCHED; PG8_LDA(At, 1, 0); PG8_STAGE(PG8_SA(0, 1), a2 + hstep, voffA);
;             PG8_WAIT_V(8); PG8_WAIT_L(0); PG8_BAR; PG8_MMA(0, 0, At, B0); PG8_MMA(0, 1, At, B1); PG8_BAR; PG8_SCHED;
	s_setprio 1
	s_waitcnt lgkmcnt(0)
	v_mfma_f32_16x16x32_bf16 v[60:63], v[128:131], v[192:195], v[60:63]
	v_mfma_f32_16x16x32_bf16 v[56:59], v[136:139], v[192:195], v[56:59]
	v_mfma_f32_16x16x32_bf16 v[48:51], v[128:131], v[200:203], v[48:51]
	v_mfma_f32_16x16x32_bf16 v[40:43], v[136:139], v[200:203], v[40:43]
	v_mfma_f32_16x16x32_bf16 v[36:39], v[128:131], v[208:211], v[36:39]
	v_mfma_f32_16x16x32_bf16 v[28:31], v[136:139], v[208:211], v[28:31]
	v_mfma_f32_16x16x32_bf16 v[20:23], v[128:131], v[216:219], v[20:23]
	v_mfma_f32_16x16x32_bf16 v[12:15], v[136:139], v[216:219], v[12:15]
	v_mfma_f32_16x16x32_bf16 v[60:63], v[132:135], v[196:199], v[60:63]
	v_mfma_f32_16x16x32_bf16 v[56:59], v[166:169], v[196:199], v[56:59]
	v_mfma_f32_16x16x32_bf16 v[48:51], v[132:135], v[204:207], v[48:51]
	v_mfma_f32_16x16x32_bf16 v[40:43], v[166:169], v[204:207], v[40:43]
	v_mfma_f32_16x16x32_bf16 v[36:39], v[132:135], v[212:215], v[36:39]
	v_mfma_f32_16x16x32_bf16 v[28:31], v[166:169], v[212:215], v[28:31]
	v_mfma_f32_16x16x32_bf16 v[20:23], v[132:135], v[220:223], v[20:23]
	v_mfma_f32_16x16x32_bf16 v[12:15], v[166:169], v[220:223], v[12:15]
	s_setprio 0
	s_setprio 1
	v_mfma_f32_16x16x32_bf16 v[52:55], v[174:177], v[192:195], v[52:55]
	v_mfma_f32_16x16x32_bf16 v[44:47], v[182:185], v[192:195], v[44:47]
	v_mfma_f32_16x16x32_bf16 v[32:35], v[174:177], v[200:203], v[32:35]
	v_mfma_f32_16x16x32_bf16 v[24:27], v[182:185], v[200:203], v[24:27]
	v_mfma_f32_16x16x32_bf16 v[16:19], v[174:177], v[208:211], v[16:19]
	v_mfma_f32_16x16x32_bf16 v[8:11], v[182:185], v[208:211], v[8:11]
	v_mfma_f32_16x16x32_bf16 v[4:7], v[174:177], v[216:219], v[4:7]
	v_mfma_f32_16x16x32_bf16 v[0:3], v[182:185], v[216:219], v[0:3]
	v_mfma_f32_16x16x32_bf16 v[52:55], v[178:181], v[196:199], v[52:55]
	v_mfma_f32_16x16x32_bf16 v[44:47], v[188:191], v[196:199], v[44:47]
	v_mfma_f32_16x16x32_bf16 v[32:35], v[178:181], v[204:207], v[32:35]
	v_mfma_f32_16x16x32_bf16 v[24:27], v[188:191], v[204:207], v[24:27]
	v_mfma_f32_16x16x32_bf16 v[16:19], v[178:181], v[212:215], v[16:19]
	v_mfma_f32_16x16x32_bf16 v[8:11], v[188:191], v[212:215], v[8:11]
	v_mfma_f32_16x16x32_bf16 v[4:7], v[178:181], v[220:223], v[4:7]
	v_mfma_f32_16x16x32_bf16 v[0:3], v[188:191], v[220:223], v[0:3]
	s_setprio 0
	s_barrier
	s_add_i32 s84, 0, 0x18000
	s_add_i32 s85, 0, 0x1c000
	v_add_u32_e32 v166, s84, v155
	v_add_u32_e32 v173, s85, v155
	ds_read_b128 v[128:131], v166
	ds_read_b128 v[132:135], v166 offset:1024
	ds_read_b128 v[136:139], v166 offset:2048
	ds_read_b128 v[166:169], v166 offset:3072
	ds_read_b128 v[174:177], v173
	ds_read_b128 v[178:181], v173 offset:1024
	ds_read_b128 v[182:185], v173 offset:2048
	ds_read_b128 v[188:191], v173 offset:3072
	s_add_u32 s6, s58, 0x80000
	s_addc_u32 s7, s59, 0
	s_mov_b32 m0, s66
	v_lshl_add_u64 v[230:231], s[6:7], 0, v[140:141]
	ds_read_b128 v[192:195], v172 offset:32768
	ds_read_b128 v[196:199], v172 offset:33792
	ds_read_b128 v[200:203], v172 offset:34816
	ds_read_b128 v[204:207], v172 offset:35840
	ds_read_b128 v[208:211], v172 offset:36864
	ds_read_b128 v[212:215], v172 offset:37888
	ds_read_b128 v[216:219], v172 offset:38912
	ds_read_b128 v[220:223], v172 offset:39936
	global_load_lds_dwordx4 v[230:231], off sc0
	v_lshl_add_u64 v[230:231], s[6:7], 0, v[144:145]
	s_mov_b32 m0, s67
	s_nop 0
	global_load_lds_dwordx4 v[230:231], off sc0
	s_waitcnt vmcnt(8)
	s_waitcnt lgkmcnt(0)
	s_barrier
	s_setprio 1
	s_waitcnt lgkmcnt(0)
	v_mfma_f32_16x16x32_bf16 v[124:127], v[128:131], v[192:195], v[124:127]
	v_mfma_f32_16x16x32_bf16 v[120:123], v[136:139], v[192:195], v[120:123]
	v_mfma_f32_16x16x32_bf16 v[112:115], v[128:131], v[200:203], v[112:115]
	v_mfma_f32_16x16x32_bf16 v[104:107], v[136:139], v[200:203], v[104:107]
	v_mfma_f32_16x16x32_bf16 v[92:95], v[128:131], v[208:211], v[92:95]
	v_mfma_f32_16x16x32_bf16 v[88:91], v[136:139], v[208:211], v[88:91]
	v_mfma_f32_16x16x32_bf16 v[76:79], v[128:131], v[216:219], v[76:79]
	v_mfma_f32_16x16x32_bf16 v[72:75], v[136:139], v[216:219], v[72:75]
	v_mfma_f32_16x16x32_bf16 v[124:127], v[132:135], v[196:199], v[124:127]
	v_mfma_f32_16x16x32_bf16 v[120:123], v[166:169], v[196:199], v[120:123]
	v_mfma_f32_16x16x32_bf16 v[112:115], v[132:135], v[204:207], v[112:115]
	v_mfma_f32_16x16x32_bf16 v[104:107], v[166:169], v[204:207], v[104:107]
	v_mfma_f32_16x16x32_bf16 v[92:95], v[132:135], v[212:215], v[92:95]
	v_mfma_f32_16x16x32_bf16 v[88:91], v[166:169], v[212:215], v[88:91]
	v_mfma_f32_16x16x32_bf16 v[76:79], v[132:135], v[220:223], v[76:79]
	v_mfma_f32_16x16x32_bf16 v[72:75], v[166:169], v[220:223], v[72:75]
	s_setprio 0
	s_setprio 1
	v_mfma_f32_16x16x32_bf16 v[116:119], v[174:177], v[192:195], v[116:119]
	v_mfma_f32_16x16x32_bf16 v[108:111], v[182:185], v[192:195], v[108:111]
	v_mfma_f32_16x16x32_bf16 v[100:103], v[174:177], v[200:203], v[100:103]
	v_mfma_f32_16x16x32_bf16 v[96:99], v[182:185], v[200:203], v[96:99]
	v_mfma_f32_16x16x32_bf16 v[84:87], v[174:177], v[208:211], v[84:87]
	v_mfma_f32_16x16x32_bf16 v[80:83], v[182:185], v[208:211], v[80:83]
	v_mfma_f32_16x16x32_bf16 v[68:71], v[174:177], v[216:219], v[68:71]
	v_mfma_f32_16x16x32_bf16 v[64:67], v[182:185], v[216:219], v[64:67]
	v_mfma_f32_16x16x32_bf16 v[116:119], v[178:181], v[196:199], v[116:119]
	v_mfma_f32_16x16x32_bf16 v[108:111], v[188:191], v[196:199], v[108:111]
	v_mfma_f32_16x16x32_bf16 v[100:103], v[178:181], v[204:207], v[100:103]
	v_mfma_f32_16x16x32_bf16 v[96:99], v[188:191], v[204:207], v[96:99]
	v_mfma_f32_16x16x32_bf16 v[84:87], v[178:181], v[212:215], v[84:87]
	v_mfma_f32_16x16x32_bf16 v[80:83], v[188:191], v[212:215], v[80:83]
	v_mfma_f32_16x16x32_bf16 v[68:71], v[178:181], v[220:223], v[68:71]
	v_mfma_f32_16x16x32_bf16 v[64:67], v[188:191], v[220:223], v[64:67]
	s_setprio 0
	s_barrier
; #define PG8_STAGE(bufoff, gbase, voff) do { _Pragma("unroll") for (int _i = 0; _i < 2; ++_i) \
;         __builtin_amdgcn_global_load_lds((const unsigned*)((const char*)(gbase) + (voff)[_i]), (LAS unsigned*)(lds + (bufoff) + ldsw + _i * 8192), 16, 0, 1); } while (0)
; #define PG8_LDA(dst, b, h) do { _Pragma("unroll") for (int m = 0; m < 4; ++m) _Pragma("unroll") for (int k = 0; k < 2; ++k) dst[m][k] = *(const LAS bf16x8*)(lds + PG8_SA(b, h) + aoff + m * 2048 + k * 1024); } while (0)
; #define PG8_MMA(ai, bj, At, Bt) do { __builtin_amdgcn_s_setprio(1); _Pragma("unroll") for (int m = 0; m < 4; ++m) _Pragma("unroll") for (int n = 0; n < 2; ++n) _Pragma("unroll") for (int k = 0; k < 2; ++k) \
;         acc[ai][bj][m][n] = __builtin_amdgcn_mfma_f32_16x16x32_bf16(Bt[n][k], At[m][k], acc[ai][bj][m][n], 0, 0, 0); __builtin_amdgcn_s_setprio(0); } while (0)
; #define PG8_WAIT_V(n) asm volatile("s_waitcnt vmcnt(" #n ")" ::: "memory")
; #define PG8_WAIT_L(n) asm volatile("s_waitcnt lgkmcnt(" #n ")" ::: "memory")
; #define PG8_BAR __builtin_amdgcn_s_barrier()
; #define PG8_SCHED __builtin_amdgcn_sched_barrier(0)
; template <class Epi, class Sched, bool ALIGN_EPI = false, bool SP2 = false>
; __device__ __forceinline__ void gemm_phase(LAS unsigned char* lds, const Gemm g, const Sched& S, const Epi& E) {
;     ...
;         for (int t = 0; t < nt; t += 2) {
;             const bool last = (t == nt - 2);
;             const char* a1 = cA + (size_t)(t + 1) * kstep;
;             const char* a2 = last ? nA : cA + (size_t)(t + 2) * kstep; const char* b2 = last ? nB : cB + (size_t)(t + 2) * kstep;
;     ...
;             PG8_LDA(At, 1, 1); PG8_STAGE(PG8_SB(1, 0), b3, voffB); PG8_STAGE(PG8_SB(1, 1), b3 + hstep, voffB); PG8_STAGE(PG8_SA(1, 0), a3, voffA);
;             PG8_WAIT_V(8); PG8_WAIT_L(0); PG8_BAR; PG8_MMA(1, 0, At, B0); PG8_MMA(1, 1, At, B1); PG8_BAR; PG8_SCHED;
	s_add_i32 s6, s84, s64
	v_lshl_add_u64 v[170:171], v[170:171], 0, s[24:25]
	s_mov_b32 m0, s6
	ds_read_b128 v[192:195], v172 offset:49152
	ds_read_b128 v[196:199], v172 offset:50176
	ds_read_b128 v[200:203], v172 offset:51200
	ds_read_b128 v[204:207], v172 offset:52224
	ds_read_b128 v[208:211], v172 offset:53248
	ds_read_b128 v[212:215], v172 offset:54272
	ds_read_b128 v[216:219], v172 offset:55296
	ds_read_b128 v[220:223], v172 offset:56320
	global_load_lds_dwordx4 v[170:171], off sc0
	s_add_i32 m0, s6, 0x2000
	s_add_u32 s6, s56, 0x80080
	v_lshl_add_u64 v[170:171], v[224:225], 0, s[24:25]
	s_addc_u32 s7, s57, 0
	s_add_i32 s56, s85, s64
	global_load_lds_dwordx4 v[170:171], off sc0
	v_lshl_add_u64 v[170:171], s[6:7], 0, v[142:143]
	s_mov_b32 m0, s56
	s_nop 0
	global_load_lds_dwordx4 v[170:171], off sc0
	v_lshl_add_u64 v[170:171], s[6:7], 0, v[146:147]
	s_add_i32 m0, s56, 0x2000
	s_nop 0
	global_load_lds_dwordx4 v[170:171], off sc0
	v_lshl_add_u64 v[170:171], v[226:227], 0, s[24:25]
	s_mov_b32 m0, s69
	s_nop 0
	global_load_lds_dwordx4 v[170:171], off sc0
	v_lshl_add_u64 v[170:171], v[228:229], 0, s[24:25]
	s_mov_b32 m0, s73
	s_nop 0
	global_load_lds_dwordx4 v[170:171], off sc0
	s_waitcnt vmcnt(8)
	s_waitcnt lgkmcnt(0)
	s_barrier
	s_setprio 1
	s_waitcnt lgkmcnt(0)
	v_mfma_f32_16x16x32_bf16 v[60:63], v[128:131], v[192:195], v[60:63]
	v_mfma_f32_16x16x32_bf16 v[56:59], v[136:139], v[192:195], v[56:59]
	v_mfma_f32_16x16x32_bf16 v[48:51], v[128:131], v[200:203], v[48:51]
	v_mfma_f32_16x16x32_bf16 v[40:43], v[136:139], v[200:203], v[40:43]
	v_mfma_f32_16x16x32_bf16 v[36:39], v[128:131], v[208:211], v[36:39]
	v_mfma_f32_16x16x32_bf16 v[28:31], v[136:139], v[208:211], v[28:31]
	v_mfma_f32_16x16x32_bf16 v[20:23], v[128:131], v[216:219], v[20:23]
	v_mfma_f32_16x16x32_bf16 v[12:15], v[136:139], v[216:219], v[12:15]
	v_mfma_f32_16x16x32_bf16 v[60:63], v[132:135], v[196:199], v[60:63]
	v_mfma_f32_16x16x32_bf16 v[56:59], v[166:169], v[196:199], v[56:59]
	v_mfma_f32_16x16x32_bf16 v[48:51], v[132:135], v[204:207], v[48:51]
	v_mfma_f32_16x16x32_bf16 v[40:43], v[166:169], v[204:207], v[40:43]
	v_mfma_f32_16x16x32_bf16 v[36:39], v[132:135], v[212:215], v[36:39]
	v_mfma_f32_16x16x32_bf16 v[28:31], v[166:169], v[212:215], v[28:31]
	v_mfma_f32_16x16x32_bf16 v[20:23], v[132:135], v[220:223], v[20:23]
	v_mfma_f32_16x16x32_bf16 v[12:15], v[166:169], v[220:223], v[12:15]
	s_setprio 0
	s_setprio 1
	v_mfma_f32_16x16x32_bf16 v[52:55], v[174:177], v[192:195], v[52:55]
	v_mfma_f32_16x16x32_bf16 v[44:47], v[182:185], v[192:195], v[44:47]
	v_mfma_f32_16x16x32_bf16 v[32:35], v[174:177], v[200:203], v[32:35]
	v_mfma_f32_16x16x32_bf16 v[24:27], v[182:185], v[200:203], v[24:27]
	v_mfma_f32_16x16x32_bf16 v[16:19], v[174:177], v[208:211], v[16:19]
	v_mfma_f32_16x16x32_bf16 v[8:11], v[182:185], v[208:211], v[8:11]
	v_mfma_f32_16x16x32_bf16 v[4:7], v[174:177], v[216:219], v[4:7]
	v_mfma_f32_16x16x32_bf16 v[0:3], v[182:185], v[216:219], v[0:3]
	v_mfma_f32_16x16x32_bf16 v[52:55], v[178:181], v[196:199], v[52:55]
	v_mfma_f32_16x16x32_bf16 v[44:47], v[188:191], v[196:199], v[44:47]
	v_mfma_f32_16x16x32_bf16 v[32:35], v[178:181], v[204:207], v[32:35]
	v_mfma_f32_16x16x32_bf16 v[24:27], v[188:191], v[204:207], v[24:27]
	v_mfma_f32_16x16x32_bf16 v[16:19], v[178:181], v[212:215], v[16:19]
	v_mfma_f32_16x16x32_bf16 v[8:11], v[188:191], v[212:215], v[8:11]
	v_mfma_f32_16x16x32_bf16 v[4:7], v[178:181], v[220:223], v[4:7]
	v_mfma_f32_16x16x32_bf16 v[0:3], v[188:191], v[220:223], v[0:3]
	s_setprio 0
	s_add_i32 s43, s43, 2
	s_add_u32 s54, s54, 0x100
	s_addc_u32 s55, s55, 0
	s_add_u32 s83, s83, 0x100
	s_addc_u32 s42, s42, 0
	s_cmp_gt_u32 s43, 29
	s_barrier
	s_cbranch_scc0 .LBB0_563
	s_and_b64 vcc, exec, s[26:27]
	s_cbranch_vccz .LBB0_566
	s_barrier

; #define PG8_STAGE(bufoff, gbase, voff) do { _Pragma("unroll") for (int _i = 0; _i < 2; ++_i) \
;         __builtin_amdgcn_global_load_lds((const unsigned*)((const char*)(gbase) + (voff)[_i]), (LAS unsigned*)(lds + (bufoff) + ldsw + _i * 8192), 16, 0, 1); } while (0)
; #define PG8_LDA(dst, b, h) do { _Pragma("unroll") for (int m = 0; m < 4; ++m) _Pragma("unroll") for (int k = 0; k < 2; ++k) dst[m][k] = *(const LAS bf16x8*)(lds + PG8_SA(b, h) + aoff + m * 2048 + k * 1024); } while (0)
; #define PG8_LDB(dst, b, h) do { _Pragma("unroll") for (int n = 0; n < 2; ++n) _Pragma("unroll") for (int k = 0; k < 2; ++k) dst[n][k] = *(const LAS bf16x8*)(lds + PG8_SB(b, h) + boff + n * 2048 + k * 1024); } while (0)
; #define PG8_MMA(ai, bj, At, Bt) do { __builtin_amdgcn_s_setprio(1); _Pragma("unroll") for (int m = 0; m < 4; ++m) _Pragma("unroll") for (int n = 0; n < 2; ++n) _Pragma("unroll") for (int k = 0; k < 2; ++k) \
;         acc[ai][bj][m][n] = __builtin_amdgcn_mfma_f32_16x16x32_bf16(Bt[n][k], At[m][k], acc[ai][bj][m][n], 0, 0, 0); __builtin_amdgcn_s_setprio(0); } while (0)
; #define PG8_WAIT_V(n) asm volatile("s_waitcnt vmcnt(" #n ")" ::: "memory")
; #define PG8_WAIT_L(n) asm volatile("s_waitcnt lgkmcnt(" #n ")" ::: "memory")
; template <class Epi, class Sched, bool ALIGN_EPI = false, bool SP2 = false>
; __device__ __forceinline__ void gemm_phase(LAS unsigned char* lds, const Gemm g, const Sched& S, const Epi& E) {
;     ...
;         for (int t = 0; t < nt; t += 2) {
;             const bool last = (t == nt - 2);
;             const char* a1 = cA + (size_t)(t + 1) * kstep;
;             const char* a2 = last ? nA : cA + (size_t)(t + 2) * kstep; const char* b2 = last ? nB : cB + (size_t)(t + 2) * kstep;
;             const char* a3 = a2 + kstep; const char* b3 = b2 + kstep;
;             if (last && has_next) S.a_ready(nxt);
;             if constexpr (SP2) {
;             PG8_LDB(B0, 0, 0); PG8_LDB(B1, 0, 1); PG8_SCHED; PG8_LDA(At, 0, 0); PG8_STAGE(PG8_SA(1, 1), a1 + hstep, voffA);
;             PG8_WAIT_V(8); PG8_WAIT_L(0); PG8_BAR; PG8_MMA(0, 0, At, B0); PG8_MMA(0, 1, At, B1); PG8_BAR; PG8_SCHED;
;             PG8_LDA(At, 0, 1); PG8_STAGE(PG8_SB(0, 0), b2, voffB); PG8_STAGE(PG8_SB(0, 1), b2 + hstep, voffB); PG8_STAGE(PG8_SA(0, 0), a2, voffA);
;             PG8_WAIT_V(8); PG8_WAIT_L(0); PG8_BAR; PG8_MMA(1, 0, At, B0); PG8_MMA(1, 1, At, B1); PG8_BAR; PG8_SCHED;
.LBB0_587:
	ds_read_b128 v[144:147], v155
	ds_read_b128 v[162:165], v155 offset:1024
	ds_read_b128 v[166:169], v155 offset:2048
	ds_read_b128 v[170:173], v155 offset:3072
	ds_read_b128 v[174:177], v157
	ds_read_b128 v[178:181], v157 offset:1024
	ds_read_b128 v[182:185], v157 offset:2048
	ds_read_b128 v[188:191], v157 offset:3072
	s_add_u32 s6, s56, 0xfffc0080
	s_addc_u32 s7, s57, -1
	s_cmp_eq_u32 s43, 12
	s_cselect_b32 s61, s49, s7
	s_cselect_b32 s60, s79, s6
	s_cselect_b32 s59, s47, s42
	s_cselect_b32 s58, s80, s81
	v_lshl_add_u64 v[148:149], s[56:57], 0, v[136:137]
	s_add_i32 m0, s55, 0xc000
	ds_read_b128 v[192:195], v159
	ds_read_b128 v[196:199], v159 offset:1024
	ds_read_b128 v[200:203], v159 offset:2048
	ds_read_b128 v[204:207], v159 offset:3072
	ds_read_b128 v[208:211], v159 offset:4096
	ds_read_b128 v[212:215], v159 offset:5120
	ds_read_b128 v[216:219], v159 offset:6144
	ds_read_b128 v[220:223], v159 offset:7168
	global_load_lds_dwordx4 v[148:149], off sc0
	v_lshl_add_u64 v[148:149], s[56:57], 0, v[138:139]
	s_add_i32 m0, s55, 0xe000
	s_nop 0
	global_load_lds_dwordx4 v[148:149], off sc0
	s_waitcnt vmcnt(8)
	s_waitcnt lgkmcnt(0)
	s_barrier
	s_setprio 1
	s_waitcnt lgkmcnt(0)
	v_mfma_f32_16x16x32_bf16 v[124:127], v[144:147], v[192:195], v[124:127]
	v_mfma_f32_16x16x32_bf16 v[120:123], v[166:169], v[192:195], v[120:123]
	v_mfma_f32_16x16x32_bf16 v[108:111], v[144:147], v[200:203], v[108:111]
	v_mfma_f32_16x16x32_bf16 v[104:107], v[166:169], v[200:203], v[104:107]
	v_mfma_f32_16x16x32_bf16 v[92:95], v[144:147], v[208:211], v[92:95]
	v_mfma_f32_16x16x32_bf16 v[88:91], v[166:169], v[208:211], v[88:91]
	v_mfma_f32_16x16x32_bf16 v[76:79], v[144:147], v[216:219], v[76:79]
	v_mfma_f32_16x16x32_bf16 v[72:75], v[166:169], v[216:219], v[72:75]
	v_mfma_f32_16x16x32_bf16 v[124:127], v[162:165], v[196:199], v[124:127]
	v_mfma_f32_16x16x32_bf16 v[120:123], v[170:173], v[196:199], v[120:123]
	v_mfma_f32_16x16x32_bf16 v[108:111], v[162:165], v[204:207], v[108:111]
	v_mfma_f32_16x16x32_bf16 v[104:107], v[170:173], v[204:207], v[104:107]
	v_mfma_f32_16x16x32_bf16 v[92:95], v[162:165], v[212:215], v[92:95]
	v_mfma_f32_16x16x32_bf16 v[88:91], v[170:173], v[212:215], v[88:91]
	v_mfma_f32_16x16x32_bf16 v[76:79], v[162:165], v[220:223], v[76:79]
	v_mfma_f32_16x16x32_bf16 v[72:75], v[170:173], v[220:223], v[72:75]
	s_setprio 0
	s_setprio 1
	v_mfma_f32_16x16x32_bf16 v[116:119], v[174:177], v[192:195], v[116:119]
	v_mfma_f32_16x16x32_bf16 v[112:115], v[182:185], v[192:195], v[112:115]
	v_mfma_f32_16x16x32_bf16 v[100:103], v[174:177], v[200:203], v[100:103]
	v_mfma_f32_16x16x32_bf16 v[96:99], v[182:185], v[200:203], v[96:99]
	v_mfma_f32_16x16x32_bf16 v[84:87], v[174:177], v[208:211], v[84:87]
	v_mfma_f32_16x16x32_bf16 v[80:83], v[182:185], v[208:211], v[80:83]
	v_mfma_f32_16x16x32_bf16 v[68:71], v[174:177], v[216:219], v[68:71]
	v_mfma_f32_16x16x32_bf16 v[64:67], v[182:185], v[216:219], v[64:67]
	v_mfma_f32_16x16x32_bf16 v[116:119], v[178:181], v[196:199], v[116:119]
	v_mfma_f32_16x16x32_bf16 v[112:115], v[188:191], v[196:199], v[112:115]
	v_mfma_f32_16x16x32_bf16 v[100:103], v[178:181], v[204:207], v[100:103]
	v_mfma_f32_16x16x32_bf16 v[96:99], v[188:191], v[204:207], v[96:99]
	v_mfma_f32_16x16x32_bf16 v[84:87], v[178:181], v[212:215], v[84:87]
	v_mfma_f32_16x16x32_bf16 v[80:83], v[188:191], v[212:215], v[80:83]
	v_mfma_f32_16x16x32_bf16 v[68:71], v[178:181], v[220:223], v[68:71]
	v_mfma_f32_16x16x32_bf16 v[64:67], v[188:191], v[220:223], v[64:67]
	s_setprio 0
	s_barrier
	s_add_i32 s6, s76, s66
	v_lshl_add_u64 v[148:149], s[58:59], 0, v[130:131]
	s_mov_b32 m0, s6
	ds_read_b128 v[192:195], v159 offset:16384
	ds_read_b128 v[196:199], v159 offset:17408
	ds_read_b128 v[200:203], v159 offset:18432
	ds_read_b128 v[204:207], v159 offset:19456
	ds_read_b128 v[208:211], v159 offset:20480
	ds_read_b128 v[212:215], v159 offset:21504
	ds_read_b128 v[216:219], v159 offset:22528
	ds_read_b128 v[220:223], v159 offset:23552
	global_load_lds_dwordx4 v[148:149], off sc0
	s_add_i32 m0, s6, 0x2000
	s_add_u32 s6, s58, 0x40000
	v_lshl_add_u64 v[224:225], s[58:59], 0, v[134:135]
	s_addc_u32 s7, s59, 0
	s_add_i32 s82, s77, s66
	global_load_lds_dwordx4 v[224:225], off sc0
	v_lshl_add_u64 v[226:227], s[6:7], 0, v[130:131]
	s_mov_b32 m0, s82
	v_lshl_add_u64 v[228:229], s[60:61], 0, v[132:133]
	global_load_lds_dwordx4 v[226:227], off sc0
	v_lshl_add_u64 v[226:227], s[6:7], 0, v[134:135]
	s_add_i32 m0, s82, 0x2000
	s_nop 0
	global_load_lds_dwordx4 v[226:227], off sc0
	v_lshl_add_u64 v[226:227], s[60:61], 0, v[128:129]
	s_mov_b32 m0, s55
	s_nop 0
	global_load_lds_dwordx4 v[226:227], off sc0
	s_mov_b32 m0, s67
	s_nop 0
	global_load_lds_dwordx4 v[228:229], off sc0
	s_waitcnt vmcnt(8)
	s_waitcnt lgkmcnt(0)
	s_barrier
; #define PG8_STAGE(bufoff, gbase, voff) do { _Pragma("unroll") for (int _i = 0; _i < 2; ++_i) \
;         __builtin_amdgcn_global_load_lds((const unsigned*)((const char*)(gbase) + (voff)[_i]), (LAS unsigned*)(lds + (bufoff) + ldsw + _i * 8192), 16, 0, 1); } while (0)
; #define PG8_LDA(dst, b, h) do { _Pragma("unroll") for (int m = 0; m < 4; ++m) _Pragma("unroll") for (int k = 0; k < 2; ++k) dst[m][k] = *(const LAS bf16x8*)(lds + PG8_SA(b, h) + aoff + m * 2048 + k * 1024); } while (0)
; #define PG8_LDB(dst, b, h) do { _Pragma("unroll") for (int n = 0; n < 2; ++n) _Pragma("unroll") for (int k = 0; k < 2; ++k) dst[n][k] = *(const LAS bf16x8*)(lds + PG8_SB(b, h) + boff + n * 2048 + k * 1024); } while (0)
; #define PG8_MMA(ai, bj, At, Bt) do { __builtin_amdgcn_s_setprio(1); _Pragma("unroll") for (int m = 0; m < 4; ++m) _Pragma("unroll") for (int n = 0; n < 2; ++n) _Pragma("unroll") for (int k = 0; k < 2; ++k) \
;         acc[ai][bj][m][n] = __builtin_amdgcn_mfma_f32_16x16x32_bf16(Bt[n][k], At[m][k], acc[ai][bj][m][n], 0, 0, 0); __builtin_amdgcn_s_setprio(0); } while (0)
; #define PG8_WAIT_V(n) asm volatile("s_waitcnt vmcnt(" #n ")" ::: "memory")
; #define PG8_WAIT_L(n) asm volatile("s_waitcnt lgkmcnt(" #n ")" ::: "memory")
; #define PG8_BAR __builtin_amdgcn_s_barrier()
; #define PG8_SCHED __builtin_amdgcn_sched_barrier(0)
; template <class Epi, class Sched, bool ALIGN_EPI = false, bool SP2 = false>
; __device__ __forceinline__ void gemm_phase(LAS unsigned char* lds, const Gemm g, const Sched& S, const Epi& E) {
;     ...
;             PG8_WAIT_V(8); PG8_WAIT_L(0); PG8_BAR; PG8_MMA(1, 0, At, B0); PG8_MMA(1, 1, At, B1); PG8_BAR; PG8_SCHED;
;             PG8_LDB(B0, 1, 0); PG8_LDB(B1, 1, 1); PG8_SCHED; PG8_LDA(At, 1, 0); PG8_STAGE(PG8_SA(0, 1), a2 + hstep, voffA);
;             PG8_WAIT_V(8); PG8_WAIT_L(0); PG8_BAR; PG8_MMA(0, 0, At, B0); PG8_MMA(0, 1, At, B1); PG8_BAR; PG8_SCHED;
	s_setprio 1
	s_waitcnt lgkmcnt(0)
	v_mfma_f32_16x16x32_bf16 v[60:63], v[144:147], v[192:195], v[60:63]
	v_mfma_f32_16x16x32_bf16 v[56:59], v[166:169], v[192:195], v[56:59]
	v_mfma_f32_16x16x32_bf16 v[44:47], v[144:147], v[200:203], v[44:47]
	v_mfma_f32_16x16x32_bf16 v[40:43], v[166:169], v[200:203], v[40:43]
	v_mfma_f32_16x16x32_bf16 v[28:31], v[144:147], v[208:211], v[28:31]
	v_mfma_f32_16x16x32_bf16 v[24:27], v[166:169], v[208:211], v[24:27]
	v_mfma_f32_16x16x32_bf16 v[12:15], v[144:147], v[216:219], v[12:15]
	v_mfma_f32_16x16x32_bf16 v[8:11], v[166:169], v[216:219], v[8:11]
	v_mfma_f32_16x16x32_bf16 v[60:63], v[162:165], v[196:199], v[60:63]
	v_mfma_f32_16x16x32_bf16 v[56:59], v[170:173], v[196:199], v[56:59]
	v_mfma_f32_16x16x32_bf16 v[44:47], v[162:165], v[204:207], v[44:47]
	v_mfma_f32_16x16x32_bf16 v[40:43], v[170:173], v[204:207], v[40:43]
	v_mfma_f32_16x16x32_bf16 v[28:31], v[162:165], v[212:215], v[28:31]
	v_mfma_f32_16x16x32_bf16 v[24:27], v[170:173], v[212:215], v[24:27]
	v_mfma_f32_16x16x32_bf16 v[12:15], v[162:165], v[220:223], v[12:15]
	v_mfma_f32_16x16x32_bf16 v[8:11], v[170:173], v[220:223], v[8:11]
	s_setprio 0
	s_setprio 1
	v_mfma_f32_16x16x32_bf16 v[52:55], v[174:177], v[192:195], v[52:55]
	v_mfma_f32_16x16x32_bf16 v[48:51], v[182:185], v[192:195], v[48:51]
	v_mfma_f32_16x16x32_bf16 v[36:39], v[174:177], v[200:203], v[36:39]
	v_mfma_f32_16x16x32_bf16 v[32:35], v[182:185], v[200:203], v[32:35]
	v_mfma_f32_16x16x32_bf16 v[20:23], v[174:177], v[208:211], v[20:23]
	v_mfma_f32_16x16x32_bf16 v[16:19], v[182:185], v[208:211], v[16:19]
	v_mfma_f32_16x16x32_bf16 v[4:7], v[174:177], v[216:219], v[4:7]
	v_mfma_f32_16x16x32_bf16 v[0:3], v[182:185], v[216:219], v[0:3]
	v_mfma_f32_16x16x32_bf16 v[52:55], v[178:181], v[196:199], v[52:55]
	v_mfma_f32_16x16x32_bf16 v[48:51], v[188:191], v[196:199], v[48:51]
	v_mfma_f32_16x16x32_bf16 v[36:39], v[178:181], v[204:207], v[36:39]
	v_mfma_f32_16x16x32_bf16 v[32:35], v[188:191], v[204:207], v[32:35]
	v_mfma_f32_16x16x32_bf16 v[20:23], v[178:181], v[212:215], v[20:23]
	v_mfma_f32_16x16x32_bf16 v[16:19], v[188:191], v[212:215], v[16:19]
	v_mfma_f32_16x16x32_bf16 v[4:7], v[178:181], v[220:223], v[4:7]
	v_mfma_f32_16x16x32_bf16 v[0:3], v[188:191], v[220:223], v[0:3]
	s_setprio 0
	s_barrier
	s_add_i32 s82, 0, 0x18000
	v_add_u32_e32 v161, s82, v151
	s_add_i32 s83, 0, 0x1c000
	ds_read_b128 v[144:147], v161
	ds_read_b128 v[162:165], v161 offset:1024
	ds_read_b128 v[166:169], v161 offset:2048
	ds_read_b128 v[170:173], v161 offset:3072
	v_add_u32_e32 v161, s83, v151
	ds_read_b128 v[174:177], v161
	ds_read_b128 v[178:181], v161 offset:1024
	ds_read_b128 v[182:185], v161 offset:2048
	ds_read_b128 v[188:191], v161 offset:3072
	s_add_u32 s6, s60, 0x40000
	s_addc_u32 s7, s61, 0
	s_mov_b32 m0, s68
	v_lshl_add_u64 v[230:231], s[6:7], 0, v[128:129]
	ds_read_b128 v[192:195], v159 offset:32768
	ds_read_b128 v[196:199], v159 offset:33792
	ds_read_b128 v[200:203], v159 offset:34816
	ds_read_b128 v[204:207], v159 offset:35840
	ds_read_b128 v[208:211], v159 offset:36864
	ds_read_b128 v[212:215], v159 offset:37888
	ds_read_b128 v[216:219], v159 offset:38912
	ds_read_b128 v[220:223], v159 offset:39936
	global_load_lds_dwordx4 v[230:231], off sc0
	v_lshl_add_u64 v[230:231], s[6:7], 0, v[132:133]
	s_mov_b32 m0, s69
	s_nop 0
	global_load_lds_dwordx4 v[230:231], off sc0
	s_waitcnt vmcnt(8)
	s_waitcnt lgkmcnt(0)
	s_barrier
	s_setprio 1
	s_waitcnt lgkmcnt(0)
	v_mfma_f32_16x16x32_bf16 v[124:127], v[144:147], v[192:195], v[124:127]
	v_mfma_f32_16x16x32_bf16 v[120:123], v[166:169], v[192:195], v[120:123]
	v_mfma_f32_16x16x32_bf16 v[108:111], v[144:147], v[200:203], v[108:111]
	v_mfma_f32_16x16x32_bf16 v[104:107], v[166:169], v[200:203], v[104:107]
	v_mfma_f32_16x16x32_bf16 v[92:95], v[144:147], v[208:211], v[92:95]
	v_mfma_f32_16x16x32_bf16 v[88:91], v[166:169], v[208:211], v[88:91]
	v_mfma_f32_16x16x32_bf16 v[76:79], v[144:147], v[216:219], v[76:79]
	v_mfma_f32_16x16x32_bf16 v[72:75], v[166:169], v[216:219], v[72:75]
	v_mfma_f32_16x16x32_bf16 v[124:127], v[162:165], v[196:199], v[124:127]
	v_mfma_f32_16x16x32_bf16 v[120:123], v[170:173], v[196:199], v[120:123]
	v_mfma_f32_16x16x32_bf16 v[108:111], v[162:165], v[204:207], v[108:111]
	v_mfma_f32_16x16x32_bf16 v[104:107], v[170:173], v[204:207], v[104:107]
	v_mfma_f32_16x16x32_bf16 v[92:95], v[162:165], v[212:215], v[92:95]
	v_mfma_f32_16x16x32_bf16 v[88:91], v[170:173], v[212:215], v[88:91]
	v_mfma_f32_16x16x32_bf16 v[76:79], v[162:165], v[220:223], v[76:79]
	v_mfma_f32_16x16x32_bf16 v[72:75], v[170:173], v[220:223], v[72:75]
	s_setprio 0
	s_setprio 1
	v_mfma_f32_16x16x32_bf16 v[116:119], v[174:177], v[192:195], v[116:119]
	v_mfma_f32_16x16x32_bf16 v[112:115], v[182:185], v[192:195], v[112:115]
	v_mfma_f32_16x16x32_bf16 v[100:103], v[174:177], v[200:203], v[100:103]
	v_mfma_f32_16x16x32_bf16 v[96:99], v[182:185], v[200:203], v[96:99]
	v_mfma_f32_16x16x32_bf16 v[84:87], v[174:177], v[208:211], v[84:87]
	v_mfma_f32_16x16x32_bf16 v[80:83], v[182:185], v[208:211], v[80:83]
	v_mfma_f32_16x16x32_bf16 v[68:71], v[174:177], v[216:219], v[68:71]
	v_mfma_f32_16x16x32_bf16 v[64:67], v[182:185], v[216:219], v[64:67]
	v_mfma_f32_16x16x32_bf16 v[116:119], v[178:181], v[196:199], v[116:119]
	v_mfma_f32_16x16x32_bf16 v[112:115], v[188:191], v[196:199], v[112:115]
	v_mfma_f32_16x16x32_bf16 v[100:103], v[178:181], v[204:207], v[100:103]
	v_mfma_f32_16x16x32_bf16 v[96:99], v[188:191], v[204:207], v[96:99]
	v_mfma_f32_16x16x32_bf16 v[84:87], v[178:181], v[212:215], v[84:87]
	v_mfma_f32_16x16x32_bf16 v[80:83], v[188:191], v[212:215], v[80:83]
	v_mfma_f32_16x16x32_bf16 v[68:71], v[178:181], v[220:223], v[68:71]
	v_mfma_f32_16x16x32_bf16 v[64:67], v[188:191], v[220:223], v[64:67]
	s_setprio 0
	s_barrier
; #define PG8_STAGE(bufoff, gbase, voff) do { _Pragma("unroll") for (int _i = 0; _i < 2; ++_i) \
;         __builtin_amdgcn_global_load_lds((const unsigned*)((const char*)(gbase) + (voff)[_i]), (LAS unsigned*)(lds + (bufoff) + ldsw + _i * 8192), 16, 0, 1); } while (0)
; #define PG8_LDA(dst, b, h) do { _Pragma("unroll") for (int m = 0; m < 4; ++m) _Pragma("unroll") for (int k = 0; k < 2; ++k) dst[m][k] = *(const LAS bf16x8*)(lds + PG8_SA(b, h) + aoff + m * 2048 + k * 1024); } while (0)
; #define PG8_MMA(ai, bj, At, Bt) do { __builtin_amdgcn_s_setprio(1); _Pragma("unroll") for (int m = 0; m < 4; ++m) _Pragma("unroll") for (int n = 0; n < 2; ++n) _Pragma("unroll") for (int k = 0; k < 2; ++k) \
;         acc[ai][bj][m][n] = __builtin_amdgcn_mfma_f32_16x16x32_bf16(Bt[n][k], At[m][k], acc[ai][bj][m][n], 0, 0, 0); __builtin_amdgcn_s_setprio(0); } while (0)
; #define PG8_WAIT_V(n) asm volatile("s_waitcnt vmcnt(" #n ")" ::: "memory")
; #define PG8_WAIT_L(n) asm volatile("s_waitcnt lgkmcnt(" #n ")" ::: "memory")
; #define PG8_BAR __builtin_amdgcn_s_barrier()
; #define PG8_SCHED __builtin_amdgcn_sched_barrier(0)
; template <class Epi, class Sched, bool ALIGN_EPI = false, bool SP2 = false>
; __device__ __forceinline__ void gemm_phase(LAS unsigned char* lds, const Gemm g, const Sched& S, const Epi& E) {
;     ...
;         for (int t = 0; t < nt; t += 2) {
;     ...
;             PG8_LDA(At, 1, 1); PG8_STAGE(PG8_SB(1, 0), b3, voffB); PG8_STAGE(PG8_SB(1, 1), b3 + hstep, voffB); PG8_STAGE(PG8_SA(1, 0), a3, voffA);
;             PG8_WAIT_V(8); PG8_WAIT_L(0); PG8_BAR; PG8_MMA(1, 0, At, B0); PG8_MMA(1, 1, At, B1); PG8_BAR; PG8_SCHED;
	s_add_i32 s6, s82, s66
	v_lshl_add_u64 v[148:149], v[148:149], 0, s[24:25]
	s_mov_b32 m0, s6
	ds_read_b128 v[192:195], v159 offset:49152
	ds_read_b128 v[196:199], v159 offset:50176
	ds_read_b128 v[200:203], v159 offset:51200
	ds_read_b128 v[204:207], v159 offset:52224
	ds_read_b128 v[208:211], v159 offset:53248
	ds_read_b128 v[212:215], v159 offset:54272
	ds_read_b128 v[216:219], v159 offset:55296
	ds_read_b128 v[220:223], v159 offset:56320
	global_load_lds_dwordx4 v[148:149], off sc0
	s_add_i32 m0, s6, 0x2000
	s_add_u32 s6, s58, 0x40080
	v_lshl_add_u64 v[148:149], v[224:225], 0, s[24:25]
	s_addc_u32 s7, s59, 0
	s_add_i32 s58, s83, s66
	global_load_lds_dwordx4 v[148:149], off sc0
	v_lshl_add_u64 v[148:149], s[6:7], 0, v[130:131]
	s_mov_b32 m0, s58
	s_nop 0
	global_load_lds_dwordx4 v[148:149], off sc0
	v_lshl_add_u64 v[148:149], s[6:7], 0, v[134:135]
	s_add_i32 m0, s58, 0x2000
	s_nop 0
	global_load_lds_dwordx4 v[148:149], off sc0
	v_lshl_add_u64 v[148:149], v[226:227], 0, s[24:25]
	s_mov_b32 m0, s74
	s_nop 0
	global_load_lds_dwordx4 v[148:149], off sc0
	v_lshl_add_u64 v[148:149], v[228:229], 0, s[24:25]
	s_mov_b32 m0, s75
	s_nop 0
	global_load_lds_dwordx4 v[148:149], off sc0
	s_waitcnt vmcnt(8)
	s_waitcnt lgkmcnt(0)
	s_barrier
	s_setprio 1
	s_waitcnt lgkmcnt(0)
	v_mfma_f32_16x16x32_bf16 v[60:63], v[144:147], v[192:195], v[60:63]
	v_mfma_f32_16x16x32_bf16 v[56:59], v[166:169], v[192:195], v[56:59]
	v_mfma_f32_16x16x32_bf16 v[44:47], v[144:147], v[200:203], v[44:47]
	v_mfma_f32_16x16x32_bf16 v[40:43], v[166:169], v[200:203], v[40:43]
	v_mfma_f32_16x16x32_bf16 v[28:31], v[144:147], v[208:211], v[28:31]
	v_mfma_f32_16x16x32_bf16 v[24:27], v[166:169], v[208:211], v[24:27]
	v_mfma_f32_16x16x32_bf16 v[12:15], v[144:147], v[216:219], v[12:15]
	v_mfma_f32_16x16x32_bf16 v[8:11], v[166:169], v[216:219], v[8:11]
	v_mfma_f32_16x16x32_bf16 v[60:63], v[162:165], v[196:199], v[60:63]
	v_mfma_f32_16x16x32_bf16 v[56:59], v[170:173], v[196:199], v[56:59]
	v_mfma_f32_16x16x32_bf16 v[44:47], v[162:165], v[204:207], v[44:47]
	v_mfma_f32_16x16x32_bf16 v[40:43], v[170:173], v[204:207], v[40:43]
	v_mfma_f32_16x16x32_bf16 v[28:31], v[162:165], v[212:215], v[28:31]
	v_mfma_f32_16x16x32_bf16 v[24:27], v[170:173], v[212:215], v[24:27]
	v_mfma_f32_16x16x32_bf16 v[12:15], v[162:165], v[220:223], v[12:15]
	v_mfma_f32_16x16x32_bf16 v[8:11], v[170:173], v[220:223], v[8:11]
	s_setprio 0
	s_setprio 1
	v_mfma_f32_16x16x32_bf16 v[52:55], v[174:177], v[192:195], v[52:55]
	v_mfma_f32_16x16x32_bf16 v[48:51], v[182:185], v[192:195], v[48:51]
	v_mfma_f32_16x16x32_bf16 v[36:39], v[174:177], v[200:203], v[36:39]
	v_mfma_f32_16x16x32_bf16 v[32:35], v[182:185], v[200:203], v[32:35]
	v_mfma_f32_16x16x32_bf16 v[20:23], v[174:177], v[208:211], v[20:23]
	v_mfma_f32_16x16x32_bf16 v[16:19], v[182:185], v[208:211], v[16:19]
	v_mfma_f32_16x16x32_bf16 v[4:7], v[174:177], v[216:219], v[4:7]
	v_mfma_f32_16x16x32_bf16 v[0:3], v[182:185], v[216:219], v[0:3]
	v_mfma_f32_16x16x32_bf16 v[52:55], v[178:181], v[196:199], v[52:55]
	v_mfma_f32_16x16x32_bf16 v[48:51], v[188:191], v[196:199], v[48:51]
	v_mfma_f32_16x16x32_bf16 v[36:39], v[178:181], v[204:207], v[36:39]
	v_mfma_f32_16x16x32_bf16 v[32:35], v[188:191], v[204:207], v[32:35]
	v_mfma_f32_16x16x32_bf16 v[20:23], v[178:181], v[212:215], v[20:23]
	v_mfma_f32_16x16x32_bf16 v[16:19], v[188:191], v[212:215], v[16:19]
	v_mfma_f32_16x16x32_bf16 v[4:7], v[178:181], v[220:223], v[4:7]
	v_mfma_f32_16x16x32_bf16 v[0:3], v[188:191], v[220:223], v[0:3]
	s_setprio 0
	s_add_i32 s43, s43, 2
	s_add_u32 s56, s56, 0x100
	s_addc_u32 s57, s57, 0
	s_add_u32 s81, s81, 0x100
	s_addc_u32 s42, s42, 0
	s_cmp_gt_u32 s43, 13
	s_barrier
	s_cbranch_scc0 .LBB0_587
	s_and_b64 vcc, exec, s[26:27]
	s_cbranch_vccz .LBB0_590
	s_barrier

; #define PG8_STAGE(bufoff, gbase, voff) do { _Pragma("unroll") for (int _i = 0; _i < 2; ++_i) \
;         __builtin_amdgcn_global_load_lds((const unsigned*)((const char*)(gbase) + (voff)[_i]), (LAS unsigned*)(lds + (bufoff) + ldsw + _i * 8192), 16, 0, 1); } while (0)
; #define PG8_LDA(dst, b, h) do { _Pragma("unroll") for (int m = 0; m < 4; ++m) _Pragma("unroll") for (int k = 0; k < 2; ++k) dst[m][k] = *(const LAS bf16x8*)(lds + PG8_SA(b, h) + aoff + m * 2048 + k * 1024); } while (0)
; #define PG8_LDB(dst, b, h) do { _Pragma("unroll") for (int n = 0; n < 2; ++n) _Pragma("unroll") for (int k = 0; k < 2; ++k) dst[n][k] = *(const LAS bf16x8*)(lds + PG8_SB(b, h) + boff + n * 2048 + k * 1024); } while (0)
; #define PG8_MMA(ai, bj, At, Bt) do { __builtin_amdgcn_s_setprio(1); _Pragma("unroll") for (int m = 0; m < 4; ++m) _Pragma("unroll") for (int n = 0; n < 2; ++n) _Pragma("unroll") for (int k = 0; k < 2; ++k) \
;         acc[ai][bj][m][n] = __builtin_amdgcn_mfma_f32_16x16x32_bf16(Bt[n][k], At[m][k], acc[ai][bj][m][n], 0, 0, 0); __builtin_amdgcn_s_setprio(0); } while (0)
; #define PG8_WAIT_V(n) asm volatile("s_waitcnt vmcnt(" #n ")" ::: "memory")
; #define PG8_WAIT_L(n) asm volatile("s_waitcnt lgkmcnt(" #n ")" ::: "memory")
; template <class Epi, class Sched, bool ALIGN_EPI = false, bool SP2 = false>
; __device__ __forceinline__ void gemm_phase(LAS unsigned char* lds, const Gemm g, const Sched& S, const Epi& E) {
;     ...
;         for (int t = 0; t < nt; t += 2) {
;             const bool last = (t == nt - 2);
;             const char* a1 = cA + (size_t)(t + 1) * kstep;
;             const char* a2 = last ? nA : cA + (size_t)(t + 2) * kstep; const char* b2 = last ? nB : cB + (size_t)(t + 2) * kstep;
;             const char* a3 = a2 + kstep; const char* b3 = b2 + kstep;
;             if (last && has_next) S.a_ready(nxt);
;             if constexpr (SP2) {
;             PG8_LDB(B0, 0, 0); PG8_LDB(B1, 0, 1); PG8_SCHED; PG8_LDA(At, 0, 0); PG8_STAGE(PG8_SA(1, 1), a1 + hstep, voffA);
;             PG8_WAIT_V(8); PG8_WAIT_L(0); PG8_BAR; PG8_MMA(0, 0, At, B0); PG8_MMA(0, 1, At, B1); PG8_BAR; PG8_SCHED;
;             PG8_LDA(At, 0, 1); PG8_STAGE(PG8_SB(0, 0), b2, voffB); PG8_STAGE(PG8_SB(0, 1), b2 + hstep, voffB); PG8_STAGE(PG8_SA(0, 0), a2, voffA);
;             PG8_WAIT_V(8); PG8_WAIT_L(0); PG8_BAR; PG8_MMA(1, 0, At, B0); PG8_MMA(1, 1, At, B1); PG8_BAR; PG8_SCHED;
.LBB0_634:
	ds_read_b128 v[128:131], v159
	ds_read_b128 v[132:135], v159 offset:1024
	ds_read_b128 v[136:139], v159 offset:2048
	ds_read_b128 v[140:143], v159 offset:3072
	ds_read_b128 v[166:169], v161
	ds_read_b128 v[172:175], v161 offset:1024
	ds_read_b128 v[176:179], v161 offset:2048
	ds_read_b128 v[180:183], v161 offset:3072
	s_add_u32 s58, s56, 0x100
	s_addc_u32 s59, s57, 0
	s_cmp_eq_u32 s6, 28
	s_cselect_b32 s63, s49, s59
	s_cselect_b32 s62, s86, s58
	s_cselect_b32 s61, s47, s43
	s_cselect_b32 s60, s87, s42
	v_lshl_add_u64 v[184:185], s[56:57], 0, v[148:149]
	s_add_i32 m0, s55, 0xc000
	ds_read_b128 v[188:191], v170
	ds_read_b128 v[192:195], v170 offset:1024
	ds_read_b128 v[196:199], v170 offset:2048
	ds_read_b128 v[200:203], v170 offset:3072
	ds_read_b128 v[204:207], v170 offset:4096
	ds_read_b128 v[208:211], v170 offset:5120
	ds_read_b128 v[212:215], v170 offset:6144
	ds_read_b128 v[216:219], v170 offset:7168
	global_load_lds_dwordx4 v[184:185], off sc0
	v_lshl_add_u64 v[184:185], s[56:57], 0, v[150:151]
	s_add_i32 m0, s55, 0xe000
	s_nop 0
	global_load_lds_dwordx4 v[184:185], off sc0
	s_waitcnt vmcnt(8)
	s_waitcnt lgkmcnt(0)
	s_barrier
	s_setprio 1
	s_waitcnt lgkmcnt(0)
	v_mfma_f32_16x16x32_bf16 v[124:127], v[128:131], v[188:191], v[124:127]
	v_mfma_f32_16x16x32_bf16 v[120:123], v[136:139], v[188:191], v[120:123]
	v_mfma_f32_16x16x32_bf16 v[116:119], v[128:131], v[196:199], v[116:119]
	v_mfma_f32_16x16x32_bf16 v[112:115], v[136:139], v[196:199], v[112:115]
	v_mfma_f32_16x16x32_bf16 v[92:95], v[128:131], v[204:207], v[92:95]
	v_mfma_f32_16x16x32_bf16 v[88:91], v[136:139], v[204:207], v[88:91]
	v_mfma_f32_16x16x32_bf16 v[84:87], v[128:131], v[212:215], v[84:87]
	v_mfma_f32_16x16x32_bf16 v[80:83], v[136:139], v[212:215], v[80:83]
	v_mfma_f32_16x16x32_bf16 v[124:127], v[132:135], v[192:195], v[124:127]
	v_mfma_f32_16x16x32_bf16 v[120:123], v[140:143], v[192:195], v[120:123]
	v_mfma_f32_16x16x32_bf16 v[116:119], v[132:135], v[200:203], v[116:119]
	v_mfma_f32_16x16x32_bf16 v[112:115], v[140:143], v[200:203], v[112:115]
	v_mfma_f32_16x16x32_bf16 v[92:95], v[132:135], v[208:211], v[92:95]
	v_mfma_f32_16x16x32_bf16 v[88:91], v[140:143], v[208:211], v[88:91]
	v_mfma_f32_16x16x32_bf16 v[84:87], v[132:135], v[216:219], v[84:87]
	v_mfma_f32_16x16x32_bf16 v[80:83], v[140:143], v[216:219], v[80:83]
	s_setprio 0
	s_setprio 1
	v_mfma_f32_16x16x32_bf16 v[108:111], v[166:169], v[188:191], v[108:111]
	v_mfma_f32_16x16x32_bf16 v[104:107], v[176:179], v[188:191], v[104:107]
	v_mfma_f32_16x16x32_bf16 v[100:103], v[166:169], v[196:199], v[100:103]
	v_mfma_f32_16x16x32_bf16 v[96:99], v[176:179], v[196:199], v[96:99]
	v_mfma_f32_16x16x32_bf16 v[76:79], v[166:169], v[204:207], v[76:79]
	v_mfma_f32_16x16x32_bf16 v[72:75], v[176:179], v[204:207], v[72:75]
	v_mfma_f32_16x16x32_bf16 v[68:71], v[166:169], v[212:215], v[68:71]
	v_mfma_f32_16x16x32_bf16 v[64:67], v[176:179], v[212:215], v[64:67]
	v_mfma_f32_16x16x32_bf16 v[108:111], v[172:175], v[192:195], v[108:111]
	v_mfma_f32_16x16x32_bf16 v[104:107], v[180:183], v[192:195], v[104:107]
	v_mfma_f32_16x16x32_bf16 v[100:103], v[172:175], v[200:203], v[100:103]
	v_mfma_f32_16x16x32_bf16 v[96:99], v[180:183], v[200:203], v[96:99]
	v_mfma_f32_16x16x32_bf16 v[76:79], v[172:175], v[208:211], v[76:79]
	v_mfma_f32_16x16x32_bf16 v[72:75], v[180:183], v[208:211], v[72:75]
	v_mfma_f32_16x16x32_bf16 v[68:71], v[172:175], v[216:219], v[68:71]
	v_mfma_f32_16x16x32_bf16 v[64:67], v[180:183], v[216:219], v[64:67]
	s_setprio 0
	s_barrier
	s_add_i32 s7, s79, s67
	v_lshl_add_u64 v[184:185], s[60:61], 0, v[144:145]
	s_mov_b32 m0, s7
	ds_read_b128 v[188:191], v170 offset:16384
	ds_read_b128 v[192:195], v170 offset:17408
	ds_read_b128 v[196:199], v170 offset:18432
	ds_read_b128 v[200:203], v170 offset:19456
	ds_read_b128 v[204:207], v170 offset:20480
	ds_read_b128 v[208:211], v170 offset:21504
	ds_read_b128 v[212:215], v170 offset:22528
	ds_read_b128 v[216:219], v170 offset:23552
	global_load_lds_dwordx4 v[184:185], off sc0
	s_add_i32 m0, s7, 0x2000
	s_add_u32 s56, s60, 0x80000
	v_lshl_add_u64 v[220:221], s[60:61], 0, v[146:147]
	s_addc_u32 s57, s61, 0
	s_add_i32 s7, s80, s67
	global_load_lds_dwordx4 v[220:221], off sc0
	v_lshl_add_u64 v[222:223], s[56:57], 0, v[144:145]
	s_mov_b32 m0, s7
	v_lshl_add_u64 v[224:225], s[62:63], 0, v[146:147]
	global_load_lds_dwordx4 v[222:223], off sc0
	v_lshl_add_u64 v[222:223], s[56:57], 0, v[146:147]
	s_add_i32 m0, s7, 0x2000
	s_nop 0
	global_load_lds_dwordx4 v[222:223], off sc0
	v_lshl_add_u64 v[222:223], s[62:63], 0, v[144:145]
	s_mov_b32 m0, s55
	s_nop 0
	global_load_lds_dwordx4 v[222:223], off sc0
	s_mov_b32 m0, s68
	s_nop 0
	global_load_lds_dwordx4 v[224:225], off sc0
	s_waitcnt vmcnt(8)
	s_waitcnt lgkmcnt(0)
	s_barrier
; #define PG8_STAGE(bufoff, gbase, voff) do { _Pragma("unroll") for (int _i = 0; _i < 2; ++_i) \
;         __builtin_amdgcn_global_load_lds((const unsigned*)((const char*)(gbase) + (voff)[_i]), (LAS unsigned*)(lds + (bufoff) + ldsw + _i * 8192), 16, 0, 1); } while (0)
; #define PG8_LDA(dst, b, h) do { _Pragma("unroll") for (int m = 0; m < 4; ++m) _Pragma("unroll") for (int k = 0; k < 2; ++k) dst[m][k] = *(const LAS bf16x8*)(lds + PG8_SA(b, h) + aoff + m * 2048 + k * 1024); } while (0)
; #define PG8_LDB(dst, b, h) do { _Pragma("unroll") for (int n = 0; n < 2; ++n) _Pragma("unroll") for (int k = 0; k < 2; ++k) dst[n][k] = *(const LAS bf16x8*)(lds + PG8_SB(b, h) + boff + n * 2048 + k * 1024); } while (0)
; #define PG8_MMA(ai, bj, At, Bt) do { __builtin_amdgcn_s_setprio(1); _Pragma("unroll") for (int m = 0; m < 4; ++m) _Pragma("unroll") for (int n = 0; n < 2; ++n) _Pragma("unroll") for (int k = 0; k < 2; ++k) \
;         acc[ai][bj][m][n] = __builtin_amdgcn_mfma_f32_16x16x32_bf16(Bt[n][k], At[m][k], acc[ai][bj][m][n], 0, 0, 0); __builtin_amdgcn_s_setprio(0); } while (0)
; #define PG8_WAIT_V(n) asm volatile("s_waitcnt vmcnt(" #n ")" ::: "memory")
; #define PG8_WAIT_L(n) asm volatile("s_waitcnt lgkmcnt(" #n ")" ::: "memory")
; #define PG8_BAR __builtin_amdgcn_s_barrier()
; #define PG8_SCHED __builtin_amdgcn_sched_barrier(0)
; template <class Epi, class Sched, bool ALIGN_EPI = false, bool SP2 = false>
; __device__ __forceinline__ void gemm_phase(LAS unsigned char* lds, const Gemm g, const Sched& S, const Epi& E) {
;     ...
;             PG8_WAIT_V(8); PG8_WAIT_L(0); PG8_BAR; PG8_MMA(1, 0, At, B0); PG8_MMA(1, 1, At, B1); PG8_BAR; PG8_SCHED;
;             PG8_LDB(B0, 1, 0); PG8_LDB(B1, 1, 1); PG8_SCHED; PG8_LDA(At, 1, 0); PG8_STAGE(PG8_SA(0, 1), a2 + hstep, voffA);
;             PG8_WAIT_V(8); PG8_WAIT_L(0); PG8_BAR; PG8_MMA(0, 0, At, B0); PG8_MMA(0, 1, At, B1); PG8_BAR; PG8_SCHED;
	s_setprio 1
	s_waitcnt lgkmcnt(0)
	v_mfma_f32_16x16x32_bf16 v[60:63], v[128:131], v[188:191], v[60:63]
	v_mfma_f32_16x16x32_bf16 v[56:59], v[136:139], v[188:191], v[56:59]
	v_mfma_f32_16x16x32_bf16 v[52:55], v[128:131], v[196:199], v[52:55]
	v_mfma_f32_16x16x32_bf16 v[48:51], v[136:139], v[196:199], v[48:51]
	v_mfma_f32_16x16x32_bf16 v[28:31], v[128:131], v[204:207], v[28:31]
	v_mfma_f32_16x16x32_bf16 v[24:27], v[136:139], v[204:207], v[24:27]
	v_mfma_f32_16x16x32_bf16 v[20:23], v[128:131], v[212:215], v[20:23]
	v_mfma_f32_16x16x32_bf16 v[16:19], v[136:139], v[212:215], v[16:19]
	v_mfma_f32_16x16x32_bf16 v[60:63], v[132:135], v[192:195], v[60:63]
	v_mfma_f32_16x16x32_bf16 v[56:59], v[140:143], v[192:195], v[56:59]
	v_mfma_f32_16x16x32_bf16 v[52:55], v[132:135], v[200:203], v[52:55]
	v_mfma_f32_16x16x32_bf16 v[48:51], v[140:143], v[200:203], v[48:51]
	v_mfma_f32_16x16x32_bf16 v[28:31], v[132:135], v[208:211], v[28:31]
	v_mfma_f32_16x16x32_bf16 v[24:27], v[140:143], v[208:211], v[24:27]
	v_mfma_f32_16x16x32_bf16 v[20:23], v[132:135], v[216:219], v[20:23]
	v_mfma_f32_16x16x32_bf16 v[16:19], v[140:143], v[216:219], v[16:19]
	s_setprio 0
	s_setprio 1
	v_mfma_f32_16x16x32_bf16 v[44:47], v[166:169], v[188:191], v[44:47]
	v_mfma_f32_16x16x32_bf16 v[40:43], v[176:179], v[188:191], v[40:43]
	v_mfma_f32_16x16x32_bf16 v[36:39], v[166:169], v[196:199], v[36:39]
	v_mfma_f32_16x16x32_bf16 v[32:35], v[176:179], v[196:199], v[32:35]
	v_mfma_f32_16x16x32_bf16 v[12:15], v[166:169], v[204:207], v[12:15]
	v_mfma_f32_16x16x32_bf16 v[8:11], v[176:179], v[204:207], v[8:11]
	v_mfma_f32_16x16x32_bf16 v[4:7], v[166:169], v[212:215], v[4:7]
	v_mfma_f32_16x16x32_bf16 v[0:3], v[176:179], v[212:215], v[0:3]
	v_mfma_f32_16x16x32_bf16 v[44:47], v[172:175], v[192:195], v[44:47]
	v_mfma_f32_16x16x32_bf16 v[40:43], v[180:183], v[192:195], v[40:43]
	v_mfma_f32_16x16x32_bf16 v[36:39], v[172:175], v[200:203], v[36:39]
	v_mfma_f32_16x16x32_bf16 v[32:35], v[180:183], v[200:203], v[32:35]
	v_mfma_f32_16x16x32_bf16 v[12:15], v[172:175], v[208:211], v[12:15]
	v_mfma_f32_16x16x32_bf16 v[8:11], v[180:183], v[208:211], v[8:11]
	v_mfma_f32_16x16x32_bf16 v[4:7], v[172:175], v[216:219], v[4:7]
	v_mfma_f32_16x16x32_bf16 v[0:3], v[180:183], v[216:219], v[0:3]
	s_setprio 0
	s_barrier
	s_add_i32 s7, 0, 0x18000
	s_add_i32 s88, 0, 0x1c000
	v_add_u32_e32 v140, s7, v155
	v_add_u32_e32 v171, s88, v155
	ds_read_b128 v[128:131], v140
	ds_read_b128 v[132:135], v140 offset:1024
	ds_read_b128 v[136:139], v140 offset:2048
	ds_read_b128 v[140:143], v140 offset:3072
	ds_read_b128 v[166:169], v171
	ds_read_b128 v[172:175], v171 offset:1024
	ds_read_b128 v[176:179], v171 offset:2048
	ds_read_b128 v[180:183], v171 offset:3072
	s_add_u32 s56, s62, 0x80000
	s_addc_u32 s57, s63, 0
	s_mov_b32 m0, s69
	v_lshl_add_u64 v[226:227], s[56:57], 0, v[144:145]
	ds_read_b128 v[188:191], v170 offset:32768
	ds_read_b128 v[192:195], v170 offset:33792
	ds_read_b128 v[196:199], v170 offset:34816
	ds_read_b128 v[200:203], v170 offset:35840
	ds_read_b128 v[204:207], v170 offset:36864
	ds_read_b128 v[208:211], v170 offset:37888
	ds_read_b128 v[212:215], v170 offset:38912
	ds_read_b128 v[216:219], v170 offset:39936
	global_load_lds_dwordx4 v[226:227], off sc0
	v_lshl_add_u64 v[226:227], s[56:57], 0, v[146:147]
	s_mov_b32 m0, s73
	s_nop 0
	global_load_lds_dwordx4 v[226:227], off sc0
	s_waitcnt vmcnt(8)
	s_waitcnt lgkmcnt(0)
	s_barrier
	s_setprio 1
	s_waitcnt lgkmcnt(0)
	v_mfma_f32_16x16x32_bf16 v[124:127], v[128:131], v[188:191], v[124:127]
	v_mfma_f32_16x16x32_bf16 v[120:123], v[136:139], v[188:191], v[120:123]
	v_mfma_f32_16x16x32_bf16 v[116:119], v[128:131], v[196:199], v[116:119]
	v_mfma_f32_16x16x32_bf16 v[112:115], v[136:139], v[196:199], v[112:115]
	v_mfma_f32_16x16x32_bf16 v[92:95], v[128:131], v[204:207], v[92:95]
	v_mfma_f32_16x16x32_bf16 v[88:91], v[136:139], v[204:207], v[88:91]
	v_mfma_f32_16x16x32_bf16 v[84:87], v[128:131], v[212:215], v[84:87]
	v_mfma_f32_16x16x32_bf16 v[80:83], v[136:139], v[212:215], v[80:83]
	v_mfma_f32_16x16x32_bf16 v[124:127], v[132:135], v[192:195], v[124:127]
	v_mfma_f32_16x16x32_bf16 v[120:123], v[140:143], v[192:195], v[120:123]
	v_mfma_f32_16x16x32_bf16 v[116:119], v[132:135], v[200:203], v[116:119]
	v_mfma_f32_16x16x32_bf16 v[112:115], v[140:143], v[200:203], v[112:115]
	v_mfma_f32_16x16x32_bf16 v[92:95], v[132:135], v[208:211], v[92:95]
	v_mfma_f32_16x16x32_bf16 v[88:91], v[140:143], v[208:211], v[88:91]
	v_mfma_f32_16x16x32_bf16 v[84:87], v[132:135], v[216:219], v[84:87]
	v_mfma_f32_16x16x32_bf16 v[80:83], v[140:143], v[216:219], v[80:83]
	s_setprio 0
	s_setprio 1
	v_mfma_f32_16x16x32_bf16 v[108:111], v[166:169], v[188:191], v[108:111]
	v_mfma_f32_16x16x32_bf16 v[104:107], v[176:179], v[188:191], v[104:107]
	v_mfma_f32_16x16x32_bf16 v[100:103], v[166:169], v[196:199], v[100:103]
	v_mfma_f32_16x16x32_bf16 v[96:99], v[176:179], v[196:199], v[96:99]
	v_mfma_f32_16x16x32_bf16 v[76:79], v[166:169], v[204:207], v[76:79]
	v_mfma_f32_16x16x32_bf16 v[72:75], v[176:179], v[204:207], v[72:75]
	v_mfma_f32_16x16x32_bf16 v[68:71], v[166:169], v[212:215], v[68:71]
	v_mfma_f32_16x16x32_bf16 v[64:67], v[176:179], v[212:215], v[64:67]
	v_mfma_f32_16x16x32_bf16 v[108:111], v[172:175], v[192:195], v[108:111]
	v_mfma_f32_16x16x32_bf16 v[104:107], v[180:183], v[192:195], v[104:107]
	v_mfma_f32_16x16x32_bf16 v[100:103], v[172:175], v[200:203], v[100:103]
	v_mfma_f32_16x16x32_bf16 v[96:99], v[180:183], v[200:203], v[96:99]
	v_mfma_f32_16x16x32_bf16 v[76:79], v[172:175], v[208:211], v[76:79]
	v_mfma_f32_16x16x32_bf16 v[72:75], v[180:183], v[208:211], v[72:75]
	v_mfma_f32_16x16x32_bf16 v[68:71], v[172:175], v[216:219], v[68:71]
	v_mfma_f32_16x16x32_bf16 v[64:67], v[180:183], v[216:219], v[64:67]
	s_setprio 0
	s_barrier
; #define PG8_STAGE(bufoff, gbase, voff) do { _Pragma("unroll") for (int _i = 0; _i < 2; ++_i) \
;         __builtin_amdgcn_global_load_lds((const unsigned*)((const char*)(gbase) + (voff)[_i]), (LAS unsigned*)(lds + (bufoff) + ldsw + _i * 8192), 16, 0, 1); } while (0)
; #define PG8_LDA(dst, b, h) do { _Pragma("unroll") for (int m = 0; m < 4; ++m) _Pragma("unroll") for (int k = 0; k < 2; ++k) dst[m][k] = *(const LAS bf16x8*)(lds + PG8_SA(b, h) + aoff + m * 2048 + k * 1024); } while (0)
; #define PG8_MMA(ai, bj, At, Bt) do { __builtin_amdgcn_s_setprio(1); _Pragma("unroll") for (int m = 0; m < 4; ++m) _Pragma("unroll") for (int n = 0; n < 2; ++n) _Pragma("unroll") for (int k = 0; k < 2; ++k) \
;         acc[ai][bj][m][n] = __builtin_amdgcn_mfma_f32_16x16x32_bf16(Bt[n][k], At[m][k], acc[ai][bj][m][n], 0, 0, 0); __builtin_amdgcn_s_setprio(0); } while (0)
; #define PG8_WAIT_V(n) asm volatile("s_waitcnt vmcnt(" #n ")" ::: "memory")
; #define PG8_WAIT_L(n) asm volatile("s_waitcnt lgkmcnt(" #n ")" ::: "memory")
; #define PG8_BAR __builtin_amdgcn_s_barrier()
; #define PG8_SCHED __builtin_amdgcn_sched_barrier(0)
; template <class Epi, class Sched, bool ALIGN_EPI = false, bool SP2 = false>
; __device__ __forceinline__ void gemm_phase(LAS unsigned char* lds, const Gemm g, const Sched& S, const Epi& E) {
;     ...
;         for (int t = 0; t < nt; t += 2) {
;     ...
;             PG8_LDA(At, 1, 1); PG8_STAGE(PG8_SB(1, 0), b3, voffB); PG8_STAGE(PG8_SB(1, 1), b3 + hstep, voffB); PG8_STAGE(PG8_SA(1, 0), a3, voffA);
;             PG8_WAIT_V(8); PG8_WAIT_L(0); PG8_BAR; PG8_MMA(1, 0, At, B0); PG8_MMA(1, 1, At, B1); PG8_BAR; PG8_SCHED;
	s_add_i32 s7, s7, s67
	v_lshl_add_u64 v[184:185], v[184:185], 0, s[18:19]
	s_mov_b32 m0, s7
	ds_read_b128 v[188:191], v170 offset:49152
	ds_read_b128 v[192:195], v170 offset:50176
	ds_read_b128 v[196:199], v170 offset:51200
	ds_read_b128 v[200:203], v170 offset:52224
	ds_read_b128 v[204:207], v170 offset:53248
	ds_read_b128 v[208:211], v170 offset:54272
	ds_read_b128 v[212:215], v170 offset:55296
	ds_read_b128 v[216:219], v170 offset:56320
	global_load_lds_dwordx4 v[184:185], off sc0
	s_add_i32 m0, s7, 0x2000
	s_add_u32 s56, s60, 0x80080
	v_lshl_add_u64 v[184:185], v[220:221], 0, s[18:19]
	s_addc_u32 s57, s61, 0
	s_add_i32 s7, s88, s67
	global_load_lds_dwordx4 v[184:185], off sc0
	v_lshl_add_u64 v[184:185], s[56:57], 0, v[144:145]
	s_mov_b32 m0, s7
	s_nop 0
	global_load_lds_dwordx4 v[184:185], off sc0
	v_lshl_add_u64 v[184:185], s[56:57], 0, v[146:147]
	s_add_i32 m0, s7, 0x2000
	s_nop 0
	global_load_lds_dwordx4 v[184:185], off sc0
	v_lshl_add_u64 v[184:185], v[222:223], 0, s[18:19]
	s_mov_b32 m0, s77
	s_nop 0
	global_load_lds_dwordx4 v[184:185], off sc0
	v_lshl_add_u64 v[184:185], v[224:225], 0, s[18:19]
	s_mov_b32 m0, s78
	s_nop 0
	global_load_lds_dwordx4 v[184:185], off sc0
	s_waitcnt vmcnt(8)
	s_waitcnt lgkmcnt(0)
	s_barrier
	s_setprio 1
	s_waitcnt lgkmcnt(0)
	v_mfma_f32_16x16x32_bf16 v[60:63], v[128:131], v[188:191], v[60:63]
	v_mfma_f32_16x16x32_bf16 v[56:59], v[136:139], v[188:191], v[56:59]
	v_mfma_f32_16x16x32_bf16 v[52:55], v[128:131], v[196:199], v[52:55]
	v_mfma_f32_16x16x32_bf16 v[48:51], v[136:139], v[196:199], v[48:51]
	v_mfma_f32_16x16x32_bf16 v[28:31], v[128:131], v[204:207], v[28:31]
	v_mfma_f32_16x16x32_bf16 v[24:27], v[136:139], v[204:207], v[24:27]
	v_mfma_f32_16x16x32_bf16 v[20:23], v[128:131], v[212:215], v[20:23]
	v_mfma_f32_16x16x32_bf16 v[16:19], v[136:139], v[212:215], v[16:19]
	v_mfma_f32_16x16x32_bf16 v[60:63], v[132:135], v[192:195], v[60:63]
	v_mfma_f32_16x16x32_bf16 v[56:59], v[140:143], v[192:195], v[56:59]
	v_mfma_f32_16x16x32_bf16 v[52:55], v[132:135], v[200:203], v[52:55]
	v_mfma_f32_16x16x32_bf16 v[48:51], v[140:143], v[200:203], v[48:51]
	v_mfma_f32_16x16x32_bf16 v[28:31], v[132:135], v[208:211], v[28:31]
	v_mfma_f32_16x16x32_bf16 v[24:27], v[140:143], v[208:211], v[24:27]
	v_mfma_f32_16x16x32_bf16 v[20:23], v[132:135], v[216:219], v[20:23]
	v_mfma_f32_16x16x32_bf16 v[16:19], v[140:143], v[216:219], v[16:19]
	s_setprio 0
	s_setprio 1
	v_mfma_f32_16x16x32_bf16 v[44:47], v[166:169], v[188:191], v[44:47]
	v_mfma_f32_16x16x32_bf16 v[40:43], v[176:179], v[188:191], v[40:43]
	v_mfma_f32_16x16x32_bf16 v[36:39], v[166:169], v[196:199], v[36:39]
	v_mfma_f32_16x16x32_bf16 v[32:35], v[176:179], v[196:199], v[32:35]
	v_mfma_f32_16x16x32_bf16 v[12:15], v[166:169], v[204:207], v[12:15]
	v_mfma_f32_16x16x32_bf16 v[8:11], v[176:179], v[204:207], v[8:11]
	v_mfma_f32_16x16x32_bf16 v[4:7], v[166:169], v[212:215], v[4:7]
	v_mfma_f32_16x16x32_bf16 v[0:3], v[176:179], v[212:215], v[0:3]
	v_mfma_f32_16x16x32_bf16 v[44:47], v[172:175], v[192:195], v[44:47]
	v_mfma_f32_16x16x32_bf16 v[40:43], v[180:183], v[192:195], v[40:43]
	v_mfma_f32_16x16x32_bf16 v[36:39], v[172:175], v[200:203], v[36:39]
	v_mfma_f32_16x16x32_bf16 v[32:35], v[180:183], v[200:203], v[32:35]
	v_mfma_f32_16x16x32_bf16 v[12:15], v[172:175], v[208:211], v[12:15]
	v_mfma_f32_16x16x32_bf16 v[8:11], v[180:183], v[208:211], v[8:11]
	v_mfma_f32_16x16x32_bf16 v[4:7], v[172:175], v[216:219], v[4:7]
	v_mfma_f32_16x16x32_bf16 v[0:3], v[180:183], v[216:219], v[0:3]
	s_setprio 0
	s_add_i32 s6, s6, 2
	s_add_u32 s42, s42, 0x100
	s_addc_u32 s43, s43, 0
	s_cmp_gt_u32 s6, 29
	s_mov_b64 s[56:57], s[58:59]
	s_barrier
	s_cbranch_scc0 .LBB0_634
	s_and_b64 vcc, exec, s[24:25]
	s_cbranch_vccz .LBB0_637
	s_barrier

; #define PG8_STAGE(bufoff, gbase, voff) do { _Pragma("unroll") for (int _i = 0; _i < 2; ++_i) \
;         __builtin_amdgcn_global_load_lds((const unsigned*)((const char*)(gbase) + (voff)[_i]), (LAS unsigned*)(lds + (bufoff) + ldsw + _i * 8192), 16, 0, 1); } while (0)
; #define PG8_LDA(dst, b, h) do { _Pragma("unroll") for (int m = 0; m < 4; ++m) _Pragma("unroll") for (int k = 0; k < 2; ++k) dst[m][k] = *(const LAS bf16x8*)(lds + PG8_SA(b, h) + aoff + m * 2048 + k * 1024); } while (0)
; #define PG8_LDB(dst, b, h) do { _Pragma("unroll") for (int n = 0; n < 2; ++n) _Pragma("unroll") for (int k = 0; k < 2; ++k) dst[n][k] = *(const LAS bf16x8*)(lds + PG8_SB(b, h) + boff + n * 2048 + k * 1024); } while (0)
; #define PG8_MMA(ai, bj, At, Bt) do { __builtin_amdgcn_s_setprio(1); _Pragma("unroll") for (int m = 0; m < 4; ++m) _Pragma("unroll") for (int n = 0; n < 2; ++n) _Pragma("unroll") for (int k = 0; k < 2; ++k) \
;         acc[ai][bj][m][n] = __builtin_amdgcn_mfma_f32_16x16x32_bf16(Bt[n][k], At[m][k], acc[ai][bj][m][n], 0, 0, 0); __builtin_amdgcn_s_setprio(0); } while (0)
; #define PG8_WAIT_V(n) asm volatile("s_waitcnt vmcnt(" #n ")" ::: "memory")
; #define PG8_WAIT_L(n) asm volatile("s_waitcnt lgkmcnt(" #n ")" ::: "memory")
; template <class Epi, class Sched, bool ALIGN_EPI = false, bool SP2 = false>
; __device__ __forceinline__ void gemm_phase(LAS unsigned char* lds, const Gemm g, const Sched& S, const Epi& E) {
;     ...
;         for (int t = 0; t < nt; t += 2) {
;             const bool last = (t == nt - 2);
;             const char* a1 = cA + (size_t)(t + 1) * kstep;
;             const char* a2 = last ? nA : cA + (size_t)(t + 2) * kstep; const char* b2 = last ? nB : cB + (size_t)(t + 2) * kstep;
;             const char* a3 = a2 + kstep; const char* b3 = b2 + kstep;
;             if (last && has_next) S.a_ready(nxt);
;             if constexpr (SP2) {
;             PG8_LDB(B0, 0, 0); PG8_LDB(B1, 0, 1); PG8_SCHED; PG8_LDA(At, 0, 0); PG8_STAGE(PG8_SA(1, 1), a1 + hstep, voffA);
;             PG8_WAIT_V(8); PG8_WAIT_L(0); PG8_BAR; PG8_MMA(0, 0, At, B0); PG8_MMA(0, 1, At, B1); PG8_BAR; PG8_SCHED;
;             PG8_LDA(At, 0, 1); PG8_STAGE(PG8_SB(0, 0), b2, voffB); PG8_STAGE(PG8_SB(0, 1), b2 + hstep, voffB); PG8_STAGE(PG8_SA(0, 0), a2, voffA);
;             PG8_WAIT_V(8); PG8_WAIT_L(0); PG8_BAR; PG8_MMA(1, 0, At, B0); PG8_MMA(1, 1, At, B1); PG8_BAR; PG8_SCHED;
.LBB0_699:
	ds_read_b128 v[156:159], v147
	ds_read_b128 v[160:163], v147 offset:1024
	ds_read_b128 v[164:167], v147 offset:2048
	ds_read_b128 v[168:171], v147 offset:3072
	ds_read_b128 v[172:175], v148
	ds_read_b128 v[176:179], v148 offset:1024
	ds_read_b128 v[180:183], v148 offset:2048
	ds_read_b128 v[188:191], v148 offset:3072
	s_add_u32 s6, s42, 0xfff80080
	s_addc_u32 s7, s43, -1
	s_cmp_eq_u32 s68, 28
	s_cselect_b32 s47, s27, s7
	s_cselect_b32 s46, s64, s6
	s_cselect_b32 s45, s25, s67
	s_cselect_b32 s44, s65, s66
	v_lshl_add_u64 v[150:151], s[42:43], 0, v[136:137]
	s_add_i32 m0, s39, 0xc000
	ds_read_b128 v[192:195], v149
	ds_read_b128 v[196:199], v149 offset:1024
	ds_read_b128 v[200:203], v149 offset:2048
	ds_read_b128 v[204:207], v149 offset:3072
	ds_read_b128 v[208:211], v149 offset:4096
	ds_read_b128 v[212:215], v149 offset:5120
	ds_read_b128 v[216:219], v149 offset:6144
	ds_read_b128 v[220:223], v149 offset:7168
	global_load_lds_dwordx4 v[150:151], off sc0
	v_lshl_add_u64 v[150:151], s[42:43], 0, v[138:139]
	s_add_i32 m0, s39, 0xe000
	s_nop 0
	global_load_lds_dwordx4 v[150:151], off sc0
	s_waitcnt vmcnt(8)
	s_waitcnt lgkmcnt(0)
	s_barrier
	s_setprio 1
	s_waitcnt lgkmcnt(0)
	v_mfma_f32_16x16x32_bf16 v[124:127], v[156:159], v[192:195], v[124:127]
	v_mfma_f32_16x16x32_bf16 v[116:119], v[164:167], v[192:195], v[116:119]
	v_mfma_f32_16x16x32_bf16 v[108:111], v[156:159], v[200:203], v[108:111]
	v_mfma_f32_16x16x32_bf16 v[100:103], v[164:167], v[200:203], v[100:103]
	v_mfma_f32_16x16x32_bf16 v[92:95], v[156:159], v[208:211], v[92:95]
	v_mfma_f32_16x16x32_bf16 v[84:87], v[164:167], v[208:211], v[84:87]
	v_mfma_f32_16x16x32_bf16 v[76:79], v[156:159], v[216:219], v[76:79]
	v_mfma_f32_16x16x32_bf16 v[68:71], v[164:167], v[216:219], v[68:71]
	v_mfma_f32_16x16x32_bf16 v[124:127], v[160:163], v[196:199], v[124:127]
	v_mfma_f32_16x16x32_bf16 v[116:119], v[168:171], v[196:199], v[116:119]
	v_mfma_f32_16x16x32_bf16 v[108:111], v[160:163], v[204:207], v[108:111]
	v_mfma_f32_16x16x32_bf16 v[100:103], v[168:171], v[204:207], v[100:103]
	v_mfma_f32_16x16x32_bf16 v[92:95], v[160:163], v[212:215], v[92:95]
	v_mfma_f32_16x16x32_bf16 v[84:87], v[168:171], v[212:215], v[84:87]
	v_mfma_f32_16x16x32_bf16 v[76:79], v[160:163], v[220:223], v[76:79]
	v_mfma_f32_16x16x32_bf16 v[68:71], v[168:171], v[220:223], v[68:71]
	s_setprio 0
	s_setprio 1
	v_mfma_f32_16x16x32_bf16 v[120:123], v[172:175], v[192:195], v[120:123]
	v_mfma_f32_16x16x32_bf16 v[112:115], v[180:183], v[192:195], v[112:115]
	v_mfma_f32_16x16x32_bf16 v[104:107], v[172:175], v[200:203], v[104:107]
	v_mfma_f32_16x16x32_bf16 v[96:99], v[180:183], v[200:203], v[96:99]
	v_mfma_f32_16x16x32_bf16 v[88:91], v[172:175], v[208:211], v[88:91]
	v_mfma_f32_16x16x32_bf16 v[80:83], v[180:183], v[208:211], v[80:83]
	v_mfma_f32_16x16x32_bf16 v[72:75], v[172:175], v[216:219], v[72:75]
	v_mfma_f32_16x16x32_bf16 v[64:67], v[180:183], v[216:219], v[64:67]
	v_mfma_f32_16x16x32_bf16 v[120:123], v[176:179], v[196:199], v[120:123]
	v_mfma_f32_16x16x32_bf16 v[112:115], v[188:191], v[196:199], v[112:115]
	v_mfma_f32_16x16x32_bf16 v[104:107], v[176:179], v[204:207], v[104:107]
	v_mfma_f32_16x16x32_bf16 v[96:99], v[188:191], v[204:207], v[96:99]
	v_mfma_f32_16x16x32_bf16 v[88:91], v[176:179], v[212:215], v[88:91]
	v_mfma_f32_16x16x32_bf16 v[80:83], v[188:191], v[212:215], v[80:83]
	v_mfma_f32_16x16x32_bf16 v[72:75], v[176:179], v[220:223], v[72:75]
	v_mfma_f32_16x16x32_bf16 v[64:67], v[188:191], v[220:223], v[64:67]
	s_setprio 0
	s_barrier
	s_add_i32 s6, s60, s52
	v_lshl_add_u64 v[150:151], s[44:45], 0, v[132:133]
	s_mov_b32 m0, s6
	ds_read_b128 v[192:195], v149 offset:16384
	ds_read_b128 v[196:199], v149 offset:17408
	ds_read_b128 v[200:203], v149 offset:18432
	ds_read_b128 v[204:207], v149 offset:19456
	ds_read_b128 v[208:211], v149 offset:20480
	ds_read_b128 v[212:215], v149 offset:21504
	ds_read_b128 v[216:219], v149 offset:22528
	ds_read_b128 v[220:223], v149 offset:23552
	global_load_lds_dwordx4 v[150:151], off sc0
	s_add_i32 m0, s6, 0x2000
	s_add_u32 s6, s44, 0x80000
	v_lshl_add_u64 v[184:185], s[44:45], 0, v[128:129]
	s_addc_u32 s7, s45, 0
	s_add_i32 s69, s61, s52
	global_load_lds_dwordx4 v[184:185], off sc0
	v_lshl_add_u64 v[224:225], s[6:7], 0, v[132:133]
	s_mov_b32 m0, s69
	v_lshl_add_u64 v[226:227], s[46:47], 0, v[130:131]
	global_load_lds_dwordx4 v[224:225], off sc0
	v_lshl_add_u64 v[224:225], s[6:7], 0, v[128:129]
	s_add_i32 m0, s69, 0x2000
	s_nop 0
	global_load_lds_dwordx4 v[224:225], off sc0
	v_lshl_add_u64 v[224:225], s[46:47], 0, v[134:135]
	s_mov_b32 m0, s39
	s_nop 0
	global_load_lds_dwordx4 v[224:225], off sc0
	s_mov_b32 m0, s54
	s_nop 0
	global_load_lds_dwordx4 v[226:227], off sc0
	s_waitcnt vmcnt(8)
	s_waitcnt lgkmcnt(0)
	s_barrier
; #define PG8_STAGE(bufoff, gbase, voff) do { _Pragma("unroll") for (int _i = 0; _i < 2; ++_i) \
;         __builtin_amdgcn_global_load_lds((const unsigned*)((const char*)(gbase) + (voff)[_i]), (LAS unsigned*)(lds + (bufoff) + ldsw + _i * 8192), 16, 0, 1); } while (0)
; #define PG8_LDA(dst, b, h) do { _Pragma("unroll") for (int m = 0; m < 4; ++m) _Pragma("unroll") for (int k = 0; k < 2; ++k) dst[m][k] = *(const LAS bf16x8*)(lds + PG8_SA(b, h) + aoff + m * 2048 + k * 1024); } while (0)
; #define PG8_LDB(dst, b, h) do { _Pragma("unroll") for (int n = 0; n < 2; ++n) _Pragma("unroll") for (int k = 0; k < 2; ++k) dst[n][k] = *(const LAS bf16x8*)(lds + PG8_SB(b, h) + boff + n * 2048 + k * 1024); } while (0)
; #define PG8_MMA(ai, bj, At, Bt) do { __builtin_amdgcn_s_setprio(1); _Pragma("unroll") for (int m = 0; m < 4; ++m) _Pragma("unroll") for (int n = 0; n < 2; ++n) _Pragma("unroll") for (int k = 0; k < 2; ++k) \
;         acc[ai][bj][m][n] = __builtin_amdgcn_mfma_f32_16x16x32_bf16(Bt[n][k], At[m][k], acc[ai][bj][m][n], 0, 0, 0); __builtin_amdgcn_s_setprio(0); } while (0)
; #define PG8_WAIT_V(n) asm volatile("s_waitcnt vmcnt(" #n ")" ::: "memory")
; #define PG8_WAIT_L(n) asm volatile("s_waitcnt lgkmcnt(" #n ")" ::: "memory")
; #define PG8_BAR __builtin_amdgcn_s_barrier()
; #define PG8_SCHED __builtin_amdgcn_sched_barrier(0)
; template <class Epi, class Sched, bool ALIGN_EPI = false, bool SP2 = false>
; __device__ __forceinline__ void gemm_phase(LAS unsigned char* lds, const Gemm g, const Sched& S, const Epi& E) {
;     ...
;             PG8_WAIT_V(8); PG8_WAIT_L(0); PG8_BAR; PG8_MMA(1, 0, At, B0); PG8_MMA(1, 1, At, B1); PG8_BAR; PG8_SCHED;
;             PG8_LDB(B0, 1, 0); PG8_LDB(B1, 1, 1); PG8_SCHED; PG8_LDA(At, 1, 0); PG8_STAGE(PG8_SA(0, 1), a2 + hstep, voffA);
;             PG8_WAIT_V(8); PG8_WAIT_L(0); PG8_BAR; PG8_MMA(0, 0, At, B0); PG8_MMA(0, 1, At, B1); PG8_BAR; PG8_SCHED;
	s_setprio 1
	s_waitcnt lgkmcnt(0)
	v_mfma_f32_16x16x32_bf16 v[60:63], v[156:159], v[192:195], v[60:63]
	v_mfma_f32_16x16x32_bf16 v[52:55], v[164:167], v[192:195], v[52:55]
	v_mfma_f32_16x16x32_bf16 v[44:47], v[156:159], v[200:203], v[44:47]
	v_mfma_f32_16x16x32_bf16 v[36:39], v[164:167], v[200:203], v[36:39]
	v_mfma_f32_16x16x32_bf16 v[28:31], v[156:159], v[208:211], v[28:31]
	v_mfma_f32_16x16x32_bf16 v[20:23], v[164:167], v[208:211], v[20:23]
	v_mfma_f32_16x16x32_bf16 v[12:15], v[156:159], v[216:219], v[12:15]
	v_mfma_f32_16x16x32_bf16 v[4:7], v[164:167], v[216:219], v[4:7]
	v_mfma_f32_16x16x32_bf16 v[60:63], v[160:163], v[196:199], v[60:63]
	v_mfma_f32_16x16x32_bf16 v[52:55], v[168:171], v[196:199], v[52:55]
	v_mfma_f32_16x16x32_bf16 v[44:47], v[160:163], v[204:207], v[44:47]
	v_mfma_f32_16x16x32_bf16 v[36:39], v[168:171], v[204:207], v[36:39]
	v_mfma_f32_16x16x32_bf16 v[28:31], v[160:163], v[212:215], v[28:31]
	v_mfma_f32_16x16x32_bf16 v[20:23], v[168:171], v[212:215], v[20:23]
	v_mfma_f32_16x16x32_bf16 v[12:15], v[160:163], v[220:223], v[12:15]
	v_mfma_f32_16x16x32_bf16 v[4:7], v[168:171], v[220:223], v[4:7]
	s_setprio 0
	s_setprio 1
	v_mfma_f32_16x16x32_bf16 v[56:59], v[172:175], v[192:195], v[56:59]
	v_mfma_f32_16x16x32_bf16 v[48:51], v[180:183], v[192:195], v[48:51]
	v_mfma_f32_16x16x32_bf16 v[40:43], v[172:175], v[200:203], v[40:43]
	v_mfma_f32_16x16x32_bf16 v[32:35], v[180:183], v[200:203], v[32:35]
	v_mfma_f32_16x16x32_bf16 v[24:27], v[172:175], v[208:211], v[24:27]
	v_mfma_f32_16x16x32_bf16 v[16:19], v[180:183], v[208:211], v[16:19]
	v_mfma_f32_16x16x32_bf16 v[8:11], v[172:175], v[216:219], v[8:11]
	v_mfma_f32_16x16x32_bf16 v[0:3], v[180:183], v[216:219], v[0:3]
	v_mfma_f32_16x16x32_bf16 v[56:59], v[176:179], v[196:199], v[56:59]
	v_mfma_f32_16x16x32_bf16 v[48:51], v[188:191], v[196:199], v[48:51]
	v_mfma_f32_16x16x32_bf16 v[40:43], v[176:179], v[204:207], v[40:43]
	v_mfma_f32_16x16x32_bf16 v[32:35], v[188:191], v[204:207], v[32:35]
	v_mfma_f32_16x16x32_bf16 v[24:27], v[176:179], v[212:215], v[24:27]
	v_mfma_f32_16x16x32_bf16 v[16:19], v[188:191], v[212:215], v[16:19]
	v_mfma_f32_16x16x32_bf16 v[8:11], v[176:179], v[220:223], v[8:11]
	v_mfma_f32_16x16x32_bf16 v[0:3], v[188:191], v[220:223], v[0:3]
	s_setprio 0
	s_barrier
	s_add_i32 s69, 0, 0x18000
	v_add_u32_e32 v153, s69, v145
	s_add_i32 s73, 0, 0x1c000
	ds_read_b128 v[156:159], v153
	ds_read_b128 v[160:163], v153 offset:1024
	ds_read_b128 v[164:167], v153 offset:2048
	ds_read_b128 v[168:171], v153 offset:3072
	v_add_u32_e32 v153, s73, v145
	ds_read_b128 v[172:175], v153
	ds_read_b128 v[176:179], v153 offset:1024
	ds_read_b128 v[180:183], v153 offset:2048
	ds_read_b128 v[188:191], v153 offset:3072
	s_add_u32 s6, s46, 0x80000
	s_addc_u32 s7, s47, 0
	s_mov_b32 m0, s55
	v_lshl_add_u64 v[228:229], s[6:7], 0, v[134:135]
	ds_read_b128 v[192:195], v149 offset:32768
	ds_read_b128 v[196:199], v149 offset:33792
	ds_read_b128 v[200:203], v149 offset:34816
	ds_read_b128 v[204:207], v149 offset:35840
	ds_read_b128 v[208:211], v149 offset:36864
	ds_read_b128 v[212:215], v149 offset:37888
	ds_read_b128 v[216:219], v149 offset:38912
	ds_read_b128 v[220:223], v149 offset:39936
	global_load_lds_dwordx4 v[228:229], off sc0
	v_lshl_add_u64 v[228:229], s[6:7], 0, v[130:131]
	s_mov_b32 m0, s56
	s_nop 0
	global_load_lds_dwordx4 v[228:229], off sc0
	s_waitcnt vmcnt(8)
	s_waitcnt lgkmcnt(0)
	s_barrier
	s_setprio 1
	s_waitcnt lgkmcnt(0)
	v_mfma_f32_16x16x32_bf16 v[124:127], v[156:159], v[192:195], v[124:127]
	v_mfma_f32_16x16x32_bf16 v[116:119], v[164:167], v[192:195], v[116:119]
	v_mfma_f32_16x16x32_bf16 v[108:111], v[156:159], v[200:203], v[108:111]
	v_mfma_f32_16x16x32_bf16 v[100:103], v[164:167], v[200:203], v[100:103]
	v_mfma_f32_16x16x32_bf16 v[92:95], v[156:159], v[208:211], v[92:95]
	v_mfma_f32_16x16x32_bf16 v[84:87], v[164:167], v[208:211], v[84:87]
	v_mfma_f32_16x16x32_bf16 v[76:79], v[156:159], v[216:219], v[76:79]
	v_mfma_f32_16x16x32_bf16 v[68:71], v[164:167], v[216:219], v[68:71]
	v_mfma_f32_16x16x32_bf16 v[124:127], v[160:163], v[196:199], v[124:127]
	v_mfma_f32_16x16x32_bf16 v[116:119], v[168:171], v[196:199], v[116:119]
	v_mfma_f32_16x16x32_bf16 v[108:111], v[160:163], v[204:207], v[108:111]
	v_mfma_f32_16x16x32_bf16 v[100:103], v[168:171], v[204:207], v[100:103]
	v_mfma_f32_16x16x32_bf16 v[92:95], v[160:163], v[212:215], v[92:95]
	v_mfma_f32_16x16x32_bf16 v[84:87], v[168:171], v[212:215], v[84:87]
	v_mfma_f32_16x16x32_bf16 v[76:79], v[160:163], v[220:223], v[76:79]
	v_mfma_f32_16x16x32_bf16 v[68:71], v[168:171], v[220:223], v[68:71]
	s_setprio 0
	s_setprio 1
	v_mfma_f32_16x16x32_bf16 v[120:123], v[172:175], v[192:195], v[120:123]
	v_mfma_f32_16x16x32_bf16 v[112:115], v[180:183], v[192:195], v[112:115]
	v_mfma_f32_16x16x32_bf16 v[104:107], v[172:175], v[200:203], v[104:107]
	v_mfma_f32_16x16x32_bf16 v[96:99], v[180:183], v[200:203], v[96:99]
	v_mfma_f32_16x16x32_bf16 v[88:91], v[172:175], v[208:211], v[88:91]
	v_mfma_f32_16x16x32_bf16 v[80:83], v[180:183], v[208:211], v[80:83]
	v_mfma_f32_16x16x32_bf16 v[72:75], v[172:175], v[216:219], v[72:75]
	v_mfma_f32_16x16x32_bf16 v[64:67], v[180:183], v[216:219], v[64:67]
	v_mfma_f32_16x16x32_bf16 v[120:123], v[176:179], v[196:199], v[120:123]
	v_mfma_f32_16x16x32_bf16 v[112:115], v[188:191], v[196:199], v[112:115]
	v_mfma_f32_16x16x32_bf16 v[104:107], v[176:179], v[204:207], v[104:107]
	v_mfma_f32_16x16x32_bf16 v[96:99], v[188:191], v[204:207], v[96:99]
	v_mfma_f32_16x16x32_bf16 v[88:91], v[176:179], v[212:215], v[88:91]
	v_mfma_f32_16x16x32_bf16 v[80:83], v[188:191], v[212:215], v[80:83]
	v_mfma_f32_16x16x32_bf16 v[72:75], v[176:179], v[220:223], v[72:75]
	v_mfma_f32_16x16x32_bf16 v[64:67], v[188:191], v[220:223], v[64:67]
	s_setprio 0
	s_barrier
; #define PG8_STAGE(bufoff, gbase, voff) do { _Pragma("unroll") for (int _i = 0; _i < 2; ++_i) \
;         __builtin_amdgcn_global_load_lds((const unsigned*)((const char*)(gbase) + (voff)[_i]), (LAS unsigned*)(lds + (bufoff) + ldsw + _i * 8192), 16, 0, 1); } while (0)
; #define PG8_LDA(dst, b, h) do { _Pragma("unroll") for (int m = 0; m < 4; ++m) _Pragma("unroll") for (int k = 0; k < 2; ++k) dst[m][k] = *(const LAS bf16x8*)(lds + PG8_SA(b, h) + aoff + m * 2048 + k * 1024); } while (0)
; #define PG8_MMA(ai, bj, At, Bt) do { __builtin_amdgcn_s_setprio(1); _Pragma("unroll") for (int m = 0; m < 4; ++m) _Pragma("unroll") for (int n = 0; n < 2; ++n) _Pragma("unroll") for (int k = 0; k < 2; ++k) \
;         acc[ai][bj][m][n] = __builtin_amdgcn_mfma_f32_16x16x32_bf16(Bt[n][k], At[m][k], acc[ai][bj][m][n], 0, 0, 0); __builtin_amdgcn_s_setprio(0); } while (0)
; #define PG8_WAIT_V(n) asm volatile("s_waitcnt vmcnt(" #n ")" ::: "memory")
; #define PG8_WAIT_L(n) asm volatile("s_waitcnt lgkmcnt(" #n ")" ::: "memory")
; #define PG8_BAR __builtin_amdgcn_s_barrier()
; #define PG8_SCHED __builtin_amdgcn_sched_barrier(0)
; template <class Epi, class Sched, bool ALIGN_EPI = false, bool SP2 = false>
; __device__ __forceinline__ void gemm_phase(LAS unsigned char* lds, const Gemm g, const Sched& S, const Epi& E) {
;     ...
;         for (int t = 0; t < nt; t += 2) {
;     ...
;             PG8_LDA(At, 1, 1); PG8_STAGE(PG8_SB(1, 0), b3, voffB); PG8_STAGE(PG8_SB(1, 1), b3 + hstep, voffB); PG8_STAGE(PG8_SA(1, 0), a3, voffA);
;             PG8_WAIT_V(8); PG8_WAIT_L(0); PG8_BAR; PG8_MMA(1, 0, At, B0); PG8_MMA(1, 1, At, B1); PG8_BAR; PG8_SCHED;
	s_add_i32 s6, s69, s52
	v_lshl_add_u64 v[150:151], v[150:151], 0, s[18:19]
	s_mov_b32 m0, s6
	ds_read_b128 v[192:195], v149 offset:49152
	ds_read_b128 v[196:199], v149 offset:50176
	ds_read_b128 v[200:203], v149 offset:51200
	ds_read_b128 v[204:207], v149 offset:52224
	ds_read_b128 v[208:211], v149 offset:53248
	ds_read_b128 v[212:215], v149 offset:54272
	ds_read_b128 v[216:219], v149 offset:55296
	ds_read_b128 v[220:223], v149 offset:56320
	global_load_lds_dwordx4 v[150:151], off sc0
	s_add_i32 m0, s6, 0x2000
	s_add_u32 s6, s44, 0x80080
	v_lshl_add_u64 v[150:151], v[184:185], 0, s[18:19]
	s_addc_u32 s7, s45, 0
	s_add_i32 s44, s73, s52
	global_load_lds_dwordx4 v[150:151], off sc0
	v_lshl_add_u64 v[150:151], s[6:7], 0, v[132:133]
	s_mov_b32 m0, s44
	s_nop 0
	global_load_lds_dwordx4 v[150:151], off sc0
	v_lshl_add_u64 v[150:151], s[6:7], 0, v[128:129]
	s_add_i32 m0, s44, 0x2000
	s_nop 0
	global_load_lds_dwordx4 v[150:151], off sc0
	v_lshl_add_u64 v[150:151], v[224:225], 0, s[18:19]
	s_mov_b32 m0, s58
	s_nop 0
	global_load_lds_dwordx4 v[150:151], off sc0
	v_lshl_add_u64 v[150:151], v[226:227], 0, s[18:19]
	s_mov_b32 m0, s59
	s_nop 0
	global_load_lds_dwordx4 v[150:151], off sc0
	s_waitcnt vmcnt(8)
	s_waitcnt lgkmcnt(0)
	s_barrier
	s_setprio 1
	s_waitcnt lgkmcnt(0)
	v_mfma_f32_16x16x32_bf16 v[60:63], v[156:159], v[192:195], v[60:63]
	v_mfma_f32_16x16x32_bf16 v[52:55], v[164:167], v[192:195], v[52:55]
	v_mfma_f32_16x16x32_bf16 v[44:47], v[156:159], v[200:203], v[44:47]
	v_mfma_f32_16x16x32_bf16 v[36:39], v[164:167], v[200:203], v[36:39]
	v_mfma_f32_16x16x32_bf16 v[28:31], v[156:159], v[208:211], v[28:31]
	v_mfma_f32_16x16x32_bf16 v[20:23], v[164:167], v[208:211], v[20:23]
	v_mfma_f32_16x16x32_bf16 v[12:15], v[156:159], v[216:219], v[12:15]
	v_mfma_f32_16x16x32_bf16 v[4:7], v[164:167], v[216:219], v[4:7]
	v_mfma_f32_16x16x32_bf16 v[60:63], v[160:163], v[196:199], v[60:63]
	v_mfma_f32_16x16x32_bf16 v[52:55], v[168:171], v[196:199], v[52:55]
	v_mfma_f32_16x16x32_bf16 v[44:47], v[160:163], v[204:207], v[44:47]
	v_mfma_f32_16x16x32_bf16 v[36:39], v[168:171], v[204:207], v[36:39]
	v_mfma_f32_16x16x32_bf16 v[28:31], v[160:163], v[212:215], v[28:31]
	v_mfma_f32_16x16x32_bf16 v[20:23], v[168:171], v[212:215], v[20:23]
	v_mfma_f32_16x16x32_bf16 v[12:15], v[160:163], v[220:223], v[12:15]
	v_mfma_f32_16x16x32_bf16 v[4:7], v[168:171], v[220:223], v[4:7]
	s_setprio 0
	s_setprio 1
	v_mfma_f32_16x16x32_bf16 v[56:59], v[172:175], v[192:195], v[56:59]
	v_mfma_f32_16x16x32_bf16 v[48:51], v[180:183], v[192:195], v[48:51]
	v_mfma_f32_16x16x32_bf16 v[40:43], v[172:175], v[200:203], v[40:43]
	v_mfma_f32_16x16x32_bf16 v[32:35], v[180:183], v[200:203], v[32:35]
	v_mfma_f32_16x16x32_bf16 v[24:27], v[172:175], v[208:211], v[24:27]
	v_mfma_f32_16x16x32_bf16 v[16:19], v[180:183], v[208:211], v[16:19]
	v_mfma_f32_16x16x32_bf16 v[8:11], v[172:175], v[216:219], v[8:11]
	v_mfma_f32_16x16x32_bf16 v[0:3], v[180:183], v[216:219], v[0:3]
	v_mfma_f32_16x16x32_bf16 v[56:59], v[176:179], v[196:199], v[56:59]
	v_mfma_f32_16x16x32_bf16 v[48:51], v[188:191], v[196:199], v[48:51]
	v_mfma_f32_16x16x32_bf16 v[40:43], v[176:179], v[204:207], v[40:43]
	v_mfma_f32_16x16x32_bf16 v[32:35], v[188:191], v[204:207], v[32:35]
	v_mfma_f32_16x16x32_bf16 v[24:27], v[176:179], v[212:215], v[24:27]
	v_mfma_f32_16x16x32_bf16 v[16:19], v[188:191], v[212:215], v[16:19]
	v_mfma_f32_16x16x32_bf16 v[8:11], v[176:179], v[220:223], v[8:11]
	v_mfma_f32_16x16x32_bf16 v[0:3], v[188:191], v[220:223], v[0:3]
	s_setprio 0
	s_add_i32 s68, s68, 2
	s_add_u32 s42, s42, 0x100
	s_addc_u32 s43, s43, 0
	s_add_u32 s66, s66, 0x100
	s_addc_u32 s67, s67, 0
	s_cmp_gt_u32 s68, 29
	s_barrier
	s_cbranch_scc0 .LBB0_699
	s_and_b64 vcc, exec, s[22:23]
	s_cbranch_vccz .LBB0_702
	s_barrier

; #define PG8_STAGE(bufoff, gbase, voff) do { _Pragma("unroll") for (int _i = 0; _i < 2; ++_i) \
;         __builtin_amdgcn_global_load_lds((const unsigned*)((const char*)(gbase) + (voff)[_i]), (LAS unsigned*)(lds + (bufoff) + ldsw + _i * 8192), 16, 0, 1); } while (0)
; #define PG8_LDA(dst, b, h) do { _Pragma("unroll") for (int m = 0; m < 4; ++m) _Pragma("unroll") for (int k = 0; k < 2; ++k) dst[m][k] = *(const LAS bf16x8*)(lds + PG8_SA(b, h) + aoff + m * 2048 + k * 1024); } while (0)
; #define PG8_LDB(dst, b, h) do { _Pragma("unroll") for (int n = 0; n < 2; ++n) _Pragma("unroll") for (int k = 0; k < 2; ++k) dst[n][k] = *(const LAS bf16x8*)(lds + PG8_SB(b, h) + boff + n * 2048 + k * 1024); } while (0)
; #define PG8_MMA(ai, bj, At, Bt) do { __builtin_amdgcn_s_setprio(1); _Pragma("unroll") for (int m = 0; m < 4; ++m) _Pragma("unroll") for (int n = 0; n < 2; ++n) _Pragma("unroll") for (int k = 0; k < 2; ++k) \
;         acc[ai][bj][m][n] = __builtin_amdgcn_mfma_f32_16x16x32_bf16(Bt[n][k], At[m][k], acc[ai][bj][m][n], 0, 0, 0); __builtin_amdgcn_s_setprio(0); } while (0)
; #define PG8_WAIT_V(n) asm volatile("s_waitcnt vmcnt(" #n ")" ::: "memory")
; #define PG8_WAIT_L(n) asm volatile("s_waitcnt lgkmcnt(" #n ")" ::: "memory")
; template <class Epi, class Sched, bool ALIGN_EPI = false, bool SP2 = false>
; __device__ __forceinline__ void gemm_phase(LAS unsigned char* lds, const Gemm g, const Sched& S, const Epi& E) {
;     ...
;         for (int t = 0; t < nt; t += 2) {
;             const bool last = (t == nt - 2);
;             const char* a1 = cA + (size_t)(t + 1) * kstep;
;             const char* a2 = last ? nA : cA + (size_t)(t + 2) * kstep; const char* b2 = last ? nB : cB + (size_t)(t + 2) * kstep;
;             const char* a3 = a2 + kstep; const char* b3 = b2 + kstep;
;             if (last && has_next) S.a_ready(nxt);
;             if constexpr (SP2) {
;             PG8_LDB(B0, 0, 0); PG8_LDB(B1, 0, 1); PG8_SCHED; PG8_LDA(At, 0, 0); PG8_STAGE(PG8_SA(1, 1), a1 + hstep, voffA);
;             PG8_WAIT_V(8); PG8_WAIT_L(0); PG8_BAR; PG8_MMA(0, 0, At, B0); PG8_MMA(0, 1, At, B1); PG8_BAR; PG8_SCHED;
;             PG8_LDA(At, 0, 1); PG8_STAGE(PG8_SB(0, 0), b2, voffB); PG8_STAGE(PG8_SB(0, 1), b2 + hstep, voffB); PG8_STAGE(PG8_SA(0, 0), a2, voffA);
;             PG8_WAIT_V(8); PG8_WAIT_L(0); PG8_BAR; PG8_MMA(1, 0, At, B0); PG8_MMA(1, 1, At, B1); PG8_BAR; PG8_SCHED;
.LBB0_750:
	ds_read_b128 v[140:143], v164
	ds_read_b128 v[144:147], v164 offset:1024
	ds_read_b128 v[148:151], v164 offset:2048
	ds_read_b128 v[154:157], v164 offset:3072
	ds_read_b128 v[158:161], v165
	ds_read_b128 v[168:171], v165 offset:1024
	ds_read_b128 v[172:175], v165 offset:2048
	ds_read_b128 v[176:179], v165 offset:3072
	s_add_u32 s44, s42, 0x100
	s_addc_u32 s45, s43, 0
	s_cmpk_eq_i32 s6, 0x54
	s_cselect_b32 s49, s13, s45
	s_cselect_b32 s48, s12, s44
	s_cselect_b32 s47, s39, s75
	s_cselect_b32 s46, s38, s74
	v_lshl_add_u64 v[184:185], s[42:43], 0, v[132:133]
	s_add_i32 m0, s54, 0xc000
	ds_read_b128 v[180:183], v166
	ds_read_b128 v[188:191], v166 offset:1024
	ds_read_b128 v[192:195], v166 offset:2048
	ds_read_b128 v[196:199], v166 offset:3072
	ds_read_b128 v[200:203], v166 offset:4096
	ds_read_b128 v[204:207], v166 offset:5120
	ds_read_b128 v[208:211], v166 offset:6144
	ds_read_b128 v[212:215], v166 offset:7168
	global_load_lds_dwordx4 v[184:185], off sc0
	v_lshl_add_u64 v[184:185], s[42:43], 0, v[134:135]
	s_add_i32 m0, s54, 0xe000
	s_nop 0
	global_load_lds_dwordx4 v[184:185], off sc0
	s_waitcnt vmcnt(8)
	s_waitcnt lgkmcnt(0)
	s_barrier
	s_setprio 1
	s_waitcnt lgkmcnt(0)
	v_mfma_f32_16x16x32_bf16 v[124:127], v[140:143], v[180:183], v[124:127]
	v_mfma_f32_16x16x32_bf16 v[120:123], v[148:151], v[180:183], v[120:123]
	v_mfma_f32_16x16x32_bf16 v[116:119], v[140:143], v[192:195], v[116:119]
	v_mfma_f32_16x16x32_bf16 v[112:115], v[148:151], v[192:195], v[112:115]
	v_mfma_f32_16x16x32_bf16 v[92:95], v[140:143], v[200:203], v[92:95]
	v_mfma_f32_16x16x32_bf16 v[88:91], v[148:151], v[200:203], v[88:91]
	v_mfma_f32_16x16x32_bf16 v[84:87], v[140:143], v[208:211], v[84:87]
	v_mfma_f32_16x16x32_bf16 v[80:83], v[148:151], v[208:211], v[80:83]
	v_mfma_f32_16x16x32_bf16 v[124:127], v[144:147], v[188:191], v[124:127]
	v_mfma_f32_16x16x32_bf16 v[120:123], v[154:157], v[188:191], v[120:123]
	v_mfma_f32_16x16x32_bf16 v[116:119], v[144:147], v[196:199], v[116:119]
	v_mfma_f32_16x16x32_bf16 v[112:115], v[154:157], v[196:199], v[112:115]
	v_mfma_f32_16x16x32_bf16 v[92:95], v[144:147], v[204:207], v[92:95]
	v_mfma_f32_16x16x32_bf16 v[88:91], v[154:157], v[204:207], v[88:91]
	v_mfma_f32_16x16x32_bf16 v[84:87], v[144:147], v[212:215], v[84:87]
	v_mfma_f32_16x16x32_bf16 v[80:83], v[154:157], v[212:215], v[80:83]
	s_setprio 0
	s_setprio 1
	v_mfma_f32_16x16x32_bf16 v[108:111], v[158:161], v[180:183], v[108:111]
	v_mfma_f32_16x16x32_bf16 v[104:107], v[172:175], v[180:183], v[104:107]
	v_mfma_f32_16x16x32_bf16 v[100:103], v[158:161], v[192:195], v[100:103]
	v_mfma_f32_16x16x32_bf16 v[96:99], v[172:175], v[192:195], v[96:99]
	v_mfma_f32_16x16x32_bf16 v[76:79], v[158:161], v[200:203], v[76:79]
	v_mfma_f32_16x16x32_bf16 v[72:75], v[172:175], v[200:203], v[72:75]
	v_mfma_f32_16x16x32_bf16 v[68:71], v[158:161], v[208:211], v[68:71]
	v_mfma_f32_16x16x32_bf16 v[64:67], v[172:175], v[208:211], v[64:67]
	v_mfma_f32_16x16x32_bf16 v[108:111], v[168:171], v[188:191], v[108:111]
	v_mfma_f32_16x16x32_bf16 v[104:107], v[176:179], v[188:191], v[104:107]
	v_mfma_f32_16x16x32_bf16 v[100:103], v[168:171], v[196:199], v[100:103]
	v_mfma_f32_16x16x32_bf16 v[96:99], v[176:179], v[196:199], v[96:99]
	v_mfma_f32_16x16x32_bf16 v[76:79], v[168:171], v[204:207], v[76:79]
	v_mfma_f32_16x16x32_bf16 v[72:75], v[176:179], v[204:207], v[72:75]
	v_mfma_f32_16x16x32_bf16 v[68:71], v[168:171], v[212:215], v[68:71]
	v_mfma_f32_16x16x32_bf16 v[64:67], v[176:179], v[212:215], v[64:67]
	s_setprio 0
	s_barrier
	s_add_i32 s7, s63, s53
	v_lshl_add_u64 v[184:185], s[46:47], 0, v[128:129]
	s_mov_b32 m0, s7
	ds_read_b128 v[180:183], v166 offset:16384
	ds_read_b128 v[188:191], v166 offset:17408
	ds_read_b128 v[192:195], v166 offset:18432
	ds_read_b128 v[196:199], v166 offset:19456
	ds_read_b128 v[200:203], v166 offset:20480
	ds_read_b128 v[204:207], v166 offset:21504
	ds_read_b128 v[208:211], v166 offset:22528
	ds_read_b128 v[212:215], v166 offset:23552
	global_load_lds_dwordx4 v[184:185], off sc0
	s_add_i32 m0, s7, 0x2000
	s_add_u32 s42, s46, 0x160000
	v_lshl_add_u64 v[216:217], s[46:47], 0, v[130:131]
	s_addc_u32 s43, s47, 0
	s_add_i32 s7, s64, s53
	global_load_lds_dwordx4 v[216:217], off sc0
	v_lshl_add_u64 v[218:219], s[42:43], 0, v[128:129]
	s_mov_b32 m0, s7
	v_lshl_add_u64 v[220:221], s[48:49], 0, v[130:131]
	global_load_lds_dwordx4 v[218:219], off sc0
	v_lshl_add_u64 v[218:219], s[42:43], 0, v[130:131]
	s_add_i32 m0, s7, 0x2000
	s_nop 0
	global_load_lds_dwordx4 v[218:219], off sc0
	v_lshl_add_u64 v[218:219], s[48:49], 0, v[128:129]
	s_mov_b32 m0, s54
	s_nop 0
	global_load_lds_dwordx4 v[218:219], off sc0
	s_mov_b32 m0, s55
	s_nop 0
	global_load_lds_dwordx4 v[220:221], off sc0
	s_waitcnt vmcnt(8)
	s_waitcnt lgkmcnt(0)
	s_barrier
; #define PG8_STAGE(bufoff, gbase, voff) do { _Pragma("unroll") for (int _i = 0; _i < 2; ++_i) \
;         __builtin_amdgcn_global_load_lds((const unsigned*)((const char*)(gbase) + (voff)[_i]), (LAS unsigned*)(lds + (bufoff) + ldsw + _i * 8192), 16, 0, 1); } while (0)
; #define PG8_LDA(dst, b, h) do { _Pragma("unroll") for (int m = 0; m < 4; ++m) _Pragma("unroll") for (int k = 0; k < 2; ++k) dst[m][k] = *(const LAS bf16x8*)(lds + PG8_SA(b, h) + aoff + m * 2048 + k * 1024); } while (0)
; #define PG8_LDB(dst, b, h) do { _Pragma("unroll") for (int n = 0; n < 2; ++n) _Pragma("unroll") for (int k = 0; k < 2; ++k) dst[n][k] = *(const LAS bf16x8*)(lds + PG8_SB(b, h) + boff + n * 2048 + k * 1024); } while (0)
; #define PG8_MMA(ai, bj, At, Bt) do { __builtin_amdgcn_s_setprio(1); _Pragma("unroll") for (int m = 0; m < 4; ++m) _Pragma("unroll") for (int n = 0; n < 2; ++n) _Pragma("unroll") for (int k = 0; k < 2; ++k) \
;         acc[ai][bj][m][n] = __builtin_amdgcn_mfma_f32_16x16x32_bf16(Bt[n][k], At[m][k], acc[ai][bj][m][n], 0, 0, 0); __builtin_amdgcn_s_setprio(0); } while (0)
; #define PG8_WAIT_V(n) asm volatile("s_waitcnt vmcnt(" #n ")" ::: "memory")
; #define PG8_WAIT_L(n) asm volatile("s_waitcnt lgkmcnt(" #n ")" ::: "memory")
; #define PG8_BAR __builtin_amdgcn_s_barrier()
; #define PG8_SCHED __builtin_amdgcn_sched_barrier(0)
; template <class Epi, class Sched, bool ALIGN_EPI = false, bool SP2 = false>
; __device__ __forceinline__ void gemm_phase(LAS unsigned char* lds, const Gemm g, const Sched& S, const Epi& E) {
;     ...
;             PG8_WAIT_V(8); PG8_WAIT_L(0); PG8_BAR; PG8_MMA(1, 0, At, B0); PG8_MMA(1, 1, At, B1); PG8_BAR; PG8_SCHED;
;             PG8_LDB(B0, 1, 0); PG8_LDB(B1, 1, 1); PG8_SCHED; PG8_LDA(At, 1, 0); PG8_STAGE(PG8_SA(0, 1), a2 + hstep, voffA);
;             PG8_WAIT_V(8); PG8_WAIT_L(0); PG8_BAR; PG8_MMA(0, 0, At, B0); PG8_MMA(0, 1, At, B1); PG8_BAR; PG8_SCHED;
	s_setprio 1
	s_waitcnt lgkmcnt(0)
	v_mfma_f32_16x16x32_bf16 v[60:63], v[140:143], v[180:183], v[60:63]
	v_mfma_f32_16x16x32_bf16 v[56:59], v[148:151], v[180:183], v[56:59]
	v_mfma_f32_16x16x32_bf16 v[52:55], v[140:143], v[192:195], v[52:55]
	v_mfma_f32_16x16x32_bf16 v[48:51], v[148:151], v[192:195], v[48:51]
	v_mfma_f32_16x16x32_bf16 v[28:31], v[140:143], v[200:203], v[28:31]
	v_mfma_f32_16x16x32_bf16 v[24:27], v[148:151], v[200:203], v[24:27]
	v_mfma_f32_16x16x32_bf16 v[20:23], v[140:143], v[208:211], v[20:23]
	v_mfma_f32_16x16x32_bf16 v[16:19], v[148:151], v[208:211], v[16:19]
	v_mfma_f32_16x16x32_bf16 v[60:63], v[144:147], v[188:191], v[60:63]
	v_mfma_f32_16x16x32_bf16 v[56:59], v[154:157], v[188:191], v[56:59]
	v_mfma_f32_16x16x32_bf16 v[52:55], v[144:147], v[196:199], v[52:55]
	v_mfma_f32_16x16x32_bf16 v[48:51], v[154:157], v[196:199], v[48:51]
	v_mfma_f32_16x16x32_bf16 v[28:31], v[144:147], v[204:207], v[28:31]
	v_mfma_f32_16x16x32_bf16 v[24:27], v[154:157], v[204:207], v[24:27]
	v_mfma_f32_16x16x32_bf16 v[20:23], v[144:147], v[212:215], v[20:23]
	v_mfma_f32_16x16x32_bf16 v[16:19], v[154:157], v[212:215], v[16:19]
	s_setprio 0
	s_setprio 1
	v_mfma_f32_16x16x32_bf16 v[44:47], v[158:161], v[180:183], v[44:47]
	v_mfma_f32_16x16x32_bf16 v[40:43], v[172:175], v[180:183], v[40:43]
	v_mfma_f32_16x16x32_bf16 v[36:39], v[158:161], v[192:195], v[36:39]
	v_mfma_f32_16x16x32_bf16 v[32:35], v[172:175], v[192:195], v[32:35]
	v_mfma_f32_16x16x32_bf16 v[12:15], v[158:161], v[200:203], v[12:15]
	v_mfma_f32_16x16x32_bf16 v[8:11], v[172:175], v[200:203], v[8:11]
	v_mfma_f32_16x16x32_bf16 v[4:7], v[158:161], v[208:211], v[4:7]
	v_mfma_f32_16x16x32_bf16 v[0:3], v[172:175], v[208:211], v[0:3]
	v_mfma_f32_16x16x32_bf16 v[44:47], v[168:171], v[188:191], v[44:47]
	v_mfma_f32_16x16x32_bf16 v[40:43], v[176:179], v[188:191], v[40:43]
	v_mfma_f32_16x16x32_bf16 v[36:39], v[168:171], v[196:199], v[36:39]
	v_mfma_f32_16x16x32_bf16 v[32:35], v[176:179], v[196:199], v[32:35]
	v_mfma_f32_16x16x32_bf16 v[12:15], v[168:171], v[204:207], v[12:15]
	v_mfma_f32_16x16x32_bf16 v[8:11], v[176:179], v[204:207], v[8:11]
	v_mfma_f32_16x16x32_bf16 v[4:7], v[168:171], v[212:215], v[4:7]
	v_mfma_f32_16x16x32_bf16 v[0:3], v[176:179], v[212:215], v[0:3]
	s_setprio 0
	s_barrier
	s_add_i32 s7, 0, 0x18000
	s_add_i32 s76, 0, 0x1c000
	v_add_u32_e32 v154, s7, v162
	v_add_u32_e32 v167, s76, v162
	ds_read_b128 v[140:143], v154
	ds_read_b128 v[144:147], v154 offset:1024
	ds_read_b128 v[148:151], v154 offset:2048
	ds_read_b128 v[154:157], v154 offset:3072
	ds_read_b128 v[158:161], v167
	ds_read_b128 v[168:171], v167 offset:1024
	ds_read_b128 v[172:175], v167 offset:2048
	ds_read_b128 v[176:179], v167 offset:3072
	s_add_u32 s42, s48, 0x160000
	s_addc_u32 s43, s49, 0
	s_mov_b32 m0, s56
	v_lshl_add_u64 v[222:223], s[42:43], 0, v[128:129]
	ds_read_b128 v[180:183], v166 offset:32768
	ds_read_b128 v[188:191], v166 offset:33792
	ds_read_b128 v[192:195], v166 offset:34816
	ds_read_b128 v[196:199], v166 offset:35840
	ds_read_b128 v[200:203], v166 offset:36864
	ds_read_b128 v[204:207], v166 offset:37888
	ds_read_b128 v[208:211], v166 offset:38912
	ds_read_b128 v[212:215], v166 offset:39936
	global_load_lds_dwordx4 v[222:223], off sc0
	v_lshl_add_u64 v[222:223], s[42:43], 0, v[130:131]
	s_mov_b32 m0, s57
	s_nop 0
	global_load_lds_dwordx4 v[222:223], off sc0
	s_waitcnt vmcnt(8)
	s_waitcnt lgkmcnt(0)
	s_barrier
	s_setprio 1
	s_waitcnt lgkmcnt(0)
	v_mfma_f32_16x16x32_bf16 v[124:127], v[140:143], v[180:183], v[124:127]
	v_mfma_f32_16x16x32_bf16 v[120:123], v[148:151], v[180:183], v[120:123]
	v_mfma_f32_16x16x32_bf16 v[116:119], v[140:143], v[192:195], v[116:119]
	v_mfma_f32_16x16x32_bf16 v[112:115], v[148:151], v[192:195], v[112:115]
	v_mfma_f32_16x16x32_bf16 v[92:95], v[140:143], v[200:203], v[92:95]
	v_mfma_f32_16x16x32_bf16 v[88:91], v[148:151], v[200:203], v[88:91]
	v_mfma_f32_16x16x32_bf16 v[84:87], v[140:143], v[208:211], v[84:87]
	v_mfma_f32_16x16x32_bf16 v[80:83], v[148:151], v[208:211], v[80:83]
	v_mfma_f32_16x16x32_bf16 v[124:127], v[144:147], v[188:191], v[124:127]
	v_mfma_f32_16x16x32_bf16 v[120:123], v[154:157], v[188:191], v[120:123]
	v_mfma_f32_16x16x32_bf16 v[116:119], v[144:147], v[196:199], v[116:119]
	v_mfma_f32_16x16x32_bf16 v[112:115], v[154:157], v[196:199], v[112:115]
	v_mfma_f32_16x16x32_bf16 v[92:95], v[144:147], v[204:207], v[92:95]
	v_mfma_f32_16x16x32_bf16 v[88:91], v[154:157], v[204:207], v[88:91]
	v_mfma_f32_16x16x32_bf16 v[84:87], v[144:147], v[212:215], v[84:87]
	v_mfma_f32_16x16x32_bf16 v[80:83], v[154:157], v[212:215], v[80:83]
	s_setprio 0
	s_setprio 1
	v_mfma_f32_16x16x32_bf16 v[108:111], v[158:161], v[180:183], v[108:111]
	v_mfma_f32_16x16x32_bf16 v[104:107], v[172:175], v[180:183], v[104:107]
	v_mfma_f32_16x16x32_bf16 v[100:103], v[158:161], v[192:195], v[100:103]
	v_mfma_f32_16x16x32_bf16 v[96:99], v[172:175], v[192:195], v[96:99]
	v_mfma_f32_16x16x32_bf16 v[76:79], v[158:161], v[200:203], v[76:79]
	v_mfma_f32_16x16x32_bf16 v[72:75], v[172:175], v[200:203], v[72:75]
	v_mfma_f32_16x16x32_bf16 v[68:71], v[158:161], v[208:211], v[68:71]
	v_mfma_f32_16x16x32_bf16 v[64:67], v[172:175], v[208:211], v[64:67]
	v_mfma_f32_16x16x32_bf16 v[108:111], v[168:171], v[188:191], v[108:111]
	v_mfma_f32_16x16x32_bf16 v[104:107], v[176:179], v[188:191], v[104:107]
	v_mfma_f32_16x16x32_bf16 v[100:103], v[168:171], v[196:199], v[100:103]
	v_mfma_f32_16x16x32_bf16 v[96:99], v[176:179], v[196:199], v[96:99]
	v_mfma_f32_16x16x32_bf16 v[76:79], v[168:171], v[204:207], v[76:79]
	v_mfma_f32_16x16x32_bf16 v[72:75], v[176:179], v[204:207], v[72:75]
	v_mfma_f32_16x16x32_bf16 v[68:71], v[168:171], v[212:215], v[68:71]
	v_mfma_f32_16x16x32_bf16 v[64:67], v[176:179], v[212:215], v[64:67]
	s_setprio 0
	s_barrier
; #define PG8_STAGE(bufoff, gbase, voff) do { _Pragma("unroll") for (int _i = 0; _i < 2; ++_i) \
;         __builtin_amdgcn_global_load_lds((const unsigned*)((const char*)(gbase) + (voff)[_i]), (LAS unsigned*)(lds + (bufoff) + ldsw + _i * 8192), 16, 0, 1); } while (0)
; #define PG8_LDA(dst, b, h) do { _Pragma("unroll") for (int m = 0; m < 4; ++m) _Pragma("unroll") for (int k = 0; k < 2; ++k) dst[m][k] = *(const LAS bf16x8*)(lds + PG8_SA(b, h) + aoff + m * 2048 + k * 1024); } while (0)
; #define PG8_MMA(ai, bj, At, Bt) do { __builtin_amdgcn_s_setprio(1); _Pragma("unroll") for (int m = 0; m < 4; ++m) _Pragma("unroll") for (int n = 0; n < 2; ++n) _Pragma("unroll") for (int k = 0; k < 2; ++k) \
;         acc[ai][bj][m][n] = __builtin_amdgcn_mfma_f32_16x16x32_bf16(Bt[n][k], At[m][k], acc[ai][bj][m][n], 0, 0, 0); __builtin_amdgcn_s_setprio(0); } while (0)
; #define PG8_WAIT_V(n) asm volatile("s_waitcnt vmcnt(" #n ")" ::: "memory")
; #define PG8_WAIT_L(n) asm volatile("s_waitcnt lgkmcnt(" #n ")" ::: "memory")
; #define PG8_BAR __builtin_amdgcn_s_barrier()
; #define PG8_SCHED __builtin_amdgcn_sched_barrier(0)
; template <class Epi, class Sched, bool ALIGN_EPI = false, bool SP2 = false>
; __device__ __forceinline__ void gemm_phase(LAS unsigned char* lds, const Gemm g, const Sched& S, const Epi& E) {
;     ...
;         for (int t = 0; t < nt; t += 2) {
;     ...
;             PG8_LDA(At, 1, 1); PG8_STAGE(PG8_SB(1, 0), b3, voffB); PG8_STAGE(PG8_SB(1, 1), b3 + hstep, voffB); PG8_STAGE(PG8_SA(1, 0), a3, voffA);
;             PG8_WAIT_V(8); PG8_WAIT_L(0); PG8_BAR; PG8_MMA(1, 0, At, B0); PG8_MMA(1, 1, At, B1); PG8_BAR; PG8_SCHED;
	s_add_i32 s7, s7, s53
	v_lshl_add_u64 v[184:185], v[184:185], 0, s[18:19]
	s_mov_b32 m0, s7
	ds_read_b128 v[180:183], v166 offset:49152
	ds_read_b128 v[188:191], v166 offset:50176
	ds_read_b128 v[192:195], v166 offset:51200
	ds_read_b128 v[196:199], v166 offset:52224
	ds_read_b128 v[200:203], v166 offset:53248
	ds_read_b128 v[204:207], v166 offset:54272
	ds_read_b128 v[208:211], v166 offset:55296
	ds_read_b128 v[212:215], v166 offset:56320
	global_load_lds_dwordx4 v[184:185], off sc0
	s_add_i32 m0, s7, 0x2000
	s_add_u32 s42, s46, 0x160080
	v_lshl_add_u64 v[184:185], v[216:217], 0, s[18:19]
	s_addc_u32 s43, s47, 0
	s_add_i32 s7, s76, s53
	global_load_lds_dwordx4 v[184:185], off sc0
	v_lshl_add_u64 v[184:185], s[42:43], 0, v[128:129]
	s_mov_b32 m0, s7
	s_nop 0
	global_load_lds_dwordx4 v[184:185], off sc0
	v_lshl_add_u64 v[184:185], s[42:43], 0, v[130:131]
	s_add_i32 m0, s7, 0x2000
	s_nop 0
	global_load_lds_dwordx4 v[184:185], off sc0
	v_lshl_add_u64 v[184:185], v[218:219], 0, s[18:19]
	s_mov_b32 m0, s61
	s_nop 0
	global_load_lds_dwordx4 v[184:185], off sc0
	v_lshl_add_u64 v[184:185], v[220:221], 0, s[18:19]
	s_mov_b32 m0, s62
	s_nop 0
	global_load_lds_dwordx4 v[184:185], off sc0
	s_waitcnt vmcnt(8)
	s_waitcnt lgkmcnt(0)
	s_barrier
	s_setprio 1
	s_waitcnt lgkmcnt(0)
	v_mfma_f32_16x16x32_bf16 v[60:63], v[140:143], v[180:183], v[60:63]
	v_mfma_f32_16x16x32_bf16 v[56:59], v[148:151], v[180:183], v[56:59]
	v_mfma_f32_16x16x32_bf16 v[52:55], v[140:143], v[192:195], v[52:55]
	v_mfma_f32_16x16x32_bf16 v[48:51], v[148:151], v[192:195], v[48:51]
	v_mfma_f32_16x16x32_bf16 v[28:31], v[140:143], v[200:203], v[28:31]
	v_mfma_f32_16x16x32_bf16 v[24:27], v[148:151], v[200:203], v[24:27]
	v_mfma_f32_16x16x32_bf16 v[20:23], v[140:143], v[208:211], v[20:23]
	v_mfma_f32_16x16x32_bf16 v[16:19], v[148:151], v[208:211], v[16:19]
	v_mfma_f32_16x16x32_bf16 v[60:63], v[144:147], v[188:191], v[60:63]
	v_mfma_f32_16x16x32_bf16 v[56:59], v[154:157], v[188:191], v[56:59]
	v_mfma_f32_16x16x32_bf16 v[52:55], v[144:147], v[196:199], v[52:55]
	v_mfma_f32_16x16x32_bf16 v[48:51], v[154:157], v[196:199], v[48:51]
	v_mfma_f32_16x16x32_bf16 v[28:31], v[144:147], v[204:207], v[28:31]
	v_mfma_f32_16x16x32_bf16 v[24:27], v[154:157], v[204:207], v[24:27]
	v_mfma_f32_16x16x32_bf16 v[20:23], v[144:147], v[212:215], v[20:23]
	v_mfma_f32_16x16x32_bf16 v[16:19], v[154:157], v[212:215], v[16:19]
	s_setprio 0
	s_setprio 1
	v_mfma_f32_16x16x32_bf16 v[44:47], v[158:161], v[180:183], v[44:47]
	v_mfma_f32_16x16x32_bf16 v[40:43], v[172:175], v[180:183], v[40:43]
	v_mfma_f32_16x16x32_bf16 v[36:39], v[158:161], v[192:195], v[36:39]
	v_mfma_f32_16x16x32_bf16 v[32:35], v[172:175], v[192:195], v[32:35]
	v_mfma_f32_16x16x32_bf16 v[12:15], v[158:161], v[200:203], v[12:15]
	v_mfma_f32_16x16x32_bf16 v[8:11], v[172:175], v[200:203], v[8:11]
	v_mfma_f32_16x16x32_bf16 v[4:7], v[158:161], v[208:211], v[4:7]
	v_mfma_f32_16x16x32_bf16 v[0:3], v[172:175], v[208:211], v[0:3]
	v_mfma_f32_16x16x32_bf16 v[44:47], v[168:171], v[188:191], v[44:47]
	v_mfma_f32_16x16x32_bf16 v[40:43], v[176:179], v[188:191], v[40:43]
	v_mfma_f32_16x16x32_bf16 v[36:39], v[168:171], v[196:199], v[36:39]
	v_mfma_f32_16x16x32_bf16 v[32:35], v[176:179], v[196:199], v[32:35]
	v_mfma_f32_16x16x32_bf16 v[12:15], v[168:171], v[204:207], v[12:15]
	v_mfma_f32_16x16x32_bf16 v[8:11], v[176:179], v[204:207], v[8:11]
	v_mfma_f32_16x16x32_bf16 v[4:7], v[168:171], v[212:215], v[4:7]
	v_mfma_f32_16x16x32_bf16 v[0:3], v[176:179], v[212:215], v[0:3]
	s_setprio 0
	s_add_i32 s6, s6, 2
	s_add_u32 s74, s74, 0x100
	s_addc_u32 s75, s75, 0
	s_cmpk_gt_u32 s6, 0x55
	s_mov_b64 s[42:43], s[44:45]
	s_barrier
	s_cbranch_scc0 .LBB0_750
	s_and_b64 vcc, exec, s[22:23]
	s_cbranch_vccz .LBB0_753
	s_barrier
